# H activation buffer stored k-block-major so GEMM A-operand LDS-DMA reads are contiguous (ph2/9/13/20); ph14 tile loads issued together
# speedup vs baseline: 1.0970x; 1.0152x over previous
; #define GAS __attribute__((address_space(1)))
; DI void rw_rows4(const RowIO4& R, const float* __restrict__ ga, const float* __restrict__ gb, int lane) {
;   f32x4 x[4][4]; u32x2 yr[4][4];
;   f32x4 ga4[4], gt4[4], gb4[4], sh4[4], sc4[4];
; #pragma unroll
;   for (int r = 0; r < 4; ++r)
; #pragma unroll
;     for (int i = 0; i < 4; ++i) x[r][i] = __builtin_nontemporal_load((const GAS f32x4*)(R.xin + r * 1024 + 4 * lane + 256 * i));
;   if (R.y) {
; #pragma unroll
;     for (int r = 0; r < 4; ++r)
; #pragma unroll
;       for (int i = 0; i < 4; ++i) yr[r][i] = *(const GAS u32x2*)(R.y + r * 1024 + 4 * lane + 256 * i);
; #pragma unroll
;     for (int i = 0; i < 4; ++i) { ga4[i] = *(const GAS f32x4*)(ga + 4 * lane + 256 * i); gt4[i] = *(const GAS f32x4*)(R.gate + 4 * lane + 256 * i); }
;   }
;   if (R.hout) {
; #pragma unroll
;     for (int i = 0; i < 4; ++i) { gb4[i] = *(const GAS f32x4*)(gb + 4 * lane + 256 * i); sh4[i] = *(const GAS f32x4*)(R.shift + 4 * lane + 256 * i); sc4[i] = *(const GAS f32x4*)(R.scale + 4 * lane + 256 * i); }
;   }
; #pragma unroll
;   for (int r = 0; r < 4; ++r) {
;     if (R.y) {
;       f32x4 yv[4]; float ss = 0.f;
; #pragma unroll
;       for (int i = 0; i < 4; ++i) {
;         yv[i] = (f32x4){bflo(yr[r][i].x), bfhi(yr[r][i].x), bflo(yr[r][i].y), bfhi(yr[r][i].y)};
;         ss += yv[i][0] * yv[i][0] + yv[i][1] * yv[i][1] + yv[i][2] * yv[i][2] + yv[i][3] * yv[i][3];
;       }
;       const float rinv = rsqrtf(wave_sum(ss) * (1.f / 1024.f) + 1e-6f);
; #pragma unroll
;       for (int i = 0; i < 4; ++i) x[r][i] = x[r][i] + gt4[i] * (yv[i] * rinv * ga4[i]);
;     }
;     if (R.xout) {
; #pragma unroll
;       for (int i = 0; i < 4; ++i) __builtin_nontemporal_store(x[r][i], (GAS f32x4*)(R.xout + r * 1024 + 4 * lane + 256 * i));
;     }
;     if (R.hout) {
;       float ss = 0.f;
; #pragma unroll
;       for (int i = 0; i < 4; ++i) ss += x[r][i][0] * x[r][i][0] + x[r][i][1] * x[r][i][1] + x[r][i][2] * x[r][i][2] + x[r][i][3] * x[r][i][3];
;       const float rinv = rsqrtf(wave_sum(ss) * (1.f / 1024.f) + 1e-6f);
; #pragma unroll
;       for (int i = 0; i < 4; ++i) {
;         const f32x4 hv = (x[r][i] * rinv * gb4[i]) * (sc4[i] + 1.f) + sh4[i];
;         u32x2 w; w.x = pk2(hv[0], hv[1]); w.y = pk2(hv[2], hv[3]);
;         *(GAS u32x2*)(R.hout + r * 1024 + 4 * lane + 256 * i) = w;
;       }
;     }
;   }
.LBB0_174:
	v_lshlrev_b32_e32 v0, 2, v86
	v_lshl_add_u64 v[18:19], s[14:15], 0, v[0:1]
	s_movk_i32 s23, 0x1000
	v_add_co_u32_e32 v20, vcc, s23, v18
	global_load_dwordx4 v[62:65], v0, s[14:15] nt
	global_load_dwordx4 v[58:61], v0, s[14:15] offset:1024 nt
	global_load_dwordx4 v[54:57], v0, s[14:15] offset:2048 nt
	global_load_dwordx4 v[50:53], v0, s[14:15] offset:3072 nt
	v_addc_co_u32_e32 v21, vcc, 0, v19, vcc
	s_movk_i32 s10, 0x2000
	v_add_co_u32_e32 v74, vcc, s10, v18
	s_min_i32 s10, s22, 0x4000
	s_nop 0
	v_addc_co_u32_e32 v75, vcc, 0, v19, vcc
	global_load_dwordx4 v[46:49], v[74:75], off offset:-4096 nt
	global_load_dwordx4 v[42:45], v[20:21], off offset:1024 nt
	global_load_dwordx4 v[38:41], v[20:21], off offset:2048 nt
	global_load_dwordx4 v[34:37], v[20:21], off offset:3072 nt
	s_ashr_i32 s10, s10, 9
	s_mul_hi_i32 s11, s10, 0x6000
	s_mulk_i32 s10, 0x6000
	s_movk_i32 s14, 0x3000
	v_add_co_u32_e32 v88, vcc, s14, v18
	s_add_u32 s14, s18, s10
	s_addc_u32 s15, s19, s11
	v_addc_co_u32_e32 v89, vcc, 0, v19, vcc
	v_lshl_add_u64 v[66:67], s[14:15], 0, v[0:1]
	s_mov_b64 s[16:17], 0x1000
	v_lshl_add_u64 v[68:69], v[66:67], 0, s[16:17]
	v_add_co_u32_e32 v66, vcc, s23, v66
	global_load_dwordx4 v[30:33], v[74:75], off nt
	global_load_dwordx4 v[26:29], v[88:89], off nt
	global_load_dwordx4 v[22:25], v0, s[14:15]
	global_load_dwordx4 v[18:21], v0, s[14:15] offset:1024
	v_addc_co_u32_e32 v67, vcc, 0, v67, vcc
	global_load_dwordx4 v[90:93], v[68:69], off offset:1024
	global_load_dwordx4 v[104:107], v[68:69], off offset:2048
	global_load_dwordx4 v[114:117], v[68:69], off offset:3072
	global_load_dwordx4 v[118:121], v[66:67], off
	s_mov_b32 s16, 0x3a800000
	s_mov_b32 s10, 0x800000
	s_waitcnt vmcnt(15)
	v_mov_b32_e32 v68, v63
	s_waitcnt vmcnt(14)
	v_mov_b32_e32 v69, v59
	s_waitcnt vmcnt(13)
	v_mov_b32_e32 v78, v55
	s_waitcnt vmcnt(12)
	v_mov_b32_e32 v79, v51
	v_mov_b32_e32 v66, v62
	v_mov_b32_e32 v67, v58
	v_mov_b32_e32 v76, v54
	v_mov_b32_e32 v77, v50
	v_pk_mul_f32 v[68:69], v[68:69], v[68:69]
	v_pk_mul_f32 v[78:79], v[78:79], v[78:79]
	v_mov_b32_e32 v70, v64
	v_mov_b32_e32 v71, v60
	v_pk_fma_f32 v[66:67], v[66:67], v[66:67], v[68:69]
	v_pk_fma_f32 v[68:69], v[76:77], v[76:77], v[78:79]
	s_waitcnt vmcnt(11)
	v_mov_b32_e32 v78, v47
	s_waitcnt vmcnt(10)
	v_mov_b32_e32 v79, v43
	v_mov_b32_e32 v76, v46
	v_mov_b32_e32 v77, v42
	s_waitcnt vmcnt(9)
	v_mov_b32_e32 v98, v39
	s_waitcnt vmcnt(8)
	v_mov_b32_e32 v99, v35
	v_pk_fma_f32 v[66:67], v[70:71], v[70:71], v[66:67]
	v_pk_mul_f32 v[70:71], v[78:79], v[78:79]
	v_mov_b32_e32 v72, v65
	v_mov_b32_e32 v73, v61
	v_mov_b32_e32 v84, v48
	v_mov_b32_e32 v85, v44
	v_mov_b32_e32 v96, v38
	v_mov_b32_e32 v97, v34
	v_pk_mul_f32 v[78:79], v[98:99], v[98:99]
	v_pk_fma_f32 v[70:71], v[76:77], v[76:77], v[70:71]
	v_mov_b32_e32 v80, v56
	v_mov_b32_e32 v81, v52
	v_mov_b32_e32 v94, v49
	v_mov_b32_e32 v95, v45
	v_mov_b32_e32 v100, v40
	v_mov_b32_e32 v101, v36
	v_pk_fma_f32 v[66:67], v[72:73], v[72:73], v[66:67]
	v_pk_fma_f32 v[72:73], v[96:97], v[96:97], v[78:79]
	v_pk_fma_f32 v[70:71], v[84:85], v[84:85], v[70:71]
	v_mov_b32_e32 v82, v57
	v_mov_b32_e32 v83, v53
	v_mov_b32_e32 v102, v41
	v_mov_b32_e32 v103, v37
	v_pk_fma_f32 v[68:69], v[80:81], v[80:81], v[68:69]
	v_pk_fma_f32 v[72:73], v[100:101], v[100:101], v[72:73]
	v_pk_fma_f32 v[70:71], v[94:95], v[94:95], v[70:71]
	v_pk_fma_f32 v[68:69], v[82:83], v[82:83], v[68:69]
	v_mov_b32_e32 v77, v66
	v_pk_fma_f32 v[72:73], v[102:103], v[102:103], v[72:73]
	v_mov_b32_e32 v76, v70
	v_mov_b32_e32 v66, v71
	v_mov_b32_e32 v79, v68
	v_mov_b32_e32 v78, v72
	v_pk_add_f32 v[66:67], v[76:77], v[66:67]
	v_mov_b32_e32 v68, v73
	v_pk_add_f32 v[66:67], v[66:67], v[78:79]
	global_load_dwordx4 v[70:73], v0, s[14:15] offset:2048
	v_pk_add_f32 v[66:67], v[66:67], v[68:69]
	ds_bpermute_b32 v69, v87, v67
	ds_bpermute_b32 v68, v87, v66
	s_waitcnt vmcnt(4)
	v_pk_add_f32 v[98:99], v[92:93], 1.0 op_sel_hi:[1,0]
	v_pk_add_f32 v[102:103], v[90:91], 1.0 op_sel_hi:[1,0]
	s_waitcnt vmcnt(2)
	v_pk_add_f32 v[90:91], v[116:117], 1.0 op_sel_hi:[1,0]
	s_waitcnt lgkmcnt(0)
	v_pk_add_f32 v[76:77], v[66:67], v[68:69]
	ds_bpermute_b32 v79, v108, v77
	ds_bpermute_b32 v78, v108, v76
	global_load_dwordx4 v[66:69], v0, s[14:15] offset:3072
	s_mov_b32 s14, 0x358637bd
	v_mov_b64_e32 v[100:101], s[14:15]
	s_lshl_b64 s[14:15], s[12:13], 6
	s_waitcnt lgkmcnt(0)
	v_pk_add_f32 v[76:77], v[76:77], v[78:79]
	ds_bpermute_b32 v79, v109, v77
	ds_bpermute_b32 v78, v109, v76
	s_add_u32 s14, s20, s14
	s_addc_u32 s15, s21, s15
	s_waitcnt lgkmcnt(0)
	v_pk_add_f32 v[76:77], v[76:77], v[78:79]
	ds_bpermute_b32 v79, v110, v77
	ds_bpermute_b32 v78, v110, v76
	s_waitcnt lgkmcnt(0)
	v_pk_add_f32 v[94:95], v[76:77], v[78:79]
	ds_bpermute_b32 v97, v111, v95
	ds_bpermute_b32 v96, v111, v94
	global_load_dwordx4 v[78:81], v[74:75], off offset:1024 nt
	global_load_dwordx4 v[82:85], v[74:75], off offset:2048 nt
	s_nop 0
	global_load_dwordx4 v[74:77], v[74:75], off offset:3072 nt
	s_waitcnt lgkmcnt(0)
	v_pk_add_f32 v[92:93], v[94:95], v[96:97]
	ds_bpermute_b32 v123, v112, v93
	ds_bpermute_b32 v122, v112, v92
	v_pk_add_f32 v[94:95], v[106:107], 1.0 op_sel_hi:[1,0]
	s_waitcnt vmcnt(5)
	v_pk_add_f32 v[106:107], v[118:119], 1.0 op_sel_hi:[1,0]
	v_pk_add_f32 v[96:97], v[104:105], 1.0 op_sel_hi:[1,0]
	v_pk_add_f32 v[104:105], v[120:121], 1.0 op_sel_hi:[1,0]
	s_waitcnt lgkmcnt(0)
; #define GAS __attribute__((address_space(1)))
; DI unsigned pk2(float a, float b) { f32x2 v = {a, b}; bf2_t r = __builtin_convertvector(v, bf2_t); return __builtin_bit_cast(unsigned, r); }
; DI float bflo(unsigned w) { return __uint_as_float(w << 16); }
; DI float bfhi(unsigned w) { return __uint_as_float(w & 0xffff0000u); }
; DI void rw_rows4(const RowIO4& R, const float* __restrict__ ga, const float* __restrict__ gb, int lane) {
;     ...
;   for (int r = 0; r < 4; ++r) {
;     if (R.y) {
;       f32x4 yv[4]; float ss = 0.f;
; #pragma unroll
;       for (int i = 0; i < 4; ++i) {
;         yv[i] = (f32x4){bflo(yr[r][i].x), bfhi(yr[r][i].x), bflo(yr[r][i].y), bfhi(yr[r][i].y)};
;         ss += yv[i][0] * yv[i][0] + yv[i][1] * yv[i][1] + yv[i][2] * yv[i][2] + yv[i][3] * yv[i][3];
;       }
;       const float rinv = rsqrtf(wave_sum(ss) * (1.f / 1024.f) + 1e-6f);
; #pragma unroll
;       for (int i = 0; i < 4; ++i) x[r][i] = x[r][i] + gt4[i] * (yv[i] * rinv * ga4[i]);
;     }
;     if (R.xout) {
; #pragma unroll
;       for (int i = 0; i < 4; ++i) __builtin_nontemporal_store(x[r][i], (GAS f32x4*)(R.xout + r * 1024 + 4 * lane + 256 * i));
;     }
;     if (R.hout) {
;       float ss = 0.f;
; #pragma unroll
;       for (int i = 0; i < 4; ++i) ss += x[r][i][0] * x[r][i][0] + x[r][i][1] * x[r][i][1] + x[r][i][2] * x[r][i][2] + x[r][i][3] * x[r][i][3];
;       const float rinv = rsqrtf(wave_sum(ss) * (1.f / 1024.f) + 1e-6f);
; #pragma unroll
;       for (int i = 0; i < 4; ++i) {
;         const f32x4 hv = (x[r][i] * rinv * gb4[i]) * (sc4[i] + 1.f) + sh4[i];
;         u32x2 w; w.x = pk2(hv[0], hv[1]); w.y = pk2(hv[2], hv[3]);
;         *(GAS u32x2*)(R.hout + r * 1024 + 4 * lane + 256 * i) = w;
;       }
;     }
	v_pk_add_f32 v[92:93], v[92:93], v[122:123]
	s_nop 0
	v_pk_fma_f32 v[116:117], v[92:93], s[16:17], v[100:101] op_sel_hi:[1,0,0]
	v_pk_add_f32 v[92:93], v[114:115], 1.0 op_sel_hi:[1,0]
	v_mul_f32_e32 v0, 0x4b800000, v117
	v_cmp_gt_f32_e32 vcc, s10, v117
	s_nop 1
	v_cndmask_b32_e32 v0, v117, v0, vcc
	v_rsq_f32_e32 v0, v0
	s_nop 0
	v_mul_f32_e32 v113, 0x45800000, v0
	v_cndmask_b32_e32 v0, v0, v113, vcc
	v_pk_mul_f32 v[114:115], v[60:61], v[0:1] op_sel_hi:[1,0]
	v_pk_mul_f32 v[118:119], v[58:59], v[0:1] op_sel_hi:[1,0]
	global_load_dwordx4 v[58:61], v[88:89], off offset:1024 nt
	v_pk_mul_f32 v[120:121], v[56:57], v[0:1] op_sel_hi:[1,0]
	v_pk_mul_f32 v[122:123], v[54:55], v[0:1] op_sel_hi:[1,0]
	v_pk_mul_f32 v[124:125], v[52:53], v[0:1] op_sel_hi:[1,0]
	v_pk_mul_f32 v[126:127], v[50:51], v[0:1] op_sel_hi:[1,0]
	global_load_dwordx4 v[54:57], v[88:89], off offset:2048 nt
	global_load_dwordx4 v[50:53], v[88:89], off offset:3072 nt
	v_pk_mul_f32 v[64:65], v[64:65], v[0:1] op_sel_hi:[1,0]
	v_pk_mul_f32 v[62:63], v[62:63], v[0:1] op_sel_hi:[1,0]
	v_pk_mul_f32 v[64:65], v[4:5], v[64:65]
	v_pk_mul_f32 v[62:63], v[2:3], v[62:63]
	v_pk_fma_f32 v[64:65], v[104:105], v[64:65], v[24:25]
	v_pk_fma_f32 v[62:63], v[106:107], v[62:63], v[22:23]
	v_lshlrev_b32_e32 v0, 1, v86
	v_lshrrev_b32_e32 v244, 6, v0
	v_and_b32_e32 v240, 56, v0
	v_mul_u32_u24_e32 v244, 0x480000, v244
	v_add_u32_e32 v240, v240, v244
	v_add_u32_e32 v241, 0x2400000, v240
	v_add_u32_e32 v242, 0x4800000, v240
	v_add_u32_e32 v243, 0x6c00000, v240
	v_cvt_pk_bf16_f32 v62, v62, v63
	v_cvt_pk_bf16_f32 v63, v64, v65
	global_store_dwordx2 v240, v[62:63], s[14:15]
	v_pk_mul_f32 v[62:63], v[6:7], v[118:119]
	v_pk_mul_f32 v[64:65], v[8:9], v[114:115]
	v_pk_fma_f32 v[62:63], v[102:103], v[62:63], v[18:19]
	v_pk_fma_f32 v[64:65], v[98:99], v[64:65], v[20:21]
	v_cvt_pk_bf16_f32 v62, v62, v63
	v_cvt_pk_bf16_f32 v63, v64, v65
	global_store_dwordx2 v241, v[62:63], s[14:15]
	v_pk_mul_f32 v[62:63], v[10:11], v[122:123]
	v_pk_mul_f32 v[64:65], v[12:13], v[120:121]
	v_mul_f32_e32 v88, 0x4b800000, v116
	v_cmp_gt_f32_e32 vcc, s10, v116
	s_waitcnt vmcnt(9)
	v_pk_fma_f32 v[64:65], v[94:95], v[64:65], v[72:73]
	v_pk_fma_f32 v[62:63], v[96:97], v[62:63], v[70:71]
	v_cndmask_b32_e32 v88, v116, v88, vcc
	v_cvt_pk_bf16_f32 v62, v62, v63
	v_cvt_pk_bf16_f32 v63, v64, v65
	v_rsq_f32_e32 v88, v88
	global_store_dwordx2 v242, v[62:63], s[14:15]
	v_pk_mul_f32 v[62:63], v[14:15], v[126:127]
	v_pk_mul_f32 v[64:65], v[16:17], v[124:125]
	s_waitcnt vmcnt(9)
	v_pk_fma_f32 v[62:63], v[92:93], v[62:63], v[66:67]
	v_pk_fma_f32 v[64:65], v[90:91], v[64:65], v[68:69]
	v_cvt_pk_bf16_f32 v62, v62, v63
	v_cvt_pk_bf16_f32 v63, v64, v65
	global_store_dwordx2 v243, v[62:63], s[14:15]
	v_mul_f32_e32 v62, 0x45800000, v88
	v_cndmask_b32_e32 v62, v88, v62, vcc
	v_pk_mul_f32 v[48:49], v[48:49], v[62:63] op_sel_hi:[1,0]
	v_pk_mul_f32 v[46:47], v[46:47], v[62:63] op_sel_hi:[1,0]
	v_pk_mul_f32 v[48:49], v[4:5], v[48:49]
	v_pk_mul_f32 v[46:47], v[2:3], v[46:47]
	v_pk_fma_f32 v[48:49], v[104:105], v[48:49], v[24:25]
	v_pk_fma_f32 v[46:47], v[106:107], v[46:47], v[22:23]
	v_mov_b32_e32 v88, v27
	v_cvt_pk_bf16_f32 v46, v46, v47
	v_cvt_pk_bf16_f32 v47, v48, v49
	v_mov_b32_e32 v48, v31
	s_waitcnt vmcnt(9)
	v_mov_b32_e32 v49, v79
	global_store_dwordx2 v240, v[46:47], s[14:15] offset:64
	v_mov_b32_e32 v46, v30
	v_mov_b32_e32 v47, v78
	v_pk_mul_f32 v[48:49], v[48:49], v[48:49]
	s_waitcnt vmcnt(9)
	v_mov_b32_e32 v64, v83
	v_pk_fma_f32 v[46:47], v[46:47], v[46:47], v[48:49]
	v_mov_b32_e32 v48, v32
	v_mov_b32_e32 v49, v80
	v_pk_fma_f32 v[46:47], v[48:49], v[48:49], v[46:47]
	v_mov_b32_e32 v48, v33
	v_mov_b32_e32 v49, v81
	s_waitcnt vmcnt(8)
	v_mov_b32_e32 v65, v75
	v_pk_fma_f32 v[46:47], v[48:49], v[48:49], v[46:47]
	v_mov_b32_e32 v48, v82
	v_mov_b32_e32 v49, v74
	v_pk_mul_f32 v[64:65], v[64:65], v[64:65]
	v_pk_mul_f32 v[44:45], v[44:45], v[62:63] op_sel_hi:[1,0]
	v_pk_fma_f32 v[48:49], v[48:49], v[48:49], v[64:65]
	v_mov_b32_e32 v64, v84
	v_mov_b32_e32 v65, v76
	v_pk_fma_f32 v[48:49], v[64:65], v[64:65], v[48:49]
	v_mov_b32_e32 v64, v85
	v_mov_b32_e32 v65, v77
	v_pk_fma_f32 v[48:49], v[64:65], v[64:65], v[48:49]
	v_mov_b32_e32 v64, v26
	v_pk_mul_f32 v[42:43], v[42:43], v[62:63] op_sel_hi:[1,0]
	s_waitcnt vmcnt(7)
	v_mov_b32_e32 v89, v59
	v_mov_b32_e32 v65, v58
	v_pk_mul_f32 v[88:89], v[88:89], v[88:89]
	v_pk_mul_f32 v[42:43], v[6:7], v[42:43]
	v_pk_fma_f32 v[64:65], v[64:65], v[64:65], v[88:89]
	v_mov_b32_e32 v88, v28
	v_mov_b32_e32 v89, v60
	v_pk_fma_f32 v[64:65], v[88:89], v[88:89], v[64:65]
	v_mov_b32_e32 v88, v29
	v_mov_b32_e32 v89, v61
	s_waitcnt vmcnt(6)
	v_mov_b32_e32 v114, v55
	s_waitcnt vmcnt(5)
	v_mov_b32_e32 v115, v51
	v_pk_fma_f32 v[64:65], v[88:89], v[88:89], v[64:65]
	v_mov_b32_e32 v88, v54
	v_mov_b32_e32 v89, v50
	v_pk_mul_f32 v[114:115], v[114:115], v[114:115]
	v_pk_mul_f32 v[44:45], v[8:9], v[44:45]
	v_pk_fma_f32 v[88:89], v[88:89], v[88:89], v[114:115]
	v_mov_b32_e32 v114, v56
	v_mov_b32_e32 v115, v52
	v_pk_fma_f32 v[88:89], v[114:115], v[114:115], v[88:89]
	v_mov_b32_e32 v114, v57
	v_mov_b32_e32 v115, v53
	v_pk_fma_f32 v[88:89], v[114:115], v[114:115], v[88:89]
	v_mov_b32_e32 v114, v64
	v_mov_b32_e32 v115, v46
	v_mov_b32_e32 v46, v65
	v_pk_add_f32 v[46:47], v[114:115], v[46:47]
	v_mov_b32_e32 v64, v88
	v_mov_b32_e32 v65, v48
	v_pk_add_f32 v[46:47], v[46:47], v[64:65]
	v_mov_b32_e32 v48, v89
	v_pk_add_f32 v[46:47], v[46:47], v[48:49]
	ds_bpermute_b32 v49, v87, v47
	ds_bpermute_b32 v48, v87, v46
	v_pk_fma_f32 v[44:45], v[98:99], v[44:45], v[20:21]
	v_pk_fma_f32 v[42:43], v[102:103], v[42:43], v[18:19]
	v_pk_mul_f32 v[40:41], v[40:41], v[62:63] op_sel_hi:[1,0]
	v_cvt_pk_bf16_f32 v42, v42, v43
	s_waitcnt lgkmcnt(0)
; #define GAS __attribute__((address_space(1)))
; DI unsigned pk2(float a, float b) { f32x2 v = {a, b}; bf2_t r = __builtin_convertvector(v, bf2_t); return __builtin_bit_cast(unsigned, r); }
; DI void rw_rows4(const RowIO4& R, const float* __restrict__ ga, const float* __restrict__ gb, int lane) {
;     ...
;     if (R.hout) {
;       float ss = 0.f;
; #pragma unroll
;       for (int i = 0; i < 4; ++i) ss += x[r][i][0] * x[r][i][0] + x[r][i][1] * x[r][i][1] + x[r][i][2] * x[r][i][2] + x[r][i][3] * x[r][i][3];
;       const float rinv = rsqrtf(wave_sum(ss) * (1.f / 1024.f) + 1e-6f);
; #pragma unroll
;       for (int i = 0; i < 4; ++i) {
;         const f32x4 hv = (x[r][i] * rinv * gb4[i]) * (sc4[i] + 1.f) + sh4[i];
;         u32x2 w; w.x = pk2(hv[0], hv[1]); w.y = pk2(hv[2], hv[3]);
;         *(GAS u32x2*)(R.hout + r * 1024 + 4 * lane + 256 * i) = w;
;       }
;     }
	v_pk_add_f32 v[46:47], v[46:47], v[48:49]
	ds_bpermute_b32 v49, v108, v47
	ds_bpermute_b32 v48, v108, v46
	v_cvt_pk_bf16_f32 v43, v44, v45
	global_store_dwordx2 v241, v[42:43], s[14:15] offset:64
	v_pk_mul_f32 v[38:39], v[38:39], v[62:63] op_sel_hi:[1,0]
	v_pk_mul_f32 v[40:41], v[12:13], v[40:41]
	s_waitcnt lgkmcnt(0)
	v_pk_add_f32 v[46:47], v[46:47], v[48:49]
	ds_bpermute_b32 v49, v109, v47
	ds_bpermute_b32 v48, v109, v46
	v_pk_mul_f32 v[38:39], v[10:11], v[38:39]
	v_pk_fma_f32 v[40:41], v[94:95], v[40:41], v[72:73]
	v_pk_fma_f32 v[38:39], v[96:97], v[38:39], v[70:71]
	v_pk_mul_f32 v[36:37], v[36:37], v[62:63] op_sel_hi:[1,0]
	s_waitcnt lgkmcnt(0)
	v_pk_add_f32 v[42:43], v[46:47], v[48:49]
	ds_bpermute_b32 v47, v110, v43
	ds_bpermute_b32 v46, v110, v42
	v_cvt_pk_bf16_f32 v38, v38, v39
	v_cvt_pk_bf16_f32 v39, v40, v41
	global_store_dwordx2 v242, v[38:39], s[14:15] offset:64
	v_pk_mul_f32 v[34:35], v[34:35], v[62:63] op_sel_hi:[1,0]
	s_waitcnt lgkmcnt(0)
	v_pk_add_f32 v[42:43], v[42:43], v[46:47]
	ds_bpermute_b32 v47, v111, v43
	ds_bpermute_b32 v46, v111, v42
	v_pk_mul_f32 v[34:35], v[14:15], v[34:35]
	v_pk_mul_f32 v[36:37], v[16:17], v[36:37]
	v_pk_fma_f32 v[34:35], v[92:93], v[34:35], v[66:67]
	v_pk_fma_f32 v[36:37], v[90:91], v[36:37], v[68:69]
	s_waitcnt lgkmcnt(0)
	v_pk_add_f32 v[38:39], v[42:43], v[46:47]
	ds_bpermute_b32 v41, v112, v39
	ds_bpermute_b32 v40, v112, v38
	v_cvt_pk_bf16_f32 v34, v34, v35
	v_cvt_pk_bf16_f32 v35, v36, v37
	v_lshl_add_u64 v[44:45], s[14:15], 0, v[0:1]
	global_store_dwordx2 v243, v[34:35], s[14:15] offset:64
	s_waitcnt lgkmcnt(0)
	v_pk_add_f32 v[38:39], v[38:39], v[40:41]
	s_nop 0
	v_pk_fma_f32 v[38:39], v[38:39], s[16:17], v[100:101] op_sel_hi:[1,0,0]
	s_nop 0
	v_mul_f32_e32 v40, 0x4b800000, v39
	v_cmp_gt_f32_e32 vcc, s10, v39
	s_nop 1
	v_cndmask_b32_e32 v39, v39, v40, vcc
	v_rsq_f32_e32 v39, v39
	s_nop 0
	v_mul_f32_e32 v0, 0x45800000, v39
	v_cndmask_b32_e32 v0, v39, v0, vcc
	v_pk_mul_f32 v[32:33], v[32:33], v[0:1] op_sel_hi:[1,0]
	v_pk_mul_f32 v[30:31], v[30:31], v[0:1] op_sel_hi:[1,0]
	v_pk_mul_f32 v[32:33], v[4:5], v[32:33]
	v_pk_mul_f32 v[30:31], v[2:3], v[30:31]
	v_pk_fma_f32 v[32:33], v[104:105], v[32:33], v[24:25]
	v_pk_fma_f32 v[30:31], v[106:107], v[30:31], v[22:23]
	v_pk_mul_f32 v[34:35], v[78:79], v[0:1] op_sel_hi:[1,0]
	v_cvt_pk_bf16_f32 v30, v30, v31
	v_cvt_pk_bf16_f32 v31, v32, v33
	v_add_co_u32_e32 v32, vcc, s23, v44
	v_pk_mul_f32 v[34:35], v[6:7], v[34:35]
	s_nop 0
	v_addc_co_u32_e32 v33, vcc, 0, v45, vcc
	global_store_dwordx2 v240, v[30:31], s[14:15] offset:128
	v_pk_mul_f32 v[30:31], v[80:81], v[0:1] op_sel_hi:[1,0]
	v_pk_fma_f32 v[34:35], v[102:103], v[34:35], v[18:19]
	v_pk_mul_f32 v[30:31], v[8:9], v[30:31]
	v_cvt_pk_bf16_f32 v34, v34, v35
	v_pk_fma_f32 v[30:31], v[98:99], v[30:31], v[20:21]
	v_cmp_gt_f32_e32 vcc, s10, v38
	v_cvt_pk_bf16_f32 v35, v30, v31
	global_store_dwordx2 v241, v[34:35], s[14:15] offset:128
	v_pk_mul_f32 v[30:31], v[84:85], v[0:1] op_sel_hi:[1,0]
	v_pk_mul_f32 v[34:35], v[82:83], v[0:1] op_sel_hi:[1,0]
	v_pk_mul_f32 v[30:31], v[12:13], v[30:31]
	v_pk_mul_f32 v[34:35], v[10:11], v[34:35]
	v_pk_fma_f32 v[30:31], v[94:95], v[30:31], v[72:73]
	v_pk_fma_f32 v[34:35], v[96:97], v[34:35], v[70:71]
	v_readlane_b32 s10, v251, 59
	v_cvt_pk_bf16_f32 v34, v34, v35
	v_cvt_pk_bf16_f32 v35, v30, v31
	global_store_dwordx2 v242, v[34:35], s[14:15] offset:128
	v_pk_mul_f32 v[30:31], v[76:77], v[0:1] op_sel_hi:[1,0]
	v_pk_mul_f32 v[34:35], v[74:75], v[0:1] op_sel_hi:[1,0]
	v_mul_f32_e32 v0, 0x4b800000, v38
	v_cndmask_b32_e32 v0, v38, v0, vcc
	v_rsq_f32_e32 v0, v0
	v_pk_mul_f32 v[34:35], v[14:15], v[34:35]
	v_pk_mul_f32 v[30:31], v[16:17], v[30:31]
	v_pk_fma_f32 v[34:35], v[92:93], v[34:35], v[66:67]
	v_pk_fma_f32 v[30:31], v[90:91], v[30:31], v[68:69]
	v_cvt_pk_bf16_f32 v34, v34, v35
	v_cvt_pk_bf16_f32 v35, v30, v31
	v_mul_f32_e32 v30, 0x45800000, v0
	v_cndmask_b32_e32 v0, v0, v30, vcc
	v_pk_mul_f32 v[28:29], v[28:29], v[0:1] op_sel_hi:[1,0]
	v_pk_mul_f32 v[26:27], v[26:27], v[0:1] op_sel_hi:[1,0]
	v_pk_mul_f32 v[28:29], v[4:5], v[28:29]
	v_pk_mul_f32 v[26:27], v[2:3], v[26:27]
	v_pk_fma_f32 v[24:25], v[104:105], v[28:29], v[24:25]
	v_pk_fma_f32 v[22:23], v[106:107], v[26:27], v[22:23]
	s_add_i32 s22, s22, s10
	v_cvt_pk_bf16_f32 v22, v22, v23
	v_cvt_pk_bf16_f32 v23, v24, v25
	global_store_dwordx2 v240, v[22:23], s[14:15] offset:192
	v_pk_mul_f32 v[22:23], v[60:61], v[0:1] op_sel_hi:[1,0]
	v_pk_mul_f32 v[24:25], v[58:59], v[0:1] op_sel_hi:[1,0]
	v_pk_mul_f32 v[22:23], v[8:9], v[22:23]
	v_pk_mul_f32 v[24:25], v[6:7], v[24:25]
	v_pk_fma_f32 v[20:21], v[98:99], v[22:23], v[20:21]
	v_pk_fma_f32 v[18:19], v[102:103], v[24:25], v[18:19]
	v_readlane_b32 s10, v251, 63
	v_cvt_pk_bf16_f32 v18, v18, v19
	v_cvt_pk_bf16_f32 v19, v20, v21
	global_store_dwordx2 v241, v[18:19], s[14:15] offset:192
	v_pk_mul_f32 v[18:19], v[56:57], v[0:1] op_sel_hi:[1,0]
	v_pk_mul_f32 v[20:21], v[54:55], v[0:1] op_sel_hi:[1,0]
	v_pk_mul_f32 v[18:19], v[12:13], v[18:19]
	v_pk_mul_f32 v[20:21], v[10:11], v[20:21]
	v_pk_fma_f32 v[18:19], v[94:95], v[18:19], v[72:73]
	v_pk_fma_f32 v[20:21], v[96:97], v[20:21], v[70:71]
	s_add_i32 s12, s12, s10
	v_cvt_pk_bf16_f32 v20, v20, v21
	v_cvt_pk_bf16_f32 v21, v18, v19
	global_store_dwordx2 v242, v[20:21], s[14:15] offset:192
	v_pk_mul_f32 v[18:19], v[52:53], v[0:1] op_sel_hi:[1,0]
	v_pk_mul_f32 v[20:21], v[50:51], v[0:1] op_sel_hi:[1,0]
	v_pk_mul_f32 v[18:19], v[16:17], v[18:19]
	v_pk_mul_f32 v[20:21], v[14:15], v[20:21]
	v_pk_fma_f32 v[18:19], v[90:91], v[18:19], v[68:69]
	v_pk_fma_f32 v[20:21], v[92:93], v[20:21], v[66:67]
	s_cmpk_gt_i32 s22, 0x47ff
	v_cvt_pk_bf16_f32 v20, v20, v21
	v_cvt_pk_bf16_f32 v21, v18, v19
	global_store_dwordx2 v243, v[34:35], s[14:15] offset:128
	global_store_dwordx2 v243, v[20:21], s[14:15] offset:192
	s_cbranch_scc1 .LBB0_197

; #define LAS __attribute__((address_space(3)))
;     ...
;   const int lane = tid & 63, wid = __builtin_amdgcn_readfirstlane(tid >> 6), wr = wid >> 1, wc = wid & 1;
;   const int m0 = mt * 128, n0 = nt * 256;
;   const int r = lane & 31, h = lane >> 5, key = (r >> 2) & 3;
;   constexpr int STG = 24576;
;   const int rowl = lane >> 2, cch = (lane & 3) ^ ((lane >> 4) & 3);
;   const unsigned voffA = (unsigned)(rowl * lda * 2 + cch * 16), voffB = (unsigned)(rowl * K * 2 + cch * 16);
;   const char* Abase = (const char*)(A + (size_t)m0 * lda) + (size_t)(wid * 2) * 32 * lda;
;   const char* Bbase = (const char*)(Bt + (size_t)n0 * K) + (size_t)(wid * 4) * 32 * K;
;   const size_t ablk = (size_t)32 * lda, bblk = (size_t)32 * K;
;   LAS char* lds = (LAS char*)smem;
;   LAS char* ldsA = lds + (wid * 2) * 1024;
;   LAS char* ldsB = lds + 8192 + (wid * 4) * 1024;
;     ...
;   const int x0 = ((0 + h) ^ key) * 16, x1 = ((2 + h) ^ key) * 16;
;   const int a_rd = (wr * 64 + r) * 64, b_rd = 8192 + (wc * 128 + r) * 64;
;   f32x16 acc[2][4];
; #pragma unroll
;   for (int i = 0; i < 2; ++i)
; #pragma unroll
;     for (int j = 0; j < 4; ++j)
; #pragma unroll
;       for (int e = 0; e < 16; ++e) acc[i][j][e] = 0.f;
;   const int nk = K >> 5;
;   DMA_STEP_(0, 0);
;   DMA_STEP_(1, STG);
;   asm volatile("s_waitcnt vmcnt(6)" ::: "memory");
;   __builtin_amdgcn_s_barrier();
;   asm volatile("" ::: "memory");
;   int s0 = 0, s2 = 2 * STG;
.LBB0_183:
	s_mul_hi_i32 s10, s20, 0x38e38e39
	s_lshr_b32 s11, s10, 31
	s_ashr_i32 s10, s10, 4
	v_mov_b32_e32 v189, v188
	s_add_i32 s10, s10, s11
	v_readlane_b32 s12, v252, 18
	s_mul_i32 s11, s10, 0xffffffb8
	v_readfirstlane_b32 s21, v189
	s_lshl_b32 s10, s10, s12
	v_readlane_b32 s12, v252, 41
	s_ashr_i32 s44, s21, 6
	s_add_i32 s10, s10, s12
	s_lshl_b32 s12, s20, 7
	s_lshl_b32 s22, s44, 1
	s_add_i32 s11, s11, s20
	s_lshl_b32 s10, s10, 10
	s_and_b32 s12, s12, 0x380
	s_ashr_i32 s23, s22, 31
	s_or_b32 s12, s10, s12
	s_lshl_b32 s10, s11, 5
	s_lshl_b64 s[28:29], s[22:23], 10
	s_lshl_b32 s22, s44, 2
	s_ashr_i32 s11, s21, 1
	s_and_b32 s14, s10, 0xffffff00
	v_and_b32_e32 v0, 31, v189
	s_ashr_i32 s23, s22, 31
	s_lshl_b32 s10, s44, 12
	s_andn2_b32 s11, s11, 63
	v_lshlrev_b32_e32 v2, 4, v189
	s_ashr_i32 s13, s12, 31
	s_lshl_b64 s[40:41], s[22:23], 10
	s_add_i32 s22, s10, 16
	v_or_b32_e32 v197, s11, v0
	s_lshl_b32 s11, s44, 7
	v_bitop3_b32 v2, v2, 48, v189 bitop3:0x48
	v_lshlrev_b32_e32 v3, 9, v189
	s_ashr_i32 s15, s14, 31
	s_add_i32 s10, s22, 0x2000
	s_and_b32 s21, s11, 0x80
	s_movk_i32 s11, 0x7800
	s_lshl_b64 s[42:43], s[12:13], 6
	v_or_b32_e32 v4, s21, v0
	v_and_or_b32 v0, v3, s11, v2
	v_lshlrev_b32_e32 v10, 4, v189
	v_and_b32_e32 v10, 0x3c0, v10
	v_or_b32_e32 v10, v10, v2
	v_mov_b32_e32 v11, 0
	s_add_u32 s11, s18, s42
	s_addc_u32 s13, s19, s43
	s_add_u32 s28, s11, s28
	s_addc_u32 s29, s13, s29
	s_lshl_b64 s[42:43], s[14:15], 6
	v_readlane_b32 s46, v250, 18
	v_readlane_b32 s47, v250, 19
	s_add_u32 s11, s46, s42
	s_addc_u32 s13, s47, s43
	s_add_u32 s40, s11, s40
	s_addc_u32 s41, s13, s41
	s_lshl_b32 s11, s44, 11
	s_sub_i32 s13, s22, s11
	v_lshl_add_u64 v[192:193], s[28:29], 0, v[10:11]
	s_mov_b32 m0, s13
	s_nop 0
	global_load_lds_dwordx4 v[192:193], off
	global_load_lds_dwordx4 v[192:193], off offset:1024
	v_lshl_add_u64 v[194:195], s[40:41], 0, v[10:11]
	s_mov_b32 m0, s10
	s_nop 0
	global_load_lds_dwordx4 v[194:195], off
	global_load_lds_dwordx4 v[194:195], off offset:1024
	global_load_lds_dwordx4 v[194:195], off offset:2048
	global_load_lds_dwordx4 v[194:195], off offset:3072
	s_mov_b64 s[10:11], 0x10000
	s_mov_b64 s[10:11], 0x18000
	s_mov_b64 s[10:11], 0x8040
	s_add_i32 m0, s13, 0x6000
	s_mov_b32 vcc_lo, 0x480000
	s_mov_b32 vcc_hi, 0
	v_lshl_add_u64 v[2:3], v[192:193], 0, vcc
	global_load_lds_dwordx4 v[2:3], off
	global_load_lds_dwordx4 v[2:3], off offset:1024
	v_bfe_u32 v196, v189, 5, 1
	s_add_i32 m0, s22, 0x8000
	s_mov_b32 s100, 0x24000
	v_lshl_add_u64 v[2:3], v[194:195], 0, s[100:101]
	global_load_lds_dwordx4 v[2:3], off
	global_load_lds_dwordx4 v[2:3], off offset:1024
	global_load_lds_dwordx4 v[2:3], off offset:2048
	global_load_lds_dwordx4 v[2:3], off offset:3072
	s_mov_b64 s[10:11], 0x10040
	s_mov_b64 s[10:11], 0x18040
	v_lshlrev_b32_e32 v218, 6, v4
	v_bfe_u32 v4, v189, 2, 2
	v_lshrrev_b32_e32 v5, 5, v189
	s_lshl_b32 s100, s100, 1
	v_lshl_add_u64 v[194:195], v[194:195], 0, s[100:101]
	s_lshl_b32 vcc_lo, vcc_lo, 1
	v_lshl_add_u64 v[192:193], v[192:193], 0, vcc
	s_waitcnt vmcnt(6)
	s_barrier
	v_bitop3_b32 v2, v196, v4, 2 bitop3:0x36
	v_bitop3_b32 v0, v5, v4, 1 bitop3:0x6c
	v_lshlrev_b32_e32 v220, 4, v2
	v_mov_b32_e32 v2, 0
	v_lshlrev_b32_e32 v219, 6, v197
	v_lshlrev_b32_e32 v0, 4, v0
	s_mov_b32 s28, 0xc000
	s_mov_b32 s23, 0
	s_mov_b32 s29, 0
	v_mov_b32_e32 v3, v2
	v_mov_b32_e32 v4, v2
	v_mov_b32_e32 v5, v2
	v_mov_b32_e32 v6, v2
	v_mov_b32_e32 v7, v2
	v_mov_b32_e32 v8, v2
	v_mov_b32_e32 v9, v2
	v_mov_b32_e32 v10, v2
	v_mov_b32_e32 v11, v2
	v_mov_b32_e32 v12, v2
	v_mov_b32_e32 v13, v2
	v_mov_b32_e32 v14, v2
	v_mov_b32_e32 v15, v2
	v_mov_b32_e32 v16, v2
	v_mov_b32_e32 v17, v2
	v_mov_b32_e32 v18, v2
	v_mov_b32_e32 v19, v2
	v_mov_b32_e32 v20, v2
	v_mov_b32_e32 v21, v2
	v_mov_b32_e32 v22, v2
	v_mov_b32_e32 v23, v2
	v_mov_b32_e32 v24, v2
	v_mov_b32_e32 v25, v2
	v_mov_b32_e32 v26, v2
	v_mov_b32_e32 v27, v2
	v_mov_b32_e32 v28, v2
	v_mov_b32_e32 v29, v2
	v_mov_b32_e32 v30, v2
	v_mov_b32_e32 v31, v2
	v_mov_b32_e32 v32, v2
	v_mov_b32_e32 v33, v2
	v_mov_b32_e32 v50, v2
	v_mov_b32_e32 v51, v2
	v_mov_b32_e32 v52, v2
	v_mov_b32_e32 v53, v2
	v_mov_b32_e32 v54, v2
	v_mov_b32_e32 v55, v2
	v_mov_b32_e32 v56, v2
	v_mov_b32_e32 v57, v2
	v_mov_b32_e32 v58, v2
	v_mov_b32_e32 v59, v2
	v_mov_b32_e32 v60, v2
	v_mov_b32_e32 v61, v2
	v_mov_b32_e32 v62, v2
	v_mov_b32_e32 v63, v2
	v_mov_b32_e32 v64, v2
	v_mov_b32_e32 v65, v2
	v_mov_b32_e32 v82, v2
	v_mov_b32_e32 v83, v2
	v_mov_b32_e32 v84, v2
	v_mov_b32_e32 v85, v2
	v_mov_b32_e32 v86, v2
	v_mov_b32_e32 v87, v2
	v_mov_b32_e32 v88, v2
	v_mov_b32_e32 v89, v2
	v_mov_b32_e32 v90, v2
	v_mov_b32_e32 v91, v2
	v_mov_b32_e32 v92, v2
	v_mov_b32_e32 v93, v2
	v_mov_b32_e32 v94, v2
	v_mov_b32_e32 v95, v2
	v_mov_b32_e32 v96, v2
	v_mov_b32_e32 v97, v2
	v_mov_b32_e32 v34, v2
	v_mov_b32_e32 v35, v2
	v_mov_b32_e32 v36, v2
	v_mov_b32_e32 v37, v2
	v_mov_b32_e32 v38, v2
	v_mov_b32_e32 v39, v2
	v_mov_b32_e32 v40, v2
	v_mov_b32_e32 v41, v2
	v_mov_b32_e32 v42, v2
	v_mov_b32_e32 v43, v2
	v_mov_b32_e32 v44, v2
	v_mov_b32_e32 v45, v2
	v_mov_b32_e32 v46, v2
	v_mov_b32_e32 v47, v2
	v_mov_b32_e32 v48, v2
	v_mov_b32_e32 v49, v2
	v_mov_b32_e32 v66, v2
	v_mov_b32_e32 v67, v2
	v_mov_b32_e32 v68, v2
	v_mov_b32_e32 v69, v2
	v_mov_b32_e32 v70, v2
	v_mov_b32_e32 v71, v2
	v_mov_b32_e32 v72, v2
	v_mov_b32_e32 v73, v2
	v_mov_b32_e32 v74, v2
	v_mov_b32_e32 v75, v2
	v_mov_b32_e32 v76, v2
	v_mov_b32_e32 v77, v2
	v_mov_b32_e32 v78, v2
	v_mov_b32_e32 v79, v2
	v_mov_b32_e32 v80, v2
	v_mov_b32_e32 v81, v2
	v_mov_b32_e32 v98, v2
	v_mov_b32_e32 v99, v2
	v_mov_b32_e32 v100, v2
	v_mov_b32_e32 v101, v2
	v_mov_b32_e32 v102, v2
	v_mov_b32_e32 v103, v2
	v_mov_b32_e32 v104, v2
	v_mov_b32_e32 v105, v2
	v_mov_b32_e32 v106, v2
	v_mov_b32_e32 v107, v2
	v_mov_b32_e32 v108, v2
	v_mov_b32_e32 v109, v2
	v_mov_b32_e32 v110, v2
	v_mov_b32_e32 v111, v2
	v_mov_b32_e32 v112, v2
	v_mov_b32_e32 v113, v2
	v_mov_b32_e32 v114, v2
	v_mov_b32_e32 v115, v2
	v_mov_b32_e32 v116, v2
	v_mov_b32_e32 v117, v2
	v_mov_b32_e32 v118, v2
	v_mov_b32_e32 v119, v2
	v_mov_b32_e32 v120, v2
	v_mov_b32_e32 v121, v2
	v_mov_b32_e32 v122, v2
	v_mov_b32_e32 v123, v2
	v_mov_b32_e32 v124, v2
	v_mov_b32_e32 v125, v2
	v_mov_b32_e32 v126, v2
	v_mov_b32_e32 v127, v2
	v_mov_b32_e32 v128, v2
	v_mov_b32_e32 v129, v2
	s_mov_b32 vcc_hi, 0
	v_add_u32_e32 v158, 16, v219
	v_add_u32_e32 v170, 16, v218
	v_add_u32_e32 v158, v158, v0
	v_add_u32_e32 v170, v170, v0
	ds_read_b128 v[154:157], v158
	ds_read_b128 v[182:185], v170 offset:8192
	ds_read_b128 v[178:181], v170 offset:10240
	ds_read_b128 v[158:161], v158 offset:2048
	ds_read_b128 v[174:177], v170 offset:12288
	ds_read_b128 v[170:173], v170 offset:14336
; #define LAS __attribute__((address_space(3)))
; DI f32x16 mfma32(bf16x8 a, bf16x8 b, f32x16 c) { return __builtin_amdgcn_mfma_f32_32x32x16_bf16(a, b, c, 0, 0, 0); }
;     ...
;   for (int kt = 0; kt < nk; ++kt) {
;     const int kn = (kt + 2 < nk) ? (kt + 2) : (nk - 1);
;     const LAS char* cur = lds + s0;
;     bf16x8 af[2][2], bfr[2][4];
; #pragma unroll
;     for (int kk = 0; kk < 2; ++kk) {
;       const int xo = kk ? x1 : x0;
;       af[kk][0] = *(const LAS bf16x8*)(cur + a_rd + xo);
;       bfr[kk][0] = *(const LAS bf16x8*)(cur + b_rd + xo);
;       bfr[kk][1] = *(const LAS bf16x8*)(cur + b_rd + 2048 + xo);
;       af[kk][1] = *(const LAS bf16x8*)(cur + a_rd + 2048 + xo);
;       bfr[kk][2] = *(const LAS bf16x8*)(cur + b_rd + 4096 + xo);
;       bfr[kk][3] = *(const LAS bf16x8*)(cur + b_rd + 6144 + xo);
;     }
;     DMA_STEP_(kn, s2);
; #pragma unroll
;     for (int kk = 0; kk < 2; ++kk) {
;       acc[0][0] = mfma32(bfr[kk][0], af[kk][0], acc[0][0]); acc[0][1] = mfma32(bfr[kk][1], af[kk][0], acc[0][1]);
;       acc[1][0] = mfma32(bfr[kk][0], af[kk][1], acc[1][0]); acc[1][1] = mfma32(bfr[kk][1], af[kk][1], acc[1][1]);
;       acc[0][2] = mfma32(bfr[kk][2], af[kk][0], acc[0][2]); acc[0][3] = mfma32(bfr[kk][3], af[kk][0], acc[0][3]);
;       acc[1][2] = mfma32(bfr[kk][2], af[kk][1], acc[1][2]); acc[1][3] = mfma32(bfr[kk][3], af[kk][1], acc[1][3]);
;     }
;     __builtin_amdgcn_sched_group_barrier(0x100, 12, 0);
;     __builtin_amdgcn_sched_group_barrier(0x010, 6, 0);
;     __builtin_amdgcn_sched_group_barrier(0x008, 16, 0);
;     asm volatile("s_waitcnt vmcnt(6) lgkmcnt(0)" ::: "memory");
;     __builtin_amdgcn_s_barrier();
;     asm volatile("" ::: "memory");
;     s0 = (s0 == 2 * STG) ? 0 : s0 + STG;
;     s2 = (s2 == 2 * STG) ? 0 : s2 + STG;
;   }
.LBB0_184:
	s_add_i32 s11, s29, 16
	s_mov_b32 s10, s23
	v_add_u32_e32 v142, s11, v219
	v_add_u32_e32 v150, s11, v218
	s_min_u32 s10, s10, 29
	v_add_u32_e32 v142, v142, v220
	v_add_u32_e32 v150, v150, v220
	s_lshl_b32 s70, s10, 6
	ds_read_b128 v[138:141], v142
	ds_read_b128 v[162:165], v150 offset:8192
	ds_read_b128 v[166:169], v150 offset:10240
	ds_read_b128 v[142:145], v142 offset:2048
	ds_read_b128 v[146:149], v150 offset:12288
	ds_read_b128 v[150:153], v150 offset:14336
	s_mul_i32 vcc_lo, s70, 0x12000
	s_add_i32 s10, s13, s28
	v_lshl_add_u64 v[222:223], v[192:193], 0, vcc
	s_mov_b32 m0, s10
	s_mul_i32 s100, s70, 0x900
	v_lshl_add_u64 v[224:225], v[194:195], 0, s[100:101]
	s_add_i32 s10, s22, s28
	s_waitcnt lgkmcnt(6)
	v_mfma_f32_32x32x16_bf16 v[114:129], v[182:185], v[154:157], v[114:129]
	global_load_lds_dwordx4 v[222:223], off
	v_mfma_f32_32x32x16_bf16 v[98:113], v[178:181], v[154:157], v[98:113]
	global_load_lds_dwordx4 v[222:223], off offset:1024
	s_add_i32 m0, s10, 0x2000
	v_mfma_f32_32x32x16_bf16 v[66:81], v[182:185], v[158:161], v[66:81]
	global_load_lds_dwordx4 v[224:225], off
	v_mfma_f32_32x32x16_bf16 v[34:49], v[178:181], v[158:161], v[34:49]
	global_load_lds_dwordx4 v[224:225], off offset:1024
	v_mfma_f32_32x32x16_bf16 v[82:97], v[174:177], v[154:157], v[82:97]
	global_load_lds_dwordx4 v[224:225], off offset:2048
	v_mfma_f32_32x32x16_bf16 v[50:65], v[170:173], v[154:157], v[50:65]
	global_load_lds_dwordx4 v[224:225], off offset:3072
	v_mfma_f32_32x32x16_bf16 v[18:33], v[174:177], v[158:161], v[18:33]
	s_add_i32 s10, s29, 0x6000
	s_cmpk_lg_u32 s29, 0xc000
	s_cselect_b32 s29, s10, 0
	s_add_i32 s10, s28, 0x6000
	s_cmpk_lg_u32 s28, 0xc000
	s_cselect_b32 s28, s10, 0
	v_mfma_f32_32x32x16_bf16 v[2:17], v[170:173], v[158:161], v[2:17]
	s_add_i32 s11, s29, 16
	s_waitcnt vmcnt(6) lgkmcnt(0)
	s_barrier
	v_add_u32_e32 v158, s11, v219
	v_add_u32_e32 v170, s11, v218
	v_add_u32_e32 v158, v158, v0
	v_add_u32_e32 v170, v170, v0
	ds_read_b128 v[154:157], v158
	ds_read_b128 v[182:185], v170 offset:8192
	ds_read_b128 v[178:181], v170 offset:10240
	ds_read_b128 v[158:161], v158 offset:2048
	ds_read_b128 v[174:177], v170 offset:12288
	ds_read_b128 v[170:173], v170 offset:14336
	v_mfma_f32_32x32x16_bf16 v[114:129], v[162:165], v[138:141], v[114:129]
	v_mfma_f32_32x32x16_bf16 v[98:113], v[166:169], v[138:141], v[98:113]
	v_mfma_f32_32x32x16_bf16 v[66:81], v[162:165], v[142:145], v[66:81]
	v_mfma_f32_32x32x16_bf16 v[34:49], v[166:169], v[142:145], v[34:49]
	v_mfma_f32_32x32x16_bf16 v[82:97], v[146:149], v[138:141], v[82:97]
	v_mfma_f32_32x32x16_bf16 v[50:65], v[150:153], v[138:141], v[50:65]
	v_mfma_f32_32x32x16_bf16 v[18:33], v[146:149], v[142:145], v[18:33]
	v_mfma_f32_32x32x16_bf16 v[2:17], v[150:153], v[142:145], v[2:17]
	s_add_i32 s11, s29, 16
	s_add_i32 s10, s23, 1
	v_add_u32_e32 v142, s11, v219
	v_add_u32_e32 v150, s11, v218
	s_min_u32 s10, s10, 29
	v_add_u32_e32 v142, v142, v220
	v_add_u32_e32 v150, v150, v220
	s_lshl_b32 s70, s10, 6
	ds_read_b128 v[138:141], v142
	ds_read_b128 v[162:165], v150 offset:8192
	ds_read_b128 v[166:169], v150 offset:10240
	ds_read_b128 v[142:145], v142 offset:2048
	ds_read_b128 v[146:149], v150 offset:12288
	ds_read_b128 v[150:153], v150 offset:14336
	s_mul_i32 vcc_lo, s70, 0x12000
	s_add_i32 s10, s13, s28
	v_lshl_add_u64 v[222:223], v[192:193], 0, vcc
	s_mov_b32 m0, s10
	s_mul_i32 s100, s70, 0x900
	v_lshl_add_u64 v[224:225], v[194:195], 0, s[100:101]
	s_add_i32 s10, s22, s28
	s_waitcnt lgkmcnt(6)
	v_mfma_f32_32x32x16_bf16 v[114:129], v[182:185], v[154:157], v[114:129]
	global_load_lds_dwordx4 v[222:223], off
	v_mfma_f32_32x32x16_bf16 v[98:113], v[178:181], v[154:157], v[98:113]
	global_load_lds_dwordx4 v[222:223], off offset:1024
	s_add_i32 m0, s10, 0x2000
	v_mfma_f32_32x32x16_bf16 v[66:81], v[182:185], v[158:161], v[66:81]
	global_load_lds_dwordx4 v[224:225], off
	v_mfma_f32_32x32x16_bf16 v[34:49], v[178:181], v[158:161], v[34:49]
	global_load_lds_dwordx4 v[224:225], off offset:1024
	v_mfma_f32_32x32x16_bf16 v[82:97], v[174:177], v[154:157], v[82:97]
	global_load_lds_dwordx4 v[224:225], off offset:2048
	v_mfma_f32_32x32x16_bf16 v[50:65], v[170:173], v[154:157], v[50:65]
	global_load_lds_dwordx4 v[224:225], off offset:3072
	v_mfma_f32_32x32x16_bf16 v[18:33], v[174:177], v[158:161], v[18:33]
	s_add_i32 s10, s29, 0x6000
	s_cmpk_lg_u32 s29, 0xc000
	s_cselect_b32 s29, s10, 0
	s_add_i32 s10, s28, 0x6000
	s_cmpk_lg_u32 s28, 0xc000
	s_cselect_b32 s28, s10, 0
	v_mfma_f32_32x32x16_bf16 v[2:17], v[170:173], v[158:161], v[2:17]
	s_add_i32 s11, s29, 16
	s_waitcnt vmcnt(6) lgkmcnt(0)
	s_barrier
	v_add_u32_e32 v158, s11, v219
	v_add_u32_e32 v170, s11, v218
	v_add_u32_e32 v158, v158, v0
	v_add_u32_e32 v170, v170, v0
	ds_read_b128 v[154:157], v158
	ds_read_b128 v[182:185], v170 offset:8192
	ds_read_b128 v[178:181], v170 offset:10240
	ds_read_b128 v[158:161], v158 offset:2048
	ds_read_b128 v[174:177], v170 offset:12288
	ds_read_b128 v[170:173], v170 offset:14336
	v_mfma_f32_32x32x16_bf16 v[114:129], v[162:165], v[138:141], v[114:129]
	v_mfma_f32_32x32x16_bf16 v[98:113], v[166:169], v[138:141], v[98:113]
	v_mfma_f32_32x32x16_bf16 v[66:81], v[162:165], v[142:145], v[66:81]
	v_mfma_f32_32x32x16_bf16 v[34:49], v[166:169], v[142:145], v[34:49]
	v_mfma_f32_32x32x16_bf16 v[82:97], v[146:149], v[138:141], v[82:97]
	v_mfma_f32_32x32x16_bf16 v[50:65], v[150:153], v[138:141], v[50:65]
	v_mfma_f32_32x32x16_bf16 v[18:33], v[146:149], v[142:145], v[18:33]
	v_mfma_f32_32x32x16_bf16 v[2:17], v[150:153], v[142:145], v[2:17]
	s_add_i32 s23, s23, 2
	s_cmp_lg_u32 s23, 32
	s_cbranch_scc1 .LBB0_184
; DI unsigned pk2(float a, float b) { f32x2 v = {a, b}; bf2_t r = __builtin_convertvector(v, bf2_t); return __builtin_bit_cast(unsigned, r); }
;     ...
;   asm volatile("s_waitcnt vmcnt(0)" ::: "memory");
;   __builtin_amdgcn_s_barrier();
;   asm volatile("" ::: "memory");
;     ...
;   {
;     const int h = lane >> 5, cl = lane & 31;
; #pragma unroll
;     for (int i = 0; i < 2; ++i)
; #pragma unroll
;       for (int j = 0; j < 4; ++j)
; #pragma unroll
;         for (int g = 0; g < 4; ++g) {
;           u32x2 w; w.x = pk2(acc[i][j][4 * g], acc[i][j][4 * g + 1]); w.y = pk2(acc[i][j][4 * g + 2], acc[i][j][4 * g + 3]);
;           *(u32x2*)(smem + (wr * 64 + i * 32 + cl) * 528 + (wc * 128 + j * 32 + 8 * g + 4 * h) * 2) = w;
;         }
;   }
;   __syncthreads();
	s_waitcnt lgkmcnt(0)
	v_mul_lo_u32 v0, v197, s55
	v_add_u32_e32 v0, 16, v0
	s_nop 1
	v_cvt_pk_bf16_f32 v114, v114, v115
	v_cvt_pk_bf16_f32 v115, v116, v117
	v_lshlrev_b32_e32 v116, 3, v196
	s_lshl_b32 s10, s21, 1
	v_add3_u32 v0, v0, v116, s10
	v_cvt_pk_bf16_f32 v116, v118, v119
	v_cvt_pk_bf16_f32 v117, v120, v121
	v_cvt_pk_bf16_f32 v98, v98, v99
	v_cvt_pk_bf16_f32 v99, v100, v101
	v_cvt_pk_bf16_f32 v100, v102, v103
	v_cvt_pk_bf16_f32 v101, v104, v105
	v_cvt_pk_bf16_f32 v82, v82, v83
	v_cvt_pk_bf16_f32 v83, v84, v85
	v_cvt_pk_bf16_f32 v84, v86, v87
	v_cvt_pk_bf16_f32 v85, v88, v89
	v_cvt_pk_bf16_f32 v50, v50, v51
	v_cvt_pk_bf16_f32 v51, v52, v53
	v_cvt_pk_bf16_f32 v52, v54, v55
	v_cvt_pk_bf16_f32 v53, v56, v57
	s_waitcnt vmcnt(0)
	s_barrier
	ds_write2_b64 v0, v[114:115], v[116:117] offset1:2
	v_cvt_pk_bf16_f32 v114, v122, v123
	v_cvt_pk_bf16_f32 v115, v124, v125
	v_cvt_pk_bf16_f32 v116, v126, v127
	v_cvt_pk_bf16_f32 v117, v128, v129
	ds_write2_b64 v0, v[98:99], v[100:101] offset0:8 offset1:10
	v_cvt_pk_bf16_f32 v98, v106, v107
	v_cvt_pk_bf16_f32 v99, v108, v109
	v_cvt_pk_bf16_f32 v100, v110, v111
	v_cvt_pk_bf16_f32 v101, v112, v113
	ds_write2_b64 v0, v[82:83], v[84:85] offset0:16 offset1:18
	v_cvt_pk_bf16_f32 v82, v90, v91
	v_cvt_pk_bf16_f32 v83, v92, v93
	v_cvt_pk_bf16_f32 v84, v94, v95
	v_cvt_pk_bf16_f32 v85, v96, v97
	ds_write2_b64 v0, v[50:51], v[52:53] offset0:24 offset1:26
	v_cvt_pk_bf16_f32 v50, v58, v59
	v_cvt_pk_bf16_f32 v51, v60, v61
	v_cvt_pk_bf16_f32 v52, v62, v63
	v_cvt_pk_bf16_f32 v53, v64, v65
	ds_write2_b64 v0, v[114:115], v[116:117] offset0:4 offset1:6
	ds_write2_b64 v0, v[98:99], v[100:101] offset0:12 offset1:14
	ds_write2_b64 v0, v[82:83], v[84:85] offset0:20 offset1:22
	ds_write2_b64 v0, v[50:51], v[52:53] offset0:28 offset1:30
	v_cvt_pk_bf16_f32 v50, v66, v67
	v_cvt_pk_bf16_f32 v51, v68, v69
	v_cvt_pk_bf16_f32 v52, v70, v71
	v_cvt_pk_bf16_f32 v53, v72, v73
	v_add_u32_e32 v0, 0x4000, v0
	v_cvt_pk_bf16_f32 v34, v34, v35
	v_cvt_pk_bf16_f32 v35, v36, v37
	v_cvt_pk_bf16_f32 v36, v38, v39
	v_cvt_pk_bf16_f32 v37, v40, v41
	v_cvt_pk_bf16_f32 v18, v18, v19
	v_cvt_pk_bf16_f32 v19, v20, v21
	v_cvt_pk_bf16_f32 v20, v22, v23
	v_cvt_pk_bf16_f32 v21, v24, v25
	v_cvt_pk_bf16_f32 v2, v2, v3
	v_cvt_pk_bf16_f32 v3, v4, v5
	v_cvt_pk_bf16_f32 v4, v6, v7
	v_cvt_pk_bf16_f32 v5, v8, v9
	ds_write2_b64 v0, v[50:51], v[52:53] offset0:64 offset1:66
	v_cvt_pk_bf16_f32 v50, v74, v75
	v_cvt_pk_bf16_f32 v51, v76, v77
	v_cvt_pk_bf16_f32 v52, v78, v79
	v_cvt_pk_bf16_f32 v53, v80, v81
	ds_write2_b64 v0, v[34:35], v[36:37] offset0:72 offset1:74
	v_cvt_pk_bf16_f32 v34, v42, v43
	v_cvt_pk_bf16_f32 v35, v44, v45
	v_cvt_pk_bf16_f32 v36, v46, v47
	v_cvt_pk_bf16_f32 v37, v48, v49
	ds_write2_b64 v0, v[18:19], v[20:21] offset0:80 offset1:82
	v_cvt_pk_bf16_f32 v18, v26, v27
	v_cvt_pk_bf16_f32 v19, v28, v29
	v_cvt_pk_bf16_f32 v20, v30, v31
	v_cvt_pk_bf16_f32 v21, v32, v33
	ds_write2_b64 v0, v[2:3], v[4:5] offset0:88 offset1:90
	v_cvt_pk_bf16_f32 v2, v10, v11
	v_cvt_pk_bf16_f32 v3, v12, v13
	v_cvt_pk_bf16_f32 v4, v14, v15
	v_cvt_pk_bf16_f32 v5, v16, v17
	s_lshl_b64 s[14:15], s[14:15], 1
	ds_write2_b64 v0, v[50:51], v[52:53] offset0:68 offset1:70
	ds_write2_b64 v0, v[34:35], v[36:37] offset0:76 offset1:78
	ds_write2_b64 v0, v[18:19], v[20:21] offset0:84 offset1:86
	ds_write2_b64 v0, v[2:3], v[4:5] offset0:92 offset1:94
	s_waitcnt vmcnt(0) lgkmcnt(0)
	s_barrier
; #define GAS __attribute__((address_space(1)))
;     ...
;   if (EPI == 0) {
; #pragma unroll
;     for (int i = 0; i < 16; ++i) {
;       const int id = tid2 + 256 * i, r = id >> 5, c8 = (id & 31) * 8;
;       const u32x4 v = *(const u32x4*)(smem + r * 528 + c8 * 2);
;       *(GAS u32x4*)(ea.out + (size_t)(m0 + r) * ea.ldo + n0 + c8) = v;
;     }
; __global__ void __launch_bounds__(256, 2) fwd_kernel(Params p) {
;     ...
;       for (int j = slot; j < 576 * 9 / NX; j += nslot) { int mt, nt; gemm_tile_of(j, xcd, NX, 9, 9, mt, nt);
;         gemm_tile256<0>(H, 1024, WT_IN0, 1024, mt, nt, smem, tid, ea); }
	s_add_u32 s14, s16, s14
	v_lshlrev_b32_e32 v0, 4, v189
	v_and_b32_e32 v0, 0x1f0, v0
	s_addc_u32 s15, s17, s15
	v_add_u32_e32 v10, 16, v0
	v_lshl_add_u64 v[12:13], s[14:15], 0, v[0:1]
	v_ashrrev_i32_e32 v0, 5, v189
	v_mad_u64_u32 v[2:3], s[14:15], v0, s55, v[10:11]
	v_add_u32_e32 v0, s12, v0
	v_mad_i64_i32 v[14:15], s[14:15], v0, s35, v[12:13]
	v_add_u32_e32 v0, 0x100, v189
	ds_read_b128 v[2:5], v2
	v_ashrrev_i32_e32 v0, 5, v0
	v_mad_u64_u32 v[6:7], s[14:15], v0, s55, v[10:11]
	ds_read_b128 v[6:9], v6
	v_add_u32_e32 v0, s12, v0
	s_waitcnt lgkmcnt(1)
	global_store_dwordx4 v[14:15], v[2:5], off
	v_readlane_b32 s10, v252, 12
	s_add_i32 s20, s20, s10
	v_mad_i64_i32 v[2:3], s[14:15], v0, s35, v[12:13]
	v_add_u32_e32 v0, 0x200, v189
	v_ashrrev_i32_e32 v0, 5, v0
	s_waitcnt lgkmcnt(0)
	global_store_dwordx4 v[2:3], v[6:9], off
	v_mad_u64_u32 v[2:3], s[14:15], v0, s55, v[10:11]
	v_add_u32_e32 v0, s12, v0
	v_mad_i64_i32 v[14:15], s[14:15], v0, s35, v[12:13]
	v_add_u32_e32 v0, 0x300, v189
	ds_read_b128 v[2:5], v2
	v_ashrrev_i32_e32 v0, 5, v0
	v_mad_u64_u32 v[6:7], s[14:15], v0, s55, v[10:11]
	ds_read_b128 v[6:9], v6
	v_add_u32_e32 v0, s12, v0
	s_waitcnt lgkmcnt(1)
	global_store_dwordx4 v[14:15], v[2:5], off
	s_cmp_ge_i32 s20, s45
	s_nop 0
	v_mad_i64_i32 v[2:3], s[14:15], v0, s35, v[12:13]
	v_add_u32_e32 v0, 0x400, v189
	v_ashrrev_i32_e32 v0, 5, v0
	s_waitcnt lgkmcnt(0)
	global_store_dwordx4 v[2:3], v[6:9], off
	v_mad_u64_u32 v[2:3], s[14:15], v0, s55, v[10:11]
	v_add_u32_e32 v0, s12, v0
	v_mad_i64_i32 v[14:15], s[14:15], v0, s35, v[12:13]
	v_add_u32_e32 v0, 0x500, v189
	ds_read_b128 v[2:5], v2
	v_ashrrev_i32_e32 v0, 5, v0
	v_mad_u64_u32 v[6:7], s[14:15], v0, s55, v[10:11]
	ds_read_b128 v[6:9], v6
	v_add_u32_e32 v0, s12, v0
	s_waitcnt lgkmcnt(1)
	global_store_dwordx4 v[14:15], v[2:5], off
	s_nop 1
	v_mad_i64_i32 v[2:3], s[14:15], v0, s35, v[12:13]
	v_add_u32_e32 v0, 0x600, v189
	v_ashrrev_i32_e32 v0, 5, v0
	s_waitcnt lgkmcnt(0)
	global_store_dwordx4 v[2:3], v[6:9], off
	v_mad_u64_u32 v[2:3], s[14:15], v0, s55, v[10:11]
	v_add_u32_e32 v0, s12, v0
	v_mad_i64_i32 v[14:15], s[14:15], v0, s35, v[12:13]
	v_add_u32_e32 v0, 0x700, v189
	ds_read_b128 v[2:5], v2
	v_ashrrev_i32_e32 v0, 5, v0
	v_mad_u64_u32 v[6:7], s[14:15], v0, s55, v[10:11]
	ds_read_b128 v[6:9], v6
	v_add_u32_e32 v0, s12, v0
	s_waitcnt lgkmcnt(1)
	global_store_dwordx4 v[14:15], v[2:5], off
	s_nop 1
	v_mad_i64_i32 v[2:3], s[14:15], v0, s35, v[12:13]
	v_add_u32_e32 v0, 0x800, v189
	v_ashrrev_i32_e32 v0, 5, v0
	s_waitcnt lgkmcnt(0)
	global_store_dwordx4 v[2:3], v[6:9], off
	v_mad_u64_u32 v[2:3], s[14:15], v0, s55, v[10:11]
	v_add_u32_e32 v0, s12, v0
	v_mad_i64_i32 v[14:15], s[14:15], v0, s35, v[12:13]
	v_add_u32_e32 v0, 0x900, v189
	ds_read_b128 v[2:5], v2
	v_ashrrev_i32_e32 v0, 5, v0
	v_mad_u64_u32 v[6:7], s[14:15], v0, s55, v[10:11]
	ds_read_b128 v[6:9], v6
	v_add_u32_e32 v0, s12, v0
	s_waitcnt lgkmcnt(1)
	global_store_dwordx4 v[14:15], v[2:5], off
	s_nop 1
	v_mad_i64_i32 v[2:3], s[14:15], v0, s35, v[12:13]
	v_add_u32_e32 v0, 0xa00, v189
	v_ashrrev_i32_e32 v0, 5, v0
	s_waitcnt lgkmcnt(0)
	global_store_dwordx4 v[2:3], v[6:9], off
	v_mad_u64_u32 v[2:3], s[14:15], v0, s55, v[10:11]
	v_add_u32_e32 v0, s12, v0
	v_mad_i64_i32 v[14:15], s[14:15], v0, s35, v[12:13]
	v_add_u32_e32 v0, 0xb00, v189
	ds_read_b128 v[2:5], v2
	v_ashrrev_i32_e32 v0, 5, v0
	v_mad_u64_u32 v[6:7], s[14:15], v0, s55, v[10:11]
	ds_read_b128 v[6:9], v6
	v_add_u32_e32 v0, s12, v0
	s_waitcnt lgkmcnt(1)
	global_store_dwordx4 v[14:15], v[2:5], off
	s_nop 1
	v_mad_i64_i32 v[2:3], s[14:15], v0, s35, v[12:13]
	v_add_u32_e32 v0, 0xc00, v189
	v_ashrrev_i32_e32 v0, 5, v0
	s_waitcnt lgkmcnt(0)
	global_store_dwordx4 v[2:3], v[6:9], off
	v_mad_u64_u32 v[2:3], s[14:15], v0, s55, v[10:11]
	v_add_u32_e32 v0, s12, v0
	v_mad_i64_i32 v[14:15], s[14:15], v0, s35, v[12:13]
	v_add_u32_e32 v0, 0xd00, v189
	ds_read_b128 v[2:5], v2
	v_ashrrev_i32_e32 v0, 5, v0
	v_mad_u64_u32 v[6:7], s[14:15], v0, s55, v[10:11]
	ds_read_b128 v[6:9], v6
	v_add_u32_e32 v0, s12, v0
	s_waitcnt lgkmcnt(1)
	global_store_dwordx4 v[14:15], v[2:5], off
	s_nop 1
	v_mad_i64_i32 v[2:3], s[14:15], v0, s35, v[12:13]
	v_add_u32_e32 v0, 0xe00, v189
	v_ashrrev_i32_e32 v0, 5, v0
	s_waitcnt lgkmcnt(0)
	global_store_dwordx4 v[2:3], v[6:9], off
	v_mad_u64_u32 v[2:3], s[14:15], v0, s55, v[10:11]
	v_add_u32_e32 v0, s12, v0
	v_mad_i64_i32 v[14:15], s[14:15], v0, s35, v[12:13]
	v_add_u32_e32 v0, 0xf00, v189
	v_ashrrev_i32_e32 v0, 5, v0
	ds_read_b128 v[2:5], v2
	v_mad_u64_u32 v[6:7], s[14:15], v0, s55, v[10:11]
	ds_read_b128 v[6:9], v6
	v_add_u32_e32 v0, s12, v0
	s_waitcnt lgkmcnt(1)
	global_store_dwordx4 v[14:15], v[2:5], off
	s_nop 1
	v_mad_i64_i32 v[2:3], s[12:13], v0, s35, v[12:13]
	s_waitcnt lgkmcnt(0)
	global_store_dwordx4 v[2:3], v[6:9], off
	s_barrier
	s_cbranch_scc0 .LBB0_183
	v_mov_b64_e32 v[6:7], v[130:131]
	v_mov_b64_e32 v[2:3], v[134:135]
	v_mov_b32_e32 v31, v214
	v_mov_b32_e32 v30, v215
	v_mov_b32_e32 v29, v216
	v_mov_b32_e32 v28, v217
	v_mov_b64_e32 v[8:9], v[132:133]
	v_mov_b64_e32 v[4:5], v[136:137]
	v_readlane_b32 s44, v250, 17

; #define GAS __attribute__((address_space(1)))
; DI unsigned pk2(float a, float b) { f32x2 v = {a, b}; bf2_t r = __builtin_convertvector(v, bf2_t); return __builtin_bit_cast(unsigned, r); }
; DI float bflo(unsigned w) { return __uint_as_float(w << 16); }
; DI float bfhi(unsigned w) { return __uint_as_float(w & 0xffff0000u); }
; __global__ void __launch_bounds__(256, 2) fwd_kernel(Params p) {
;     ...
;       const float* hw = pp->in[21]; const float* hb = pp->in[22];
;       float* us = (float*)smem;
;       for (int item = bid; item < 32 * 32 * 24; item += G) {
;         const int ct = item % 24, tt = (item / 24) & 31, b = item / 768;
;         const int t0 = tt * 64;
;         __syncthreads();
; #pragma unroll
;         for (int i = 0; i < 3; ++i) {
;           const int id = tid + 256 * i;
;           if (id < 528) {
;             const int rr = id >> 3, ch8 = (id & 7) * 8, t = t0 - 1 + rr;
;             u32x4 v = {0u, 0u, 0u, 0u};
;             if (t >= 0 && t < 2048) v = *(const GAS u32x4*)(P + (size_t)(b * 2048 + t) * PLD + 768 + ct * 64 + ch8);
;             float* d = us + rr * 65 + ch8;
;             d[0] = bflo(v.x); d[1] = bfhi(v.x); d[2] = bflo(v.y); d[3] = bfhi(v.y); d[4] = bflo(v.z); d[5] = bfhi(v.z); d[6] = bflo(v.w); d[7] = bfhi(v.w);
;           }
;         }
;         __syncthreads();
; #pragma unroll
;         for (int k = 0; k < 2; ++k) {
;           const int id = tid + 256 * k, ch = id >> 3, t8 = id & 7, cgl = ct * 64 + ch;
;           const float w0 = hw[cgl], w1 = hw[1536 + cgl], w2 = hw[3072 + cgl], bb = hb[cgl];
;           float v[8];
; #pragma unroll
;           for (int e = 0; e < 8; ++e) { const int tl = t8 * 8 + e; v[e] = w0 * us[tl * 65 + ch] + w1 * us[(tl + 1) * 65 + ch] + w2 * us[(tl + 2) * 65 + ch] + bb; }
;           u32x4 w; w.x = pk2(v[0], v[1]); w.y = pk2(v[2], v[3]); w.z = pk2(v[4], v[5]); w.w = pk2(v[6], v[7]);
;           *(GAS u32x4*)(HT + (size_t)cgl * 65536 + b * 2048 + t0 + t8 * 8) = w;
;         }
.LBB0_207:
	v_readlane_b32 s10, v252, 35
	v_readlane_b32 s11, v252, 36
	s_andn2_b64 vcc, exec, s[10:11]
	s_cbranch_vccnz .LBB0_222
	v_lshlrev_b32_e32 v0, 3, v188
	s_load_dwordx4 s[56:59], s[8:9], 0xa8
	v_and_b32_e32 v0, 56, v0
	v_readlane_b32 s10, v250, 18
	v_add_u32_e32 v3, 0x100, v188
	v_readlane_b32 s11, v250, 19
	s_add_u32 s46, s10, 0x22d60600
	v_ashrrev_i32_e32 v7, 3, v3
	v_mul_u32_u24_e32 v4, 0x41, v0
	v_ashrrev_i32_e32 v9, 3, v188
	v_add_u32_e32 v10, 0x200, v188
	s_addc_u32 s47, s11, 0
	v_lshlrev_b32_e32 v3, 2, v7
	v_lshlrev_b32_e32 v4, 2, v4
	s_movk_i32 s11, 0x104
	v_ashrrev_i32_e32 v10, 3, v10
	v_lshlrev_b32_e32 v12, 2, v9
	v_lshl_add_u32 v2, v0, 2, 16
	v_add3_u32 v8, 16, v3, v4
	v_mul_lo_u32 v5, v9, s11
	s_movk_i32 s10, 0x110
	v_mul_lo_u32 v6, v7, s11
	v_mul_lo_u32 v16, v10, s11
	v_add3_u32 v11, 16, v12, v4
	v_add_u32_e32 v4, 16, v4
	v_cmp_gt_i32_e64 s[40:41], s55, v188
	v_cmp_gt_i32_e64 s[42:43], s10, v188
	v_cmp_gt_i32_e64 s[44:45], 16, v188
	v_add_u32_e32 v12, v4, v12
	v_add_u32_e32 v13, v4, v3
	v_add_u32_e32 v14, v2, v5
	v_add_u32_e32 v15, v2, v6
	v_add_u32_e32 v16, v2, v16
	v_lshlrev_b32_e32 v0, 1, v0
	v_readlane_b32 s60, v250, 2
	v_readlane_b32 s61, v252, 0
	s_branch .LBB0_211
.LBB0_210:
	s_or_b64 exec, exec, s[22:23]
	s_ashr_i32 s21, s20, 31
	s_lshl_b64 s[10:11], s[20:21], 1
	s_add_u32 s10, s46, s10
	s_addc_u32 s11, s47, s11
	s_lshl_b32 s19, s62, 1
	v_add_u32_e32 v4, s18, v9
	s_add_u32 s10, s10, s19
	v_ashrrev_i32_e32 v5, 31, v4
	s_addc_u32 s11, s11, 0
	v_lshlrev_b64 v[18:19], 2, v[4:5]
	v_lshl_add_u64 v[2:3], s[10:11], 0, v[0:1]
	v_lshl_add_u64 v[20:21], s[56:57], 0, v[18:19]
	s_movk_i32 s10, 0x1000
	v_add_co_u32_e32 v22, vcc, s10, v20
	s_waitcnt lgkmcnt(0)
	s_nop 0
	v_addc_co_u32_e32 v23, vcc, 0, v21, vcc
	s_barrier
	global_load_dword v22, v[22:23], off offset:2048
	s_movk_i32 s11, 0x3000
	global_load_dword v6, v[20:21], off
	v_add_co_u32_e32 v20, vcc, s11, v20
	v_lshl_add_u64 v[18:19], s[58:59], 0, v[18:19]
	s_nop 0
	v_addc_co_u32_e32 v21, vcc, 0, v21, vcc
	global_load_dword v20, v[20:21], off
	v_add_u32_e32 v17, 0x200, v12
	global_load_dword v18, v[18:19], off
	ds_read_b32 v24, v11
	ds_read2_b32 v[26:27], v12 offset0:65 offset1:130
	ds_read2_b32 v[28:29], v17 offset0:67 offset1:132
	v_add_u32_e32 v17, 0x400, v12
	v_lshlrev_b64 v[4:5], 17, v[4:5]
	v_lshl_add_u64 v[4:5], v[2:3], 0, v[4:5]
	s_waitcnt lgkmcnt(0)
	v_mov_b32_e32 v25, v26
	s_waitcnt vmcnt(0)
	v_pk_mul_f32 v[30:31], v[22:23], v[26:27] op_sel_hi:[0,1]
	v_mov_b32_e32 v26, v27
	v_pk_fma_f32 v[24:25], v[6:7], v[24:25], v[30:31] op_sel_hi:[0,1,1]
	ds_read2_b32 v[30:31], v17 offset0:69 offset1:134
	v_mov_b32_e32 v27, v28
	v_pk_mul_f32 v[32:33], v[22:23], v[28:29] op_sel_hi:[0,1]
	v_add_u32_e32 v17, 0x600, v12
	v_mov_b32_e32 v28, v29
	v_pk_fma_f32 v[24:25], v[20:21], v[26:27], v[24:25] op_sel_hi:[0,1,1]
	v_pk_fma_f32 v[26:27], v[6:7], v[26:27], v[32:33] op_sel_hi:[0,1,1]
	ds_read2_b32 v[32:33], v17 offset0:71 offset1:136
	s_waitcnt lgkmcnt(1)
	v_pk_mul_f32 v[34:35], v[22:23], v[30:31] op_sel_hi:[0,1]
	ds_read_b32 v23, v12 offset:2340
	v_mov_b32_e32 v29, v30
	v_pk_fma_f32 v[26:27], v[20:21], v[28:29], v[26:27] op_sel_hi:[0,1,1]
	v_pk_fma_f32 v[28:29], v[6:7], v[28:29], v[34:35] op_sel_hi:[0,1,1]
	v_mov_b32_e32 v30, v31
	s_waitcnt lgkmcnt(1)
	v_mov_b32_e32 v31, v32
	s_waitcnt lgkmcnt(0)
	v_pk_mul_f32 v[34:35], v[22:23], v[32:33] op_sel_hi:[0,1]
	v_pk_fma_f32 v[28:29], v[20:21], v[30:31], v[28:29] op_sel_hi:[0,1,1]
	v_pk_fma_f32 v[30:31], v[6:7], v[30:31], v[34:35] op_sel_hi:[0,1,1]
	v_mov_b32_e32 v22, v33
	v_pk_fma_f32 v[20:21], v[20:21], v[22:23], v[30:31] op_sel_hi:[0,1,1]
	v_pk_add_f32 v[24:25], v[18:19], v[24:25] op_sel_hi:[0,1]
	v_pk_add_f32 v[26:27], v[18:19], v[26:27] op_sel_hi:[0,1]
	v_pk_add_f32 v[28:29], v[18:19], v[28:29] op_sel_hi:[0,1]
	v_pk_add_f32 v[22:23], v[18:19], v[20:21] op_sel_hi:[0,1]
	v_cvt_pk_bf16_f32 v18, v24, v25
	v_cvt_pk_bf16_f32 v19, v26, v27
	v_cvt_pk_bf16_f32 v20, v28, v29
	v_cvt_pk_bf16_f32 v21, v22, v23
	global_store_dwordx4 v[4:5], v[18:21], off
	v_add_u32_e32 v4, s18, v7
	v_ashrrev_i32_e32 v5, 31, v4
	v_lshlrev_b64 v[18:19], 2, v[4:5]
	v_lshl_add_u64 v[20:21], s[56:57], 0, v[18:19]
	v_add_co_u32_e32 v22, vcc, s10, v20
	global_load_dword v6, v[20:21], off
	s_nop 0
	v_addc_co_u32_e32 v23, vcc, 0, v21, vcc
	global_load_dword v22, v[22:23], off offset:2048
	v_add_co_u32_e32 v20, vcc, s11, v20
	v_lshl_add_u64 v[18:19], s[58:59], 0, v[18:19]
	s_nop 0
	v_addc_co_u32_e32 v21, vcc, 0, v21, vcc
	global_load_dword v20, v[20:21], off
	v_add_u32_e32 v17, 0x200, v13
	global_load_dword v18, v[18:19], off
	ds_read_b32 v24, v8
	ds_read2_b32 v[26:27], v13 offset0:65 offset1:130
	ds_read2_b32 v[28:29], v17 offset0:67 offset1:132
	v_add_u32_e32 v17, 0x400, v13
	v_readlane_b32 s10, v250, 17
	s_add_i32 s61, s61, s10
	s_waitcnt lgkmcnt(1)
	v_mov_b32_e32 v25, v26
	v_readlane_b32 s10, v250, 3
	v_lshlrev_b64 v[4:5], 17, v[4:5]
	s_add_i32 s60, s60, s10
	v_lshl_add_u64 v[2:3], v[2:3], 0, v[4:5]
	s_cmpk_gt_i32 s61, 0x5fff
	s_waitcnt vmcnt(2)
	v_pk_mul_f32 v[30:31], v[22:23], v[26:27] op_sel_hi:[0,1]
	v_pk_fma_f32 v[24:25], v[6:7], v[24:25], v[30:31] op_sel_hi:[0,1,1]
	ds_read2_b32 v[30:31], v17 offset0:69 offset1:134
	v_mov_b32_e32 v26, v27
	s_waitcnt lgkmcnt(1)
	v_mov_b32_e32 v27, v28
	v_pk_mul_f32 v[32:33], v[22:23], v[28:29] op_sel_hi:[0,1]
	v_add_u32_e32 v17, 0x600, v13
	s_waitcnt vmcnt(1)
	v_pk_fma_f32 v[24:25], v[20:21], v[26:27], v[24:25] op_sel_hi:[0,1,1]
	v_pk_fma_f32 v[26:27], v[6:7], v[26:27], v[32:33] op_sel_hi:[0,1,1]
	ds_read2_b32 v[32:33], v17 offset0:71 offset1:136
	s_waitcnt lgkmcnt(1)
	v_pk_mul_f32 v[34:35], v[22:23], v[30:31] op_sel_hi:[0,1]
	ds_read_b32 v23, v13 offset:2340
	v_mov_b32_e32 v28, v29
	v_mov_b32_e32 v29, v30
	v_pk_fma_f32 v[26:27], v[20:21], v[28:29], v[26:27] op_sel_hi:[0,1,1]
	v_pk_fma_f32 v[28:29], v[6:7], v[28:29], v[34:35] op_sel_hi:[0,1,1]
	v_mov_b32_e32 v30, v31
	s_waitcnt lgkmcnt(1)
	v_mov_b32_e32 v31, v32
	s_waitcnt lgkmcnt(0)
	v_pk_mul_f32 v[34:35], v[22:23], v[32:33] op_sel_hi:[0,1]
	v_pk_fma_f32 v[28:29], v[20:21], v[30:31], v[28:29] op_sel_hi:[0,1,1]
	v_pk_fma_f32 v[30:31], v[6:7], v[30:31], v[34:35] op_sel_hi:[0,1,1]
	v_mov_b32_e32 v22, v33
	v_pk_fma_f32 v[20:21], v[20:21], v[22:23], v[30:31] op_sel_hi:[0,1,1]
	s_waitcnt vmcnt(0)
	v_pk_add_f32 v[24:25], v[18:19], v[24:25] op_sel_hi:[0,1]
	v_pk_add_f32 v[26:27], v[18:19], v[26:27] op_sel_hi:[0,1]
	v_pk_add_f32 v[28:29], v[18:19], v[28:29] op_sel_hi:[0,1]
	v_pk_add_f32 v[22:23], v[18:19], v[20:21] op_sel_hi:[0,1]
	v_cvt_pk_bf16_f32 v18, v24, v25
	v_cvt_pk_bf16_f32 v19, v26, v27
	v_cvt_pk_bf16_f32 v20, v28, v29
	v_cvt_pk_bf16_f32 v21, v22, v23
	global_store_dwordx4 v[2:3], v[18:21], off
	s_cbranch_scc1 .LBB0_222
; #define GAS __attribute__((address_space(1)))
; DI float bflo(unsigned w) { return __uint_as_float(w << 16); }
; DI float bfhi(unsigned w) { return __uint_as_float(w & 0xffff0000u); }
; __global__ void __launch_bounds__(256, 2) fwd_kernel(Params p) {
;     ...
;       for (int item = bid; item < 32 * 32 * 24; item += G) {
;         const int ct = item % 24, tt = (item / 24) & 31, b = item / 768;
;         const int t0 = tt * 64;
;         __syncthreads();
; #pragma unroll
;         for (int i = 0; i < 3; ++i) {
;           const int id = tid + 256 * i;
;           if (id < 528) {
;             const int rr = id >> 3, ch8 = (id & 7) * 8, t = t0 - 1 + rr;
;             u32x4 v = {0u, 0u, 0u, 0u};
;             if (t >= 0 && t < 2048) v = *(const GAS u32x4*)(P + (size_t)(b * 2048 + t) * PLD + 768 + ct * 64 + ch8);
;             float* d = us + rr * 65 + ch8;
;             d[0] = bflo(v.x); d[1] = bfhi(v.x); d[2] = bflo(v.y); d[3] = bfhi(v.y); d[4] = bflo(v.z); d[5] = bfhi(v.z); d[6] = bflo(v.w); d[7] = bfhi(v.w);
;           }
;         }
;         __syncthreads();
.LBB0_211:
	s_mul_hi_i32 s10, s61, 0x2aaaaaab
	s_ashr_i32 s11, s10, 2
	s_lshr_b32 s18, s10, 31
	s_add_i32 s11, s11, s18
	s_lshr_b32 s10, s10, 7
	s_add_i32 s10, s10, s18
	s_lshl_b32 s18, s11, 6
	s_mulk_i32 s11, 0xfa00
	s_and_b32 s62, s18, 0x7c0
	s_add_i32 s18, s60, s11
	s_add_i32 s21, s62, -1
	s_lshl_b32 s20, s10, 11
	s_ashr_i32 s19, s18, 31
	s_waitcnt lgkmcnt(0)
	s_barrier
	v_add_u32_e32 v6, s21, v9
	s_movk_i32 s10, 0x800
	v_cmp_gt_u32_e32 vcc, s10, v6
	v_mov_b32_e32 v2, 0
	v_mov_b32_e32 v3, 0
	v_mov_b32_e32 v4, 0
	v_mov_b32_e32 v5, 0
	s_and_b64 s[28:29], vcc, s[40:41]
	s_and_saveexec_b64 s[22:23], s[28:29]
	s_cbranch_execz .Lmy14_l1
	v_readlane_b32 s10, v250, 18
	v_readlane_b32 s11, v250, 19
	v_or_b32_e32 v46, s20, v6
	s_nop 0
	v_mov_b64_e32 v[44:45], s[10:11]
	v_mad_i64_i32 v[44:45], s[10:11], v46, s35, v[44:45]
	v_lshl_add_u64 v[44:45], s[18:19], 1, v[44:45]
	v_lshl_add_u64 v[44:45], v[44:45], 0, v[0:1]
	v_add_co_u32_e32 v44, vcc, 0xe960000, v44
	s_nop 1
	v_addc_co_u32_e32 v45, vcc, 0, v45, vcc
	global_load_dwordx4 v[2:5], v[44:45], off offset:3072
.Lmy14_l1:
	s_or_b64 exec, exec, s[22:23]
	v_add_u32_e32 v6, s21, v7
	s_movk_i32 s10, 0x800
	v_cmp_gt_u32_e32 vcc, s10, v6
	v_mov_b32_e32 v36, 0
	v_mov_b32_e32 v37, 0
	v_mov_b32_e32 v38, 0
	v_mov_b32_e32 v39, 0
	s_and_b64 s[28:29], vcc, s[42:43]
	s_and_saveexec_b64 s[22:23], s[28:29]
	s_cbranch_execz .Lmy14_l2
	v_readlane_b32 s10, v250, 18
	v_readlane_b32 s11, v250, 19
	v_or_b32_e32 v46, s20, v6
	s_nop 0
	v_mov_b64_e32 v[44:45], s[10:11]
	v_mad_i64_i32 v[44:45], s[10:11], v46, s35, v[44:45]
	v_lshl_add_u64 v[44:45], s[18:19], 1, v[44:45]
	v_lshl_add_u64 v[44:45], v[44:45], 0, v[0:1]
	v_add_co_u32_e32 v44, vcc, 0xe960000, v44
	s_nop 1
	v_addc_co_u32_e32 v45, vcc, 0, v45, vcc
	global_load_dwordx4 v[36:39], v[44:45], off offset:3072
.Lmy14_l2:
	s_or_b64 exec, exec, s[22:23]
	v_add_u32_e32 v6, s21, v10
	s_movk_i32 s10, 0x800
	v_cmp_gt_u32_e32 vcc, s10, v6
	v_mov_b32_e32 v40, 0
	v_mov_b32_e32 v41, 0
	v_mov_b32_e32 v42, 0
	v_mov_b32_e32 v43, 0
	s_and_b64 s[28:29], vcc, s[44:45]
	s_and_saveexec_b64 s[22:23], s[28:29]
	s_cbranch_execz .Lmy14_l3
	v_readlane_b32 s10, v250, 18
	v_readlane_b32 s11, v250, 19
	v_or_b32_e32 v46, s20, v6
	s_nop 0
	v_mov_b64_e32 v[44:45], s[10:11]
	v_mad_i64_i32 v[44:45], s[10:11], v46, s35, v[44:45]
	v_lshl_add_u64 v[44:45], s[18:19], 1, v[44:45]
	v_lshl_add_u64 v[44:45], v[44:45], 0, v[0:1]
	v_add_co_u32_e32 v44, vcc, 0xe960000, v44
	s_nop 1
	v_addc_co_u32_e32 v45, vcc, 0, v45, vcc
	global_load_dwordx4 v[40:43], v[44:45], off offset:3072
.Lmy14_l3:
	s_or_b64 exec, exec, s[22:23]
	s_waitcnt vmcnt(0)
	s_and_saveexec_b64 s[22:23], s[40:41]
	v_lshlrev_b32_e32 v46, 16, v2
	v_and_b32_e32 v47, 0xffff0000, v2
	ds_write2_b32 v14, v46, v47 offset0:0 offset1:1
	v_lshlrev_b32_e32 v46, 16, v3
	v_and_b32_e32 v47, 0xffff0000, v3
	ds_write2_b32 v14, v46, v47 offset0:2 offset1:3
	v_lshlrev_b32_e32 v46, 16, v4
	v_and_b32_e32 v47, 0xffff0000, v4
	ds_write2_b32 v14, v46, v47 offset0:4 offset1:5
	v_lshlrev_b32_e32 v46, 16, v5
	v_and_b32_e32 v47, 0xffff0000, v5
	ds_write2_b32 v14, v46, v47 offset0:6 offset1:7
	s_or_b64 exec, exec, s[22:23]
	s_and_saveexec_b64 s[22:23], s[42:43]
	v_lshlrev_b32_e32 v46, 16, v36
	v_and_b32_e32 v47, 0xffff0000, v36
	ds_write2_b32 v15, v46, v47 offset0:0 offset1:1
	v_lshlrev_b32_e32 v46, 16, v37
	v_and_b32_e32 v47, 0xffff0000, v37
	ds_write2_b32 v15, v46, v47 offset0:2 offset1:3
	v_lshlrev_b32_e32 v46, 16, v38
	v_and_b32_e32 v47, 0xffff0000, v38
	ds_write2_b32 v15, v46, v47 offset0:4 offset1:5
	v_lshlrev_b32_e32 v46, 16, v39
	v_and_b32_e32 v47, 0xffff0000, v39
	ds_write2_b32 v15, v46, v47 offset0:6 offset1:7
	s_or_b64 exec, exec, s[22:23]
	s_and_saveexec_b64 s[22:23], s[44:45]
	v_lshlrev_b32_e32 v46, 16, v40
	v_and_b32_e32 v47, 0xffff0000, v40
	ds_write2_b32 v16, v46, v47 offset0:0 offset1:1
	v_lshlrev_b32_e32 v46, 16, v41
	v_and_b32_e32 v47, 0xffff0000, v41
	ds_write2_b32 v16, v46, v47 offset0:2 offset1:3
	v_lshlrev_b32_e32 v46, 16, v42
	v_and_b32_e32 v47, 0xffff0000, v42
	ds_write2_b32 v16, v46, v47 offset0:4 offset1:5
	v_lshlrev_b32_e32 v46, 16, v43
	v_and_b32_e32 v47, 0xffff0000, v43
	ds_write2_b32 v16, v46, v47 offset0:6 offset1:7
	s_or_b64 exec, exec, s[22:23]
	s_branch .LBB0_210

; #define LAS __attribute__((address_space(3)))
;     ...
;   const int lane = tid & 63, wid = __builtin_amdgcn_readfirstlane(tid >> 6), wr = wid >> 1, wc = wid & 1;
;   const int m0 = mt * 128, n0 = nt * 256;
;   const int r = lane & 31, h = lane >> 5, key = (r >> 2) & 3;
;   constexpr int STG = 24576;
;   const int rowl = lane >> 2, cch = (lane & 3) ^ ((lane >> 4) & 3);
;   const unsigned voffA = (unsigned)(rowl * lda * 2 + cch * 16), voffB = (unsigned)(rowl * K * 2 + cch * 16);
;   const char* Abase = (const char*)(A + (size_t)m0 * lda) + (size_t)(wid * 2) * 32 * lda;
;   const char* Bbase = (const char*)(Bt + (size_t)n0 * K) + (size_t)(wid * 4) * 32 * K;
;   const size_t ablk = (size_t)32 * lda, bblk = (size_t)32 * K;
;   LAS char* lds = (LAS char*)smem;
;   LAS char* ldsA = lds + (wid * 2) * 1024;
;   LAS char* ldsB = lds + 8192 + (wid * 4) * 1024;
;     ...
;   const int x0 = ((0 + h) ^ key) * 16, x1 = ((2 + h) ^ key) * 16;
;   const int a_rd = (wr * 64 + r) * 64, b_rd = 8192 + (wc * 128 + r) * 64;
;   f32x16 acc[2][4];
; #pragma unroll
;   for (int i = 0; i < 2; ++i)
; #pragma unroll
;     for (int j = 0; j < 4; ++j)
; #pragma unroll
;       for (int e = 0; e < 16; ++e) acc[i][j][e] = 0.f;
;   const int nk = K >> 5;
;   DMA_STEP_(0, 0);
;   DMA_STEP_(1, STG);
;   asm volatile("s_waitcnt vmcnt(6)" ::: "memory");
;   __builtin_amdgcn_s_barrier();
;   asm volatile("" ::: "memory");
;   int s0 = 0, s2 = 2 * STG;
.LBB0_234:
	v_mov_b32_e32 v189, v188
	s_lshl_b32 s12, s23, 7
	v_readfirstlane_b32 s42, v189
	s_ashr_i32 s44, s42, 6
	s_lshl_b32 s28, s44, 2
	s_ashr_i32 s29, s28, 31
	s_lshl_b32 s23, s44, 12
	s_lshl_b64 s[40:41], s[28:29], 10
	s_add_i32 s28, s23, 16
	s_ashr_i32 s23, s42, 1
	v_and_b32_e32 v0, 31, v189
	s_andn2_b32 s23, s23, 63
	v_lshlrev_b32_e32 v2, 4, v189
	s_lshl_b32 s10, s44, 1
	v_or_b32_e32 v197, s23, v0
	s_lshl_b32 s23, s44, 7
	v_bitop3_b32 v2, v2, 48, v189 bitop3:0x48
	v_lshlrev_b32_e32 v3, 9, v189
	s_ashr_i32 s13, s12, 31
	s_ashr_i32 s11, s10, 31
	s_and_b32 s23, s23, 0x80
	s_movk_i32 s42, 0x7800
	s_lshl_b64 s[10:11], s[10:11], 10
	s_add_i32 s29, s28, 0x2000
	v_or_b32_e32 v4, s23, v0
	v_and_or_b32 v0, v3, s42, v2
	v_lshlrev_b32_e32 v10, 4, v189
	v_and_b32_e32 v10, 0x3c0, v10
	v_or_b32_e32 v10, v10, v2
	v_mov_b32_e32 v11, 0
	s_lshl_b64 s[42:43], s[12:13], 6
	s_add_u32 s13, s18, s42
	s_addc_u32 s42, s19, s43
	s_add_u32 s10, s13, s10
	s_addc_u32 s11, s42, s11
	s_lshl_b64 s[42:43], s[14:15], 6
	s_add_u32 s13, s20, s42
	s_addc_u32 s42, s21, s43
	s_add_u32 s40, s13, s40
	s_addc_u32 s41, s42, s41
	s_lshl_b32 s13, s44, 11
	s_sub_i32 s13, s28, s13
	v_lshl_add_u64 v[192:193], s[10:11], 0, v[10:11]
	s_mov_b32 m0, s13
	s_nop 0
	global_load_lds_dwordx4 v[192:193], off
	global_load_lds_dwordx4 v[192:193], off offset:1024
	v_lshl_add_u64 v[194:195], s[40:41], 0, v[10:11]
	s_mov_b32 m0, s29
	s_nop 0
	global_load_lds_dwordx4 v[194:195], off
	global_load_lds_dwordx4 v[194:195], off offset:1024
	global_load_lds_dwordx4 v[194:195], off offset:2048
	global_load_lds_dwordx4 v[194:195], off offset:3072
	s_mov_b64 s[10:11], 0x10000
	s_mov_b64 s[10:11], 0x18000
	s_mov_b64 s[10:11], 0x8040
	s_add_i32 m0, s13, 0x6000
	s_mov_b32 vcc_lo, 0x480000
	s_mov_b32 vcc_hi, 0
	v_lshl_add_u64 v[2:3], v[192:193], 0, vcc
	global_load_lds_dwordx4 v[2:3], off
	global_load_lds_dwordx4 v[2:3], off offset:1024
	v_bfe_u32 v196, v189, 5, 1
	s_add_i32 m0, s28, 0x8000
	s_mov_b32 s100, 0x24000
	v_lshl_add_u64 v[2:3], v[194:195], 0, s[100:101]
	global_load_lds_dwordx4 v[2:3], off
	global_load_lds_dwordx4 v[2:3], off offset:1024
	global_load_lds_dwordx4 v[2:3], off offset:2048
	global_load_lds_dwordx4 v[2:3], off offset:3072
	s_mov_b64 s[10:11], 0x10040
	s_mov_b64 s[10:11], 0x18040
	v_lshlrev_b32_e32 v218, 6, v4
	v_bfe_u32 v4, v189, 2, 2
	v_lshrrev_b32_e32 v5, 5, v189
	s_lshl_b32 s100, s100, 1
	v_lshl_add_u64 v[194:195], v[194:195], 0, s[100:101]
	s_lshl_b32 vcc_lo, vcc_lo, 1
	v_lshl_add_u64 v[192:193], v[192:193], 0, vcc
	s_waitcnt vmcnt(6)
	s_barrier
	v_bitop3_b32 v2, v196, v4, 2 bitop3:0x36
	v_bitop3_b32 v0, v5, v4, 1 bitop3:0x6c
	v_lshlrev_b32_e32 v220, 4, v2
	v_mov_b32_e32 v2, 0
	v_lshlrev_b32_e32 v219, 6, v197
	v_lshlrev_b32_e32 v0, 4, v0
	s_mov_b32 s40, 0xc000
	s_mov_b32 s29, 0
	s_mov_b32 s41, 0
	v_mov_b32_e32 v3, v2
	v_mov_b32_e32 v4, v2
	v_mov_b32_e32 v5, v2
	v_mov_b32_e32 v6, v2
	v_mov_b32_e32 v7, v2
	v_mov_b32_e32 v8, v2
	v_mov_b32_e32 v9, v2
	v_mov_b32_e32 v10, v2
	v_mov_b32_e32 v11, v2
	v_mov_b32_e32 v12, v2
	v_mov_b32_e32 v13, v2
	v_mov_b32_e32 v14, v2
	v_mov_b32_e32 v15, v2
	v_mov_b32_e32 v16, v2
	v_mov_b32_e32 v17, v2
	v_mov_b32_e32 v18, v2
	v_mov_b32_e32 v19, v2
	v_mov_b32_e32 v20, v2
	v_mov_b32_e32 v21, v2
	v_mov_b32_e32 v22, v2
	v_mov_b32_e32 v23, v2
	v_mov_b32_e32 v24, v2
	v_mov_b32_e32 v25, v2
	v_mov_b32_e32 v26, v2
	v_mov_b32_e32 v27, v2
	v_mov_b32_e32 v28, v2
	v_mov_b32_e32 v29, v2
	v_mov_b32_e32 v30, v2
	v_mov_b32_e32 v31, v2
	v_mov_b32_e32 v32, v2
	v_mov_b32_e32 v33, v2
	v_mov_b32_e32 v50, v2
	v_mov_b32_e32 v51, v2
	v_mov_b32_e32 v52, v2
	v_mov_b32_e32 v53, v2
	v_mov_b32_e32 v54, v2
	v_mov_b32_e32 v55, v2
	v_mov_b32_e32 v56, v2
	v_mov_b32_e32 v57, v2
	v_mov_b32_e32 v58, v2
	v_mov_b32_e32 v59, v2
	v_mov_b32_e32 v60, v2
	v_mov_b32_e32 v61, v2
	v_mov_b32_e32 v62, v2
	v_mov_b32_e32 v63, v2
	v_mov_b32_e32 v64, v2
	v_mov_b32_e32 v65, v2
	v_mov_b32_e32 v82, v2
	v_mov_b32_e32 v83, v2
	v_mov_b32_e32 v84, v2
	v_mov_b32_e32 v85, v2
	v_mov_b32_e32 v86, v2
	v_mov_b32_e32 v87, v2
	v_mov_b32_e32 v88, v2
	v_mov_b32_e32 v89, v2
	v_mov_b32_e32 v90, v2
	v_mov_b32_e32 v91, v2
	v_mov_b32_e32 v92, v2
	v_mov_b32_e32 v93, v2
	v_mov_b32_e32 v94, v2
	v_mov_b32_e32 v95, v2
	v_mov_b32_e32 v96, v2
	v_mov_b32_e32 v97, v2
	v_mov_b32_e32 v34, v2
	v_mov_b32_e32 v35, v2
	v_mov_b32_e32 v36, v2
	v_mov_b32_e32 v37, v2
	v_mov_b32_e32 v38, v2
	v_mov_b32_e32 v39, v2
	v_mov_b32_e32 v40, v2
	v_mov_b32_e32 v41, v2
	v_mov_b32_e32 v42, v2
	v_mov_b32_e32 v43, v2
	v_mov_b32_e32 v44, v2
	v_mov_b32_e32 v45, v2
	v_mov_b32_e32 v46, v2
	v_mov_b32_e32 v47, v2
	v_mov_b32_e32 v48, v2
	v_mov_b32_e32 v49, v2
	v_mov_b32_e32 v66, v2
	v_mov_b32_e32 v67, v2
	v_mov_b32_e32 v68, v2
	v_mov_b32_e32 v69, v2
	v_mov_b32_e32 v70, v2
	v_mov_b32_e32 v71, v2
	v_mov_b32_e32 v72, v2
	v_mov_b32_e32 v73, v2
	v_mov_b32_e32 v74, v2
	v_mov_b32_e32 v75, v2
	v_mov_b32_e32 v76, v2
	v_mov_b32_e32 v77, v2
	v_mov_b32_e32 v78, v2
	v_mov_b32_e32 v79, v2
	v_mov_b32_e32 v80, v2
	v_mov_b32_e32 v81, v2
	v_mov_b32_e32 v98, v2
	v_mov_b32_e32 v99, v2
	v_mov_b32_e32 v100, v2
	v_mov_b32_e32 v101, v2
	v_mov_b32_e32 v102, v2
	v_mov_b32_e32 v103, v2
	v_mov_b32_e32 v104, v2
	v_mov_b32_e32 v105, v2
	v_mov_b32_e32 v106, v2
	v_mov_b32_e32 v107, v2
	v_mov_b32_e32 v108, v2
	v_mov_b32_e32 v109, v2
	v_mov_b32_e32 v110, v2
	v_mov_b32_e32 v111, v2
	v_mov_b32_e32 v112, v2
	v_mov_b32_e32 v113, v2
	v_mov_b32_e32 v114, v2
	v_mov_b32_e32 v115, v2
	v_mov_b32_e32 v116, v2
	v_mov_b32_e32 v117, v2
	v_mov_b32_e32 v118, v2
	v_mov_b32_e32 v119, v2
	v_mov_b32_e32 v120, v2
	v_mov_b32_e32 v121, v2
	v_mov_b32_e32 v122, v2
	v_mov_b32_e32 v123, v2
	v_mov_b32_e32 v124, v2
	v_mov_b32_e32 v125, v2
	v_mov_b32_e32 v126, v2
	v_mov_b32_e32 v127, v2
	v_mov_b32_e32 v128, v2
	v_mov_b32_e32 v129, v2
	s_mov_b32 vcc_hi, 0
	v_add_u32_e32 v158, 16, v219
	v_add_u32_e32 v170, 16, v218
	v_add_u32_e32 v158, v158, v0
	v_add_u32_e32 v170, v170, v0
	ds_read_b128 v[154:157], v158
	ds_read_b128 v[182:185], v170 offset:8192
	ds_read_b128 v[178:181], v170 offset:10240
	ds_read_b128 v[158:161], v158 offset:2048
	ds_read_b128 v[174:177], v170 offset:12288
	ds_read_b128 v[170:173], v170 offset:14336
; #define LAS __attribute__((address_space(3)))
; DI f32x16 mfma32(bf16x8 a, bf16x8 b, f32x16 c) { return __builtin_amdgcn_mfma_f32_32x32x16_bf16(a, b, c, 0, 0, 0); }
;     ...
;   for (int kt = 0; kt < nk; ++kt) {
;     const int kn = (kt + 2 < nk) ? (kt + 2) : (nk - 1);
;     const LAS char* cur = lds + s0;
;     bf16x8 af[2][2], bfr[2][4];
; #pragma unroll
;     for (int kk = 0; kk < 2; ++kk) {
;       const int xo = kk ? x1 : x0;
;       af[kk][0] = *(const LAS bf16x8*)(cur + a_rd + xo);
;       bfr[kk][0] = *(const LAS bf16x8*)(cur + b_rd + xo);
;       bfr[kk][1] = *(const LAS bf16x8*)(cur + b_rd + 2048 + xo);
;       af[kk][1] = *(const LAS bf16x8*)(cur + a_rd + 2048 + xo);
;       bfr[kk][2] = *(const LAS bf16x8*)(cur + b_rd + 4096 + xo);
;       bfr[kk][3] = *(const LAS bf16x8*)(cur + b_rd + 6144 + xo);
;     }
;     DMA_STEP_(kn, s2);
; #pragma unroll
;     for (int kk = 0; kk < 2; ++kk) {
;       acc[0][0] = mfma32(bfr[kk][0], af[kk][0], acc[0][0]); acc[0][1] = mfma32(bfr[kk][1], af[kk][0], acc[0][1]);
;       acc[1][0] = mfma32(bfr[kk][0], af[kk][1], acc[1][0]); acc[1][1] = mfma32(bfr[kk][1], af[kk][1], acc[1][1]);
;       acc[0][2] = mfma32(bfr[kk][2], af[kk][0], acc[0][2]); acc[0][3] = mfma32(bfr[kk][3], af[kk][0], acc[0][3]);
;       acc[1][2] = mfma32(bfr[kk][2], af[kk][1], acc[1][2]); acc[1][3] = mfma32(bfr[kk][3], af[kk][1], acc[1][3]);
;     }
;     __builtin_amdgcn_sched_group_barrier(0x100, 12, 0);
;     __builtin_amdgcn_sched_group_barrier(0x010, 6, 0);
;     __builtin_amdgcn_sched_group_barrier(0x008, 16, 0);
;     asm volatile("s_waitcnt vmcnt(6) lgkmcnt(0)" ::: "memory");
;     __builtin_amdgcn_s_barrier();
;     asm volatile("" ::: "memory");
;     s0 = (s0 == 2 * STG) ? 0 : s0 + STG;
;     s2 = (s2 == 2 * STG) ? 0 : s2 + STG;
;   }
.LBB0_235:
	s_add_i32 s11, s41, 16
	s_mov_b32 s10, s29
	v_add_u32_e32 v142, s11, v219
	v_add_u32_e32 v150, s11, v218
	s_min_u32 s10, s10, 29
	v_add_u32_e32 v142, v142, v220
	v_add_u32_e32 v150, v150, v220
	s_lshl_b32 s70, s10, 6
	ds_read_b128 v[138:141], v142
	ds_read_b128 v[162:165], v150 offset:8192
	ds_read_b128 v[166:169], v150 offset:10240
	ds_read_b128 v[142:145], v142 offset:2048
	ds_read_b128 v[146:149], v150 offset:12288
	ds_read_b128 v[150:153], v150 offset:14336
	s_mul_i32 vcc_lo, s70, 0x12000
	s_add_i32 s10, s13, s40
	v_lshl_add_u64 v[222:223], v[192:193], 0, vcc
	s_mov_b32 m0, s10
	s_mul_i32 s100, s70, 0x900
	v_lshl_add_u64 v[224:225], v[194:195], 0, s[100:101]
	s_add_i32 s10, s28, s40
	s_waitcnt lgkmcnt(6)
	v_mfma_f32_32x32x16_bf16 v[114:129], v[182:185], v[154:157], v[114:129]
	global_load_lds_dwordx4 v[222:223], off
	v_mfma_f32_32x32x16_bf16 v[98:113], v[178:181], v[154:157], v[98:113]
	global_load_lds_dwordx4 v[222:223], off offset:1024
	s_add_i32 m0, s10, 0x2000
	v_mfma_f32_32x32x16_bf16 v[66:81], v[182:185], v[158:161], v[66:81]
	global_load_lds_dwordx4 v[224:225], off
	v_mfma_f32_32x32x16_bf16 v[34:49], v[178:181], v[158:161], v[34:49]
	global_load_lds_dwordx4 v[224:225], off offset:1024
	v_mfma_f32_32x32x16_bf16 v[82:97], v[174:177], v[154:157], v[82:97]
	global_load_lds_dwordx4 v[224:225], off offset:2048
	v_mfma_f32_32x32x16_bf16 v[50:65], v[170:173], v[154:157], v[50:65]
	global_load_lds_dwordx4 v[224:225], off offset:3072
	v_mfma_f32_32x32x16_bf16 v[18:33], v[174:177], v[158:161], v[18:33]
	s_add_i32 s10, s41, 0x6000
	s_cmpk_lg_u32 s41, 0xc000
	s_cselect_b32 s41, s10, 0
	s_add_i32 s10, s40, 0x6000
	s_cmpk_lg_u32 s40, 0xc000
	s_cselect_b32 s40, s10, 0
	v_mfma_f32_32x32x16_bf16 v[2:17], v[170:173], v[158:161], v[2:17]
	s_add_i32 s11, s41, 16
	s_waitcnt vmcnt(6) lgkmcnt(0)
	s_barrier
	v_add_u32_e32 v158, s11, v219
	v_add_u32_e32 v170, s11, v218
	v_add_u32_e32 v158, v158, v0
	v_add_u32_e32 v170, v170, v0
	ds_read_b128 v[154:157], v158
	ds_read_b128 v[182:185], v170 offset:8192
	ds_read_b128 v[178:181], v170 offset:10240
	ds_read_b128 v[158:161], v158 offset:2048
	ds_read_b128 v[174:177], v170 offset:12288
	ds_read_b128 v[170:173], v170 offset:14336
	v_mfma_f32_32x32x16_bf16 v[114:129], v[162:165], v[138:141], v[114:129]
	v_mfma_f32_32x32x16_bf16 v[98:113], v[166:169], v[138:141], v[98:113]
	v_mfma_f32_32x32x16_bf16 v[66:81], v[162:165], v[142:145], v[66:81]
	v_mfma_f32_32x32x16_bf16 v[34:49], v[166:169], v[142:145], v[34:49]
	v_mfma_f32_32x32x16_bf16 v[82:97], v[146:149], v[138:141], v[82:97]
	v_mfma_f32_32x32x16_bf16 v[50:65], v[150:153], v[138:141], v[50:65]
	v_mfma_f32_32x32x16_bf16 v[18:33], v[146:149], v[142:145], v[18:33]
	v_mfma_f32_32x32x16_bf16 v[2:17], v[150:153], v[142:145], v[2:17]
	s_add_i32 s11, s41, 16
	s_add_i32 s10, s29, 1
	v_add_u32_e32 v142, s11, v219
	v_add_u32_e32 v150, s11, v218
	s_min_u32 s10, s10, 29
	v_add_u32_e32 v142, v142, v220
	v_add_u32_e32 v150, v150, v220
	s_lshl_b32 s70, s10, 6
	ds_read_b128 v[138:141], v142
	ds_read_b128 v[162:165], v150 offset:8192
	ds_read_b128 v[166:169], v150 offset:10240
	ds_read_b128 v[142:145], v142 offset:2048
	ds_read_b128 v[146:149], v150 offset:12288
	ds_read_b128 v[150:153], v150 offset:14336
	s_mul_i32 vcc_lo, s70, 0x12000
	s_add_i32 s10, s13, s40
	v_lshl_add_u64 v[222:223], v[192:193], 0, vcc
	s_mov_b32 m0, s10
	s_mul_i32 s100, s70, 0x900
	v_lshl_add_u64 v[224:225], v[194:195], 0, s[100:101]
	s_add_i32 s10, s28, s40
	s_waitcnt lgkmcnt(6)
	v_mfma_f32_32x32x16_bf16 v[114:129], v[182:185], v[154:157], v[114:129]
	global_load_lds_dwordx4 v[222:223], off
	v_mfma_f32_32x32x16_bf16 v[98:113], v[178:181], v[154:157], v[98:113]
	global_load_lds_dwordx4 v[222:223], off offset:1024
	s_add_i32 m0, s10, 0x2000
	v_mfma_f32_32x32x16_bf16 v[66:81], v[182:185], v[158:161], v[66:81]
	global_load_lds_dwordx4 v[224:225], off
	v_mfma_f32_32x32x16_bf16 v[34:49], v[178:181], v[158:161], v[34:49]
	global_load_lds_dwordx4 v[224:225], off offset:1024
	v_mfma_f32_32x32x16_bf16 v[82:97], v[174:177], v[154:157], v[82:97]
	global_load_lds_dwordx4 v[224:225], off offset:2048
	v_mfma_f32_32x32x16_bf16 v[50:65], v[170:173], v[154:157], v[50:65]
	global_load_lds_dwordx4 v[224:225], off offset:3072
	v_mfma_f32_32x32x16_bf16 v[18:33], v[174:177], v[158:161], v[18:33]
	s_add_i32 s10, s41, 0x6000
	s_cmpk_lg_u32 s41, 0xc000
	s_cselect_b32 s41, s10, 0
	s_add_i32 s10, s40, 0x6000
	s_cmpk_lg_u32 s40, 0xc000
	s_cselect_b32 s40, s10, 0
	v_mfma_f32_32x32x16_bf16 v[2:17], v[170:173], v[158:161], v[2:17]
	s_add_i32 s11, s41, 16
	s_waitcnt vmcnt(6) lgkmcnt(0)
	s_barrier
	v_add_u32_e32 v158, s11, v219
	v_add_u32_e32 v170, s11, v218
	v_add_u32_e32 v158, v158, v0
	v_add_u32_e32 v170, v170, v0
	ds_read_b128 v[154:157], v158
	ds_read_b128 v[182:185], v170 offset:8192
	ds_read_b128 v[178:181], v170 offset:10240
	ds_read_b128 v[158:161], v158 offset:2048
	ds_read_b128 v[174:177], v170 offset:12288
	ds_read_b128 v[170:173], v170 offset:14336
	v_mfma_f32_32x32x16_bf16 v[114:129], v[162:165], v[138:141], v[114:129]
	v_mfma_f32_32x32x16_bf16 v[98:113], v[166:169], v[138:141], v[98:113]
	v_mfma_f32_32x32x16_bf16 v[66:81], v[162:165], v[142:145], v[66:81]
	v_mfma_f32_32x32x16_bf16 v[34:49], v[166:169], v[142:145], v[34:49]
	v_mfma_f32_32x32x16_bf16 v[82:97], v[146:149], v[138:141], v[82:97]
	v_mfma_f32_32x32x16_bf16 v[50:65], v[150:153], v[138:141], v[50:65]
	v_mfma_f32_32x32x16_bf16 v[18:33], v[146:149], v[142:145], v[18:33]
	v_mfma_f32_32x32x16_bf16 v[2:17], v[150:153], v[142:145], v[2:17]
	s_add_i32 s29, s29, 2
	s_cmp_lg_u32 s29, 32
	s_cbranch_scc1 .LBB0_235
; DI unsigned pk2(float a, float b) { f32x2 v = {a, b}; bf2_t r = __builtin_convertvector(v, bf2_t); return __builtin_bit_cast(unsigned, r); }
;     ...
;   asm volatile("s_waitcnt vmcnt(0)" ::: "memory");
;   __builtin_amdgcn_s_barrier();
;   asm volatile("" ::: "memory");
;     ...
;   {
;     const int h = lane >> 5, cl = lane & 31;
; #pragma unroll
;     for (int i = 0; i < 2; ++i)
; #pragma unroll
;       for (int j = 0; j < 4; ++j)
; #pragma unroll
;         for (int g = 0; g < 4; ++g) {
;           u32x2 w; w.x = pk2(acc[i][j][4 * g], acc[i][j][4 * g + 1]); w.y = pk2(acc[i][j][4 * g + 2], acc[i][j][4 * g + 3]);
;           *(u32x2*)(smem + (wr * 64 + i * 32 + cl) * 528 + (wc * 128 + j * 32 + 8 * g + 4 * h) * 2) = w;
;         }
;   }
;   __syncthreads();
	s_waitcnt lgkmcnt(0)
	v_mul_lo_u32 v0, v197, s55
	v_add_u32_e32 v0, 16, v0
	s_nop 1
	v_cvt_pk_bf16_f32 v114, v114, v115
	v_cvt_pk_bf16_f32 v115, v116, v117
	v_lshlrev_b32_e32 v116, 3, v196
	s_lshl_b32 s10, s23, 1
	v_add3_u32 v0, v0, v116, s10
	v_cvt_pk_bf16_f32 v116, v118, v119
	v_cvt_pk_bf16_f32 v117, v120, v121
	v_cvt_pk_bf16_f32 v98, v98, v99
	v_cvt_pk_bf16_f32 v99, v100, v101
	v_cvt_pk_bf16_f32 v100, v102, v103
	v_cvt_pk_bf16_f32 v101, v104, v105
	v_cvt_pk_bf16_f32 v82, v82, v83
	v_cvt_pk_bf16_f32 v83, v84, v85
	v_cvt_pk_bf16_f32 v84, v86, v87
	v_cvt_pk_bf16_f32 v85, v88, v89
	v_cvt_pk_bf16_f32 v50, v50, v51
	v_cvt_pk_bf16_f32 v51, v52, v53
	v_cvt_pk_bf16_f32 v52, v54, v55
	v_cvt_pk_bf16_f32 v53, v56, v57
	s_waitcnt vmcnt(0)
	s_barrier
	ds_write2_b64 v0, v[114:115], v[116:117] offset1:2
	v_cvt_pk_bf16_f32 v114, v122, v123
	v_cvt_pk_bf16_f32 v115, v124, v125
	v_cvt_pk_bf16_f32 v116, v126, v127
	v_cvt_pk_bf16_f32 v117, v128, v129
	ds_write2_b64 v0, v[98:99], v[100:101] offset0:8 offset1:10
	v_cvt_pk_bf16_f32 v98, v106, v107
	v_cvt_pk_bf16_f32 v99, v108, v109
	v_cvt_pk_bf16_f32 v100, v110, v111
	v_cvt_pk_bf16_f32 v101, v112, v113
	ds_write2_b64 v0, v[82:83], v[84:85] offset0:16 offset1:18
	v_cvt_pk_bf16_f32 v82, v90, v91
	v_cvt_pk_bf16_f32 v83, v92, v93
	v_cvt_pk_bf16_f32 v84, v94, v95
	v_cvt_pk_bf16_f32 v85, v96, v97
	ds_write2_b64 v0, v[50:51], v[52:53] offset0:24 offset1:26
	v_cvt_pk_bf16_f32 v50, v58, v59
	v_cvt_pk_bf16_f32 v51, v60, v61
	v_cvt_pk_bf16_f32 v52, v62, v63
	v_cvt_pk_bf16_f32 v53, v64, v65
	ds_write2_b64 v0, v[114:115], v[116:117] offset0:4 offset1:6
	ds_write2_b64 v0, v[98:99], v[100:101] offset0:12 offset1:14
	ds_write2_b64 v0, v[82:83], v[84:85] offset0:20 offset1:22
	ds_write2_b64 v0, v[50:51], v[52:53] offset0:28 offset1:30
	v_cvt_pk_bf16_f32 v50, v66, v67
	v_cvt_pk_bf16_f32 v51, v68, v69
	v_cvt_pk_bf16_f32 v52, v70, v71
	v_cvt_pk_bf16_f32 v53, v72, v73
	v_add_u32_e32 v0, 0x4000, v0
	v_cvt_pk_bf16_f32 v34, v34, v35
	v_cvt_pk_bf16_f32 v35, v36, v37
	v_cvt_pk_bf16_f32 v36, v38, v39
	v_cvt_pk_bf16_f32 v37, v40, v41
	v_cvt_pk_bf16_f32 v18, v18, v19
	v_cvt_pk_bf16_f32 v19, v20, v21
	v_cvt_pk_bf16_f32 v20, v22, v23
	v_cvt_pk_bf16_f32 v21, v24, v25
	v_cvt_pk_bf16_f32 v2, v2, v3
	v_cvt_pk_bf16_f32 v3, v4, v5
	v_cvt_pk_bf16_f32 v4, v6, v7
	v_cvt_pk_bf16_f32 v5, v8, v9
	ds_write2_b64 v0, v[50:51], v[52:53] offset0:64 offset1:66
	v_cvt_pk_bf16_f32 v50, v74, v75
	v_cvt_pk_bf16_f32 v51, v76, v77
	v_cvt_pk_bf16_f32 v52, v78, v79
	v_cvt_pk_bf16_f32 v53, v80, v81
	ds_write2_b64 v0, v[34:35], v[36:37] offset0:72 offset1:74
	v_cvt_pk_bf16_f32 v34, v42, v43
	v_cvt_pk_bf16_f32 v35, v44, v45
	v_cvt_pk_bf16_f32 v36, v46, v47
	v_cvt_pk_bf16_f32 v37, v48, v49
	ds_write2_b64 v0, v[18:19], v[20:21] offset0:80 offset1:82
	v_cvt_pk_bf16_f32 v18, v26, v27
	v_cvt_pk_bf16_f32 v19, v28, v29
	v_cvt_pk_bf16_f32 v20, v30, v31
	v_cvt_pk_bf16_f32 v21, v32, v33
	ds_write2_b64 v0, v[2:3], v[4:5] offset0:88 offset1:90
	v_cvt_pk_bf16_f32 v2, v10, v11
	v_cvt_pk_bf16_f32 v3, v12, v13
	v_cvt_pk_bf16_f32 v4, v14, v15
	v_cvt_pk_bf16_f32 v5, v16, v17
	s_lshl_b64 s[10:11], s[14:15], 1
	ds_write2_b64 v0, v[50:51], v[52:53] offset0:68 offset1:70
	ds_write2_b64 v0, v[34:35], v[36:37] offset0:76 offset1:78
	ds_write2_b64 v0, v[18:19], v[20:21] offset0:84 offset1:86
	ds_write2_b64 v0, v[2:3], v[4:5] offset0:92 offset1:94
	s_waitcnt vmcnt(0) lgkmcnt(0)
	s_barrier
; #define GAS __attribute__((address_space(1)))
;     ...
;   if (EPI == 0) {
; #pragma unroll
;     for (int i = 0; i < 16; ++i) {
;       const int id = tid2 + 256 * i, r = id >> 5, c8 = (id & 31) * 8;
;       const u32x4 v = *(const u32x4*)(smem + r * 528 + c8 * 2);
;       *(GAS u32x4*)(ea.out + (size_t)(m0 + r) * ea.ldo + n0 + c8) = v;
;     }
	s_add_u32 s10, s16, s10
	v_lshlrev_b32_e32 v0, 4, v189
	v_and_b32_e32 v0, 0x1f0, v0
	s_addc_u32 s11, s17, s11
	v_add_u32_e32 v10, 16, v0
	v_lshl_add_u64 v[12:13], s[10:11], 0, v[0:1]
	v_ashrrev_i32_e32 v0, 5, v189
	v_mad_u64_u32 v[2:3], s[10:11], v0, s55, v[10:11]
	v_add_u32_e32 v0, s12, v0
	v_mad_i64_i32 v[14:15], s[10:11], v0, s35, v[12:13]
	v_add_u32_e32 v0, 0x100, v189
	ds_read_b128 v[2:5], v2
	v_ashrrev_i32_e32 v0, 5, v0
	v_mad_u64_u32 v[6:7], s[10:11], v0, s55, v[10:11]
	ds_read_b128 v[6:9], v6
	v_add_u32_e32 v0, s12, v0
	s_waitcnt lgkmcnt(1)
	global_store_dwordx4 v[14:15], v[2:5], off
	s_nop 1
	v_mad_i64_i32 v[2:3], s[10:11], v0, s35, v[12:13]
	v_add_u32_e32 v0, 0x200, v189
	v_ashrrev_i32_e32 v0, 5, v0
	s_waitcnt lgkmcnt(0)
	global_store_dwordx4 v[2:3], v[6:9], off
	v_mad_u64_u32 v[2:3], s[10:11], v0, s55, v[10:11]
	v_add_u32_e32 v0, s12, v0
	v_mad_i64_i32 v[14:15], s[10:11], v0, s35, v[12:13]
	v_add_u32_e32 v0, 0x300, v189
	ds_read_b128 v[2:5], v2
	v_ashrrev_i32_e32 v0, 5, v0
	v_mad_u64_u32 v[6:7], s[10:11], v0, s55, v[10:11]
	ds_read_b128 v[6:9], v6
	v_add_u32_e32 v0, s12, v0
	s_waitcnt lgkmcnt(1)
	global_store_dwordx4 v[14:15], v[2:5], off
	s_nop 1
	v_mad_i64_i32 v[2:3], s[10:11], v0, s35, v[12:13]
	v_add_u32_e32 v0, 0x400, v189
	v_ashrrev_i32_e32 v0, 5, v0
	s_waitcnt lgkmcnt(0)
	global_store_dwordx4 v[2:3], v[6:9], off
	v_mad_u64_u32 v[2:3], s[10:11], v0, s55, v[10:11]
	v_add_u32_e32 v0, s12, v0
	v_mad_i64_i32 v[14:15], s[10:11], v0, s35, v[12:13]
	v_add_u32_e32 v0, 0x500, v189
	ds_read_b128 v[2:5], v2
	v_ashrrev_i32_e32 v0, 5, v0
	v_mad_u64_u32 v[6:7], s[10:11], v0, s55, v[10:11]
	ds_read_b128 v[6:9], v6
	v_add_u32_e32 v0, s12, v0
	s_waitcnt lgkmcnt(1)
	global_store_dwordx4 v[14:15], v[2:5], off
	s_nop 1
	v_mad_i64_i32 v[2:3], s[10:11], v0, s35, v[12:13]
	v_add_u32_e32 v0, 0x600, v189
	v_ashrrev_i32_e32 v0, 5, v0
	s_waitcnt lgkmcnt(0)
	global_store_dwordx4 v[2:3], v[6:9], off
	v_mad_u64_u32 v[2:3], s[10:11], v0, s55, v[10:11]
	v_add_u32_e32 v0, s12, v0
	v_mad_i64_i32 v[14:15], s[10:11], v0, s35, v[12:13]
	v_add_u32_e32 v0, 0x700, v189
	ds_read_b128 v[2:5], v2
	v_ashrrev_i32_e32 v0, 5, v0
	v_mad_u64_u32 v[6:7], s[10:11], v0, s55, v[10:11]
	ds_read_b128 v[6:9], v6
	v_add_u32_e32 v0, s12, v0
	s_waitcnt lgkmcnt(1)
	global_store_dwordx4 v[14:15], v[2:5], off
	s_nop 1
	v_mad_i64_i32 v[2:3], s[10:11], v0, s35, v[12:13]
	v_add_u32_e32 v0, 0x800, v189
	v_ashrrev_i32_e32 v0, 5, v0
	s_waitcnt lgkmcnt(0)
	global_store_dwordx4 v[2:3], v[6:9], off
	v_mad_u64_u32 v[2:3], s[10:11], v0, s55, v[10:11]
	v_add_u32_e32 v0, s12, v0
	v_mad_i64_i32 v[14:15], s[10:11], v0, s35, v[12:13]
	v_add_u32_e32 v0, 0x900, v189
	ds_read_b128 v[2:5], v2
	v_ashrrev_i32_e32 v0, 5, v0
	v_mad_u64_u32 v[6:7], s[10:11], v0, s55, v[10:11]
	ds_read_b128 v[6:9], v6
	v_add_u32_e32 v0, s12, v0
	s_waitcnt lgkmcnt(1)
	global_store_dwordx4 v[14:15], v[2:5], off
	s_nop 1
	v_mad_i64_i32 v[2:3], s[10:11], v0, s35, v[12:13]
	v_add_u32_e32 v0, 0xa00, v189
	v_ashrrev_i32_e32 v0, 5, v0
	s_waitcnt lgkmcnt(0)
	global_store_dwordx4 v[2:3], v[6:9], off
	v_mad_u64_u32 v[2:3], s[10:11], v0, s55, v[10:11]
	v_add_u32_e32 v0, s12, v0
	v_mad_i64_i32 v[14:15], s[10:11], v0, s35, v[12:13]
	v_add_u32_e32 v0, 0xb00, v189
	ds_read_b128 v[2:5], v2
	v_ashrrev_i32_e32 v0, 5, v0
	v_mad_u64_u32 v[6:7], s[10:11], v0, s55, v[10:11]
	ds_read_b128 v[6:9], v6
	v_add_u32_e32 v0, s12, v0
	s_waitcnt lgkmcnt(1)
	global_store_dwordx4 v[14:15], v[2:5], off
	s_nop 1
	v_mad_i64_i32 v[2:3], s[10:11], v0, s35, v[12:13]
	v_add_u32_e32 v0, 0xc00, v189
	v_ashrrev_i32_e32 v0, 5, v0
	s_waitcnt lgkmcnt(0)
	global_store_dwordx4 v[2:3], v[6:9], off
	v_mad_u64_u32 v[2:3], s[10:11], v0, s55, v[10:11]
	v_add_u32_e32 v0, s12, v0
	v_mad_i64_i32 v[14:15], s[10:11], v0, s35, v[12:13]
	v_add_u32_e32 v0, 0xd00, v189
	ds_read_b128 v[2:5], v2
	v_ashrrev_i32_e32 v0, 5, v0
	v_mad_u64_u32 v[6:7], s[10:11], v0, s55, v[10:11]
	ds_read_b128 v[6:9], v6
	v_add_u32_e32 v0, s12, v0
	s_waitcnt lgkmcnt(1)
	global_store_dwordx4 v[14:15], v[2:5], off
	s_nop 1
	v_mad_i64_i32 v[2:3], s[10:11], v0, s35, v[12:13]
	v_add_u32_e32 v0, 0xe00, v189
	v_ashrrev_i32_e32 v0, 5, v0
	s_waitcnt lgkmcnt(0)
	global_store_dwordx4 v[2:3], v[6:9], off
	v_mad_u64_u32 v[2:3], s[10:11], v0, s55, v[10:11]
	ds_read_b128 v[2:5], v2
	v_add_u32_e32 v0, s12, v0
	v_mad_i64_i32 v[14:15], s[10:11], v0, s35, v[12:13]
	v_add_u32_e32 v0, 0xf00, v189
	v_ashrrev_i32_e32 v0, 5, v0
	v_mad_u64_u32 v[6:7], s[10:11], v0, s55, v[10:11]
	ds_read_b128 v[6:9], v6
	v_add_u32_e32 v0, s12, v0
	s_waitcnt lgkmcnt(1)
	global_store_dwordx4 v[14:15], v[2:5], off
	s_nop 1
	v_mad_i64_i32 v[2:3], s[10:11], v0, s35, v[12:13]
	v_readlane_b32 s10, v252, 12
	s_add_i32 s22, s22, s10
	v_readlane_b32 s10, v252, 38
	s_cmp_ge_i32 s22, s10
	s_waitcnt lgkmcnt(0)
	global_store_dwordx4 v[2:3], v[6:9], off
	s_barrier
	s_cbranch_scc0 .LBB0_230

; #define LAS __attribute__((address_space(3)))
;     ...
;   const int lane = tid & 63, wid = __builtin_amdgcn_readfirstlane(tid >> 6), wr = wid >> 1, wc = wid & 1;
;   const int m0 = mt * 128, n0 = nt * 256;
;   const int r = lane & 31, h = lane >> 5, key = (r >> 2) & 3;
;   constexpr int STG = 24576;
;   const int rowl = lane >> 2, cch = (lane & 3) ^ ((lane >> 4) & 3);
;   const unsigned voffA = (unsigned)(rowl * lda * 2 + cch * 16), voffB = (unsigned)(rowl * K * 2 + cch * 16);
;   const char* Abase = (const char*)(A + (size_t)m0 * lda) + (size_t)(wid * 2) * 32 * lda;
;   const char* Bbase = (const char*)(Bt + (size_t)n0 * K) + (size_t)(wid * 4) * 32 * K;
;   const size_t ablk = (size_t)32 * lda, bblk = (size_t)32 * K;
;   LAS char* lds = (LAS char*)smem;
;   LAS char* ldsA = lds + (wid * 2) * 1024;
;   LAS char* ldsB = lds + 8192 + (wid * 4) * 1024;
;     ...
;   const int x0 = ((0 + h) ^ key) * 16, x1 = ((2 + h) ^ key) * 16;
;   const int a_rd = (wr * 64 + r) * 64, b_rd = 8192 + (wc * 128 + r) * 64;
;   f32x16 acc[2][4];
; #pragma unroll
;   for (int i = 0; i < 2; ++i)
; #pragma unroll
;     for (int j = 0; j < 4; ++j)
; #pragma unroll
;       for (int e = 0; e < 16; ++e) acc[i][j][e] = 0.f;
;   const int nk = K >> 5;
;   DMA_STEP_(0, 0);
;   DMA_STEP_(1, STG);
;   asm volatile("s_waitcnt vmcnt(6)" ::: "memory");
;   __builtin_amdgcn_s_barrier();
;   asm volatile("" ::: "memory");
;   int s0 = 0, s2 = 2 * STG;
.LBB0_271:
	s_mul_hi_i32 s10, s14, 0x2e8ba2e9
	s_lshr_b32 s11, s10, 31
	s_ashr_i32 s10, s10, 4
	s_add_i32 s10, s10, s11
	v_readlane_b32 s15, v252, 18
	s_mul_i32 s11, s10, 0xffffffa8
	s_lshl_b32 s10, s10, s15
	v_readlane_b32 s15, v252, 41
	s_add_i32 s10, s10, s15
	s_lshr_b32 s15, s10, 31
	s_add_i32 s15, s10, s15
	s_and_b32 s18, s15, -2
	s_add_i32 s11, s11, s14
	s_sub_i32 s10, s10, s18
	s_mul_i32 s22, s10, 11
	s_ashr_i32 s10, s11, 3
	v_mov_b32_e32 v189, v188
	s_lshl_b32 s15, s15, 2
	s_add_i32 s22, s22, s10
	s_and_b32 s15, s15, -8
	v_readfirstlane_b32 s10, v189
	s_and_b32 s18, s14, 7
	s_ashr_i32 s11, s10, 6
	s_or_b32 s15, s15, s18
	s_lshl_b32 s18, s11, 1
	s_ashr_i32 s19, s18, 31
	s_lshl_b64 s[28:29], s[18:19], 10
	s_lshl_b32 s18, s11, 2
	s_ashr_i32 s19, s18, 31
	s_ashr_i32 s10, s10, 1
	s_lshl_b32 s46, s15, 7
	s_lshl_b32 s66, s22, 8
	v_and_b32_e32 v0, 31, v189
	s_lshl_b64 s[74:75], s[18:19], 10
	s_lshl_b32 s18, s11, 12
	s_andn2_b32 s10, s10, 63
	v_lshlrev_b32_e32 v3, 4, v189
	s_ashr_i32 s47, s46, 31
	s_ashr_i32 s67, s66, 31
	s_add_i32 s19, s18, 16
	v_or_b32_e32 v197, s10, v0
	s_lshl_b32 s10, s11, 7
	v_lshlrev_b32_e32 v2, 9, v189
	v_bitop3_b32 v3, v3, 48, v189 bitop3:0x48
	s_lshl_b64 s[20:21], s[46:47], 6
	s_lshl_b64 s[40:41], s[66:67], 6
	s_add_i32 s23, s19, 0x2000
	s_and_b32 s18, s10, 0x80
	s_movk_i32 s10, 0x7800
	v_or_b32_e32 v4, s18, v0
	v_and_or_b32 v0, v2, s10, v3
	v_lshlrev_b32_e32 v10, 4, v189
	v_and_b32_e32 v10, 0x3c0, v10
	v_or_b32_e32 v10, v10, v3
	v_mov_b32_e32 v11, 0
	s_add_u32 s10, s42, s20
	s_addc_u32 s20, s43, s21
	s_add_u32 s28, s10, s28
	s_addc_u32 s29, s20, s29
	s_add_u32 s10, s87, s40
	s_addc_u32 s21, s76, s41
	s_lshl_b32 s11, s11, 11
	s_sub_i32 s20, s19, s11
	s_mov_b32 m0, s20
	v_lshl_add_u64 v[192:193], s[28:29], 0, v[10:11]
	global_load_lds_dwordx4 v[192:193], off
	global_load_lds_dwordx4 v[192:193], off offset:1024
	s_add_u32 s28, s10, s74
	s_addc_u32 s29, s21, s75
	v_lshl_add_u64 v[194:195], s[28:29], 0, v[10:11]
	s_mov_b32 m0, s23
	s_nop 0
	global_load_lds_dwordx4 v[194:195], off
	global_load_lds_dwordx4 v[194:195], off offset:1024
	global_load_lds_dwordx4 v[194:195], off offset:2048
	global_load_lds_dwordx4 v[194:195], off offset:3072
	s_mov_b64 s[10:11], 0x10000
	s_mov_b64 s[10:11], 0x18000
	s_mov_b64 s[10:11], 0x8040
	s_add_i32 m0, s20, 0x6000
	s_mov_b32 vcc_lo, 0x480000
	s_mov_b32 vcc_hi, 0
	v_lshl_add_u64 v[2:3], v[192:193], 0, vcc
	global_load_lds_dwordx4 v[2:3], off
	global_load_lds_dwordx4 v[2:3], off offset:1024
	v_lshrrev_b32_e32 v5, 5, v189
	s_add_i32 m0, s19, 0x8000
	s_mov_b32 s100, 0x58000
	v_lshl_add_u64 v[2:3], v[194:195], 0, s[100:101]
	global_load_lds_dwordx4 v[2:3], off
	global_load_lds_dwordx4 v[2:3], off offset:1024
	global_load_lds_dwordx4 v[2:3], off offset:2048
	global_load_lds_dwordx4 v[2:3], off offset:3072
	s_mov_b64 s[10:11], 0x10040
	s_mov_b64 s[10:11], 0x18040
	v_bfe_u32 v6, v189, 2, 2
	v_bfe_u32 v196, v189, 5, 1
	s_lshl_b32 s100, s100, 1
	v_lshl_add_u64 v[194:195], v[194:195], 0, s[100:101]
	s_lshl_b32 vcc_lo, vcc_lo, 1
	v_lshl_add_u64 v[192:193], v[192:193], 0, vcc
	s_waitcnt vmcnt(6)
	s_barrier
	v_bitop3_b32 v2, v5, v6, 1 bitop3:0x6c
	v_lshlrev_b32_e32 v219, 4, v2
	v_bitop3_b32 v2, v196, v6, 2 bitop3:0x36
	v_mov_b32_e32 v66, 0
	v_lshlrev_b32_e32 v218, 6, v197
	v_lshlrev_b32_e32 v0, 6, v4
	v_lshlrev_b32_e32 v220, 4, v2
	s_mov_b32 s23, 0xc000
	s_mov_b32 s28, 0
	s_mov_b32 s21, 0
	v_mov_b32_e32 v67, v66
	v_mov_b32_e32 v68, v66
	v_mov_b32_e32 v69, v66
	v_mov_b32_e32 v70, v66
	v_mov_b32_e32 v71, v66
	v_mov_b32_e32 v72, v66
	v_mov_b32_e32 v73, v66
	v_mov_b32_e32 v74, v66
	v_mov_b32_e32 v75, v66
	v_mov_b32_e32 v76, v66
	v_mov_b32_e32 v77, v66
	v_mov_b32_e32 v78, v66
	v_mov_b32_e32 v79, v66
	v_mov_b32_e32 v80, v66
	v_mov_b32_e32 v81, v66
	v_mov_b32_e32 v82, v66
	v_mov_b32_e32 v83, v66
	v_mov_b32_e32 v84, v66
	v_mov_b32_e32 v85, v66
	v_mov_b32_e32 v86, v66
	v_mov_b32_e32 v87, v66
	v_mov_b32_e32 v88, v66
	v_mov_b32_e32 v89, v66
	s_waitcnt vmcnt(0)
	v_mov_b32_e32 v90, v66
	v_mov_b32_e32 v91, v66
	v_mov_b32_e32 v92, v66
	v_mov_b32_e32 v93, v66
	v_mov_b32_e32 v94, v66
	v_mov_b32_e32 v95, v66
	v_mov_b32_e32 v96, v66
	v_mov_b32_e32 v97, v66
	v_mov_b32_e32 v18, v66
	v_mov_b32_e32 v19, v66
	v_mov_b32_e32 v20, v66
	v_mov_b32_e32 v21, v66
	v_mov_b32_e32 v22, v66
	v_mov_b32_e32 v23, v66
	v_mov_b32_e32 v24, v66
	v_mov_b32_e32 v25, v66
	v_mov_b32_e32 v26, v66
	v_mov_b32_e32 v27, v66
	v_mov_b32_e32 v28, v66
	v_mov_b32_e32 v29, v66
	v_mov_b32_e32 v30, v66
	v_mov_b32_e32 v31, v66
	v_mov_b32_e32 v32, v66
	v_mov_b32_e32 v33, v66
	v_mov_b32_e32 v2, v66
	v_mov_b32_e32 v3, v66
	v_mov_b32_e32 v4, v66
	v_mov_b32_e32 v5, v66
	v_mov_b32_e32 v6, v66
	v_mov_b32_e32 v7, v66
	v_mov_b32_e32 v8, v66
	v_mov_b32_e32 v9, v66
	v_mov_b32_e32 v10, v66
	v_mov_b32_e32 v11, v66
	v_mov_b32_e32 v12, v66
	v_mov_b32_e32 v13, v66
	v_mov_b32_e32 v14, v66
	v_mov_b32_e32 v15, v66
	v_mov_b32_e32 v16, v66
	v_mov_b32_e32 v17, v66
	v_mov_b32_e32 v114, v66
	v_mov_b32_e32 v115, v66
	v_mov_b32_e32 v116, v66
	v_mov_b32_e32 v117, v66
	v_mov_b32_e32 v118, v66
	v_mov_b32_e32 v119, v66
	v_mov_b32_e32 v120, v66
	v_mov_b32_e32 v121, v66
	v_mov_b32_e32 v122, v66
	v_mov_b32_e32 v123, v66
	v_mov_b32_e32 v124, v66
	v_mov_b32_e32 v125, v66
	v_mov_b32_e32 v126, v66
	v_mov_b32_e32 v127, v66
	v_mov_b32_e32 v128, v66
	v_mov_b32_e32 v129, v66
	v_mov_b32_e32 v98, v66
	v_mov_b32_e32 v99, v66
	v_mov_b32_e32 v100, v66
	v_mov_b32_e32 v101, v66
	v_mov_b32_e32 v102, v66
	v_mov_b32_e32 v103, v66
	v_mov_b32_e32 v104, v66
	v_mov_b32_e32 v105, v66
	v_mov_b32_e32 v106, v66
	v_mov_b32_e32 v107, v66
	v_mov_b32_e32 v108, v66
	v_mov_b32_e32 v109, v66
	v_mov_b32_e32 v110, v66
	v_mov_b32_e32 v111, v66
	v_mov_b32_e32 v112, v66
	v_mov_b32_e32 v113, v66
	v_mov_b32_e32 v50, v66
	v_mov_b32_e32 v51, v66
	v_mov_b32_e32 v52, v66
	v_mov_b32_e32 v53, v66
	v_mov_b32_e32 v54, v66
	v_mov_b32_e32 v55, v66
	v_mov_b32_e32 v56, v66
	v_mov_b32_e32 v57, v66
	v_mov_b32_e32 v58, v66
	v_mov_b32_e32 v59, v66
	v_mov_b32_e32 v60, v66
	v_mov_b32_e32 v61, v66
	v_mov_b32_e32 v62, v66
	v_mov_b32_e32 v63, v66
	v_mov_b32_e32 v64, v66
	v_mov_b32_e32 v65, v66
	v_mov_b32_e32 v34, v66
	v_mov_b32_e32 v35, v66
	v_mov_b32_e32 v36, v66
	v_mov_b32_e32 v37, v66
	v_mov_b32_e32 v38, v66
	v_mov_b32_e32 v39, v66
	v_mov_b32_e32 v40, v66
	v_mov_b32_e32 v41, v66
	v_mov_b32_e32 v42, v66
	v_mov_b32_e32 v43, v66
	v_mov_b32_e32 v44, v66
	v_mov_b32_e32 v45, v66
	v_mov_b32_e32 v46, v66
	v_mov_b32_e32 v47, v66
	v_mov_b32_e32 v48, v66
	v_mov_b32_e32 v49, v66
	s_mov_b32 vcc_hi, 0
	v_add_u32_e32 v158, 16, v218
	v_add_u32_e32 v170, 16, v0
	v_add_u32_e32 v158, v158, v219
	v_add_u32_e32 v170, v170, v219
	ds_read_b128 v[154:157], v158
	ds_read_b128 v[182:185], v170 offset:8192
	ds_read_b128 v[178:181], v170 offset:10240
	ds_read_b128 v[158:161], v158 offset:2048
	ds_read_b128 v[174:177], v170 offset:12288
	ds_read_b128 v[170:173], v170 offset:14336
; #define LAS __attribute__((address_space(3)))
; DI f32x16 mfma32(bf16x8 a, bf16x8 b, f32x16 c) { return __builtin_amdgcn_mfma_f32_32x32x16_bf16(a, b, c, 0, 0, 0); }
;     ...
;   for (int kt = 0; kt < nk; ++kt) {
;     const int kn = (kt + 2 < nk) ? (kt + 2) : (nk - 1);
;     const LAS char* cur = lds + s0;
;     bf16x8 af[2][2], bfr[2][4];
; #pragma unroll
;     for (int kk = 0; kk < 2; ++kk) {
;       const int xo = kk ? x1 : x0;
;       af[kk][0] = *(const LAS bf16x8*)(cur + a_rd + xo);
;       bfr[kk][0] = *(const LAS bf16x8*)(cur + b_rd + xo);
;       bfr[kk][1] = *(const LAS bf16x8*)(cur + b_rd + 2048 + xo);
;       af[kk][1] = *(const LAS bf16x8*)(cur + a_rd + 2048 + xo);
;       bfr[kk][2] = *(const LAS bf16x8*)(cur + b_rd + 4096 + xo);
;       bfr[kk][3] = *(const LAS bf16x8*)(cur + b_rd + 6144 + xo);
;     }
;     DMA_STEP_(kn, s2);
; #pragma unroll
;     for (int kk = 0; kk < 2; ++kk) {
;       acc[0][0] = mfma32(bfr[kk][0], af[kk][0], acc[0][0]); acc[0][1] = mfma32(bfr[kk][1], af[kk][0], acc[0][1]);
;       acc[1][0] = mfma32(bfr[kk][0], af[kk][1], acc[1][0]); acc[1][1] = mfma32(bfr[kk][1], af[kk][1], acc[1][1]);
;       acc[0][2] = mfma32(bfr[kk][2], af[kk][0], acc[0][2]); acc[0][3] = mfma32(bfr[kk][3], af[kk][0], acc[0][3]);
;       acc[1][2] = mfma32(bfr[kk][2], af[kk][1], acc[1][2]); acc[1][3] = mfma32(bfr[kk][3], af[kk][1], acc[1][3]);
;     }
;     __builtin_amdgcn_sched_group_barrier(0x100, 12, 0);
;     __builtin_amdgcn_sched_group_barrier(0x010, 6, 0);
;     __builtin_amdgcn_sched_group_barrier(0x008, 16, 0);
;     asm volatile("s_waitcnt vmcnt(6) lgkmcnt(0)" ::: "memory");
;     __builtin_amdgcn_s_barrier();
;     asm volatile("" ::: "memory");
;     s0 = (s0 == 2 * STG) ? 0 : s0 + STG;
;     s2 = (s2 == 2 * STG) ? 0 : s2 + STG;
;   }
.LBB0_272:
	s_add_i32 s11, s28, 16
	s_mov_b32 s10, s21
	v_add_u32_e32 v142, s11, v218
	v_add_u32_e32 v150, s11, v0
	s_min_u32 s10, s10, 29
	v_add_u32_e32 v142, v142, v220
	v_add_u32_e32 v150, v150, v220
	s_lshl_b32 s70, s10, 6
	ds_read_b128 v[138:141], v142
	ds_read_b128 v[162:165], v150 offset:8192
	ds_read_b128 v[166:169], v150 offset:10240
	ds_read_b128 v[142:145], v142 offset:2048
	ds_read_b128 v[146:149], v150 offset:12288
	ds_read_b128 v[150:153], v150 offset:14336
	s_mul_i32 vcc_lo, s70, 0x12000
	s_add_i32 s10, s20, s23
	v_lshl_add_u64 v[222:223], v[192:193], 0, vcc
	s_mov_b32 m0, s10
	s_mul_i32 s100, s70, 0x1600
	v_lshl_add_u64 v[224:225], v[194:195], 0, s[100:101]
	s_add_i32 s10, s19, s23
	s_waitcnt lgkmcnt(6)
	v_mfma_f32_32x32x16_bf16 v[66:81], v[182:185], v[154:157], v[66:81]
	global_load_lds_dwordx4 v[222:223], off
	v_mfma_f32_32x32x16_bf16 v[82:97], v[178:181], v[154:157], v[82:97]
	global_load_lds_dwordx4 v[222:223], off offset:1024
	s_add_i32 m0, s10, 0x2000
	v_mfma_f32_32x32x16_bf16 v[18:33], v[182:185], v[158:161], v[18:33]
	global_load_lds_dwordx4 v[224:225], off
	v_mfma_f32_32x32x16_bf16 v[2:17], v[178:181], v[158:161], v[2:17]
	global_load_lds_dwordx4 v[224:225], off offset:1024
	v_mfma_f32_32x32x16_bf16 v[114:129], v[174:177], v[154:157], v[114:129]
	global_load_lds_dwordx4 v[224:225], off offset:2048
	v_mfma_f32_32x32x16_bf16 v[98:113], v[170:173], v[154:157], v[98:113]
	global_load_lds_dwordx4 v[224:225], off offset:3072
	v_mfma_f32_32x32x16_bf16 v[50:65], v[174:177], v[158:161], v[50:65]
	s_add_i32 s10, s28, 0x6000
	s_cmpk_lg_u32 s28, 0xc000
	s_cselect_b32 s28, s10, 0
	s_add_i32 s10, s23, 0x6000
	s_cmpk_lg_u32 s23, 0xc000
	s_cselect_b32 s23, s10, 0
	v_mfma_f32_32x32x16_bf16 v[34:49], v[170:173], v[158:161], v[34:49]
	s_add_i32 s11, s28, 16
	s_waitcnt vmcnt(6) lgkmcnt(0)
	s_barrier
	v_add_u32_e32 v158, s11, v218
	v_add_u32_e32 v170, s11, v0
	v_add_u32_e32 v158, v158, v219
	v_add_u32_e32 v170, v170, v219
	ds_read_b128 v[154:157], v158
	ds_read_b128 v[182:185], v170 offset:8192
	ds_read_b128 v[178:181], v170 offset:10240
	ds_read_b128 v[158:161], v158 offset:2048
	ds_read_b128 v[174:177], v170 offset:12288
	ds_read_b128 v[170:173], v170 offset:14336
	v_mfma_f32_32x32x16_bf16 v[66:81], v[162:165], v[138:141], v[66:81]
	v_mfma_f32_32x32x16_bf16 v[82:97], v[166:169], v[138:141], v[82:97]
	v_mfma_f32_32x32x16_bf16 v[18:33], v[162:165], v[142:145], v[18:33]
	v_mfma_f32_32x32x16_bf16 v[2:17], v[166:169], v[142:145], v[2:17]
	v_mfma_f32_32x32x16_bf16 v[114:129], v[146:149], v[138:141], v[114:129]
	v_mfma_f32_32x32x16_bf16 v[98:113], v[150:153], v[138:141], v[98:113]
	v_mfma_f32_32x32x16_bf16 v[50:65], v[146:149], v[142:145], v[50:65]
	v_mfma_f32_32x32x16_bf16 v[34:49], v[150:153], v[142:145], v[34:49]
	s_add_i32 s11, s28, 16
	s_add_i32 s10, s21, 1
	v_add_u32_e32 v142, s11, v218
	v_add_u32_e32 v150, s11, v0
	s_min_u32 s10, s10, 29
	v_add_u32_e32 v142, v142, v220
	v_add_u32_e32 v150, v150, v220
	s_lshl_b32 s70, s10, 6
	ds_read_b128 v[138:141], v142
	ds_read_b128 v[162:165], v150 offset:8192
	ds_read_b128 v[166:169], v150 offset:10240
	ds_read_b128 v[142:145], v142 offset:2048
	ds_read_b128 v[146:149], v150 offset:12288
	ds_read_b128 v[150:153], v150 offset:14336
	s_mul_i32 vcc_lo, s70, 0x12000
	s_add_i32 s10, s20, s23
	v_lshl_add_u64 v[222:223], v[192:193], 0, vcc
	s_mov_b32 m0, s10
	s_mul_i32 s100, s70, 0x1600
	v_lshl_add_u64 v[224:225], v[194:195], 0, s[100:101]
	s_add_i32 s10, s19, s23
	s_waitcnt lgkmcnt(6)
	v_mfma_f32_32x32x16_bf16 v[66:81], v[182:185], v[154:157], v[66:81]
	global_load_lds_dwordx4 v[222:223], off
	v_mfma_f32_32x32x16_bf16 v[82:97], v[178:181], v[154:157], v[82:97]
	global_load_lds_dwordx4 v[222:223], off offset:1024
	s_add_i32 m0, s10, 0x2000
	v_mfma_f32_32x32x16_bf16 v[18:33], v[182:185], v[158:161], v[18:33]
	global_load_lds_dwordx4 v[224:225], off
	v_mfma_f32_32x32x16_bf16 v[2:17], v[178:181], v[158:161], v[2:17]
	global_load_lds_dwordx4 v[224:225], off offset:1024
	v_mfma_f32_32x32x16_bf16 v[114:129], v[174:177], v[154:157], v[114:129]
	global_load_lds_dwordx4 v[224:225], off offset:2048
	v_mfma_f32_32x32x16_bf16 v[98:113], v[170:173], v[154:157], v[98:113]
	global_load_lds_dwordx4 v[224:225], off offset:3072
	v_mfma_f32_32x32x16_bf16 v[50:65], v[174:177], v[158:161], v[50:65]
	s_add_i32 s10, s28, 0x6000
	s_cmpk_lg_u32 s28, 0xc000
	s_cselect_b32 s28, s10, 0
	s_add_i32 s10, s23, 0x6000
	s_cmpk_lg_u32 s23, 0xc000
	s_cselect_b32 s23, s10, 0
	v_mfma_f32_32x32x16_bf16 v[34:49], v[170:173], v[158:161], v[34:49]
	s_add_i32 s11, s28, 16
	s_waitcnt vmcnt(6) lgkmcnt(0)
	s_barrier
; #define GAS __attribute__((address_space(1)))
; DI unsigned pk2(float a, float b) { f32x2 v = {a, b}; bf2_t r = __builtin_convertvector(v, bf2_t); return __builtin_bit_cast(unsigned, r); }
;     ...
;   asm volatile("s_waitcnt vmcnt(0)" ::: "memory");
;   __builtin_amdgcn_s_barrier();
;   asm volatile("" ::: "memory");
;     ...
;   {
;     const int h = lane >> 5, cl = lane & 31;
; #pragma unroll
;     for (int i = 0; i < 2; ++i)
; #pragma unroll
;       for (int j = 0; j < 4; ++j)
; #pragma unroll
;         for (int g = 0; g < 4; ++g) {
;           u32x2 w; w.x = pk2(acc[i][j][4 * g], acc[i][j][4 * g + 1]); w.y = pk2(acc[i][j][4 * g + 2], acc[i][j][4 * g + 3]);
;           *(u32x2*)(smem + (wr * 64 + i * 32 + cl) * 528 + (wc * 128 + j * 32 + 8 * g + 4 * h) * 2) = w;
;         }
;   }
;   __syncthreads();
;   int tid2 = tid; asm volatile("" : "+v"(tid2));
;   if (EPI == 0) {
; #pragma unroll
;     for (int i = 0; i < 16; ++i) {
;       const int id = tid2 + 256 * i, r = id >> 5, c8 = (id & 31) * 8;
;       const u32x4 v = *(const u32x4*)(smem + r * 528 + c8 * 2);
;       *(GAS u32x4*)(ea.out + (size_t)(m0 + r) * ea.ldo + n0 + c8) = v;
;     }
;   } else {
;     const int L = (mt < 512) ? 2048 : 256;
;     const bool first = (m0 % L) == 0, last = ((m0 + 128) % L) == 0;
;     const float* cw = ea.cw; const float* cb = ea.cb;
; #pragma unroll 1
;     for (int p = 0; p < 2; ++p) {
;       const int j8 = (tid2 & 7) * 8;
;       const int ja0 = (nt * 2 + p) * 64, ja = ja0 + j8;
	v_add_u32_e32 v158, s11, v218
	v_add_u32_e32 v170, s11, v0
	v_add_u32_e32 v158, v158, v219
	v_add_u32_e32 v170, v170, v219
	ds_read_b128 v[154:157], v158
	ds_read_b128 v[182:185], v170 offset:8192
	ds_read_b128 v[178:181], v170 offset:10240
	ds_read_b128 v[158:161], v158 offset:2048
	ds_read_b128 v[174:177], v170 offset:12288
	ds_read_b128 v[170:173], v170 offset:14336
	v_mfma_f32_32x32x16_bf16 v[66:81], v[162:165], v[138:141], v[66:81]
	v_mfma_f32_32x32x16_bf16 v[82:97], v[166:169], v[138:141], v[82:97]
	v_mfma_f32_32x32x16_bf16 v[18:33], v[162:165], v[142:145], v[18:33]
	v_mfma_f32_32x32x16_bf16 v[2:17], v[166:169], v[142:145], v[2:17]
	v_mfma_f32_32x32x16_bf16 v[114:129], v[146:149], v[138:141], v[114:129]
	v_mfma_f32_32x32x16_bf16 v[98:113], v[150:153], v[138:141], v[98:113]
	v_mfma_f32_32x32x16_bf16 v[50:65], v[146:149], v[142:145], v[50:65]
	v_mfma_f32_32x32x16_bf16 v[34:49], v[150:153], v[142:145], v[34:49]
	s_add_i32 s21, s21, 2
	s_cmp_eq_u32 s21, 32
	s_cbranch_scc0 .LBB0_272
	s_waitcnt lgkmcnt(0)
	v_mul_lo_u32 v0, v197, s55
	v_add_u32_e32 v0, 16, v0
	s_nop 1
	v_cvt_pk_bf16_f32 v66, v66, v67
	v_cvt_pk_bf16_f32 v67, v68, v69
	v_lshlrev_b32_e32 v68, 3, v196
	s_lshl_b32 s10, s18, 1
	v_add3_u32 v0, v0, v68, s10
	v_cvt_pk_bf16_f32 v68, v70, v71
	v_cvt_pk_bf16_f32 v69, v72, v73
	s_waitcnt vmcnt(0)
	s_barrier
	ds_write2_b64 v0, v[66:67], v[68:69] offset1:2
	v_cvt_pk_bf16_f32 v66, v74, v75
	v_cvt_pk_bf16_f32 v67, v76, v77
	v_cvt_pk_bf16_f32 v68, v78, v79
	v_cvt_pk_bf16_f32 v69, v80, v81
	ds_write2_b64 v0, v[66:67], v[68:69] offset0:4 offset1:6
	v_cvt_pk_bf16_f32 v66, v82, v83
	v_cvt_pk_bf16_f32 v67, v84, v85
	v_cvt_pk_bf16_f32 v68, v86, v87
	v_cvt_pk_bf16_f32 v69, v88, v89
	ds_write2_b64 v0, v[66:67], v[68:69] offset0:8 offset1:10
	v_cvt_pk_bf16_f32 v66, v90, v91
	v_cvt_pk_bf16_f32 v67, v92, v93
	v_cvt_pk_bf16_f32 v68, v94, v95
	v_cvt_pk_bf16_f32 v69, v96, v97
	ds_write2_b64 v0, v[66:67], v[68:69] offset0:12 offset1:14
	v_cvt_pk_bf16_f32 v66, v114, v115
	v_cvt_pk_bf16_f32 v67, v116, v117
	v_cvt_pk_bf16_f32 v68, v118, v119
	v_cvt_pk_bf16_f32 v69, v120, v121
	ds_write2_b64 v0, v[66:67], v[68:69] offset0:16 offset1:18
	v_cvt_pk_bf16_f32 v66, v122, v123
	v_cvt_pk_bf16_f32 v67, v124, v125
	v_cvt_pk_bf16_f32 v68, v126, v127
	v_cvt_pk_bf16_f32 v69, v128, v129
	ds_write2_b64 v0, v[66:67], v[68:69] offset0:20 offset1:22
	v_cvt_pk_bf16_f32 v66, v98, v99
	v_cvt_pk_bf16_f32 v67, v100, v101
	v_cvt_pk_bf16_f32 v68, v102, v103
	v_cvt_pk_bf16_f32 v69, v104, v105
	ds_write2_b64 v0, v[66:67], v[68:69] offset0:24 offset1:26
	v_cvt_pk_bf16_f32 v66, v106, v107
	v_cvt_pk_bf16_f32 v67, v108, v109
	v_cvt_pk_bf16_f32 v68, v110, v111
	v_cvt_pk_bf16_f32 v69, v112, v113
	ds_write2_b64 v0, v[66:67], v[68:69] offset0:28 offset1:30
	v_add_u32_e32 v0, 0x4000, v0
	v_cvt_pk_bf16_f32 v2, v2, v3
	v_cvt_pk_bf16_f32 v3, v4, v5
	v_cvt_pk_bf16_f32 v4, v6, v7
	v_cvt_pk_bf16_f32 v5, v8, v9
	ds_write2_b64 v0, v[2:3], v[4:5] offset0:72 offset1:74
	v_cvt_pk_bf16_f32 v2, v10, v11
	v_cvt_pk_bf16_f32 v3, v12, v13
	v_cvt_pk_bf16_f32 v4, v14, v15
	v_cvt_pk_bf16_f32 v5, v16, v17
	ds_write2_b64 v0, v[2:3], v[4:5] offset0:76 offset1:78
	v_cvt_pk_bf16_f32 v2, v50, v51
	v_cvt_pk_bf16_f32 v3, v52, v53
	v_cvt_pk_bf16_f32 v4, v54, v55
	v_cvt_pk_bf16_f32 v5, v56, v57
	s_cmpk_lt_i32 s15, 0x200
	ds_write2_b64 v0, v[2:3], v[4:5] offset0:80 offset1:82
	v_cvt_pk_bf16_f32 v2, v58, v59
	v_cvt_pk_bf16_f32 v3, v60, v61
	v_cvt_pk_bf16_f32 v4, v62, v63
	v_cvt_pk_bf16_f32 v5, v64, v65
	s_cselect_b32 s10, 0x7ff, s78
	v_cvt_pk_bf16_f32 v18, v18, v19
	v_cvt_pk_bf16_f32 v19, v20, v21
	v_cvt_pk_bf16_f32 v20, v22, v23
	v_cvt_pk_bf16_f32 v21, v24, v25
	ds_write2_b64 v0, v[2:3], v[4:5] offset0:84 offset1:86
	v_cvt_pk_bf16_f32 v2, v34, v35
	v_cvt_pk_bf16_f32 v3, v36, v37
	v_cvt_pk_bf16_f32 v4, v38, v39
	v_cvt_pk_bf16_f32 v5, v40, v41
	s_and_b32 s11, s10, s46
	ds_write2_b64 v0, v[18:19], v[20:21] offset0:64 offset1:66
	v_cvt_pk_bf16_f32 v18, v26, v27
	v_cvt_pk_bf16_f32 v19, v28, v29
	v_cvt_pk_bf16_f32 v20, v30, v31
	v_cvt_pk_bf16_f32 v21, v32, v33
	ds_write2_b64 v0, v[2:3], v[4:5] offset0:88 offset1:90
	v_cvt_pk_bf16_f32 v2, v42, v43
	v_cvt_pk_bf16_f32 v3, v44, v45
	v_cvt_pk_bf16_f32 v4, v46, v47
	v_cvt_pk_bf16_f32 v5, v48, v49
	s_cmp_eq_u32 s11, 0
	ds_write2_b64 v0, v[18:19], v[20:21] offset0:68 offset1:70
	ds_write2_b64 v0, v[2:3], v[4:5] offset0:92 offset1:94
	s_waitcnt vmcnt(0) lgkmcnt(0)
	s_barrier
	s_cselect_b64 s[18:19], -1, 0
	s_add_i32 s11, s46, 0x80
	v_lshlrev_b32_e32 v0, 3, v189
	s_and_b32 s10, s11, s10
	v_and_b32_e32 v96, 56, v0
	s_cmp_eq_u32 s10, 0
	v_lshlrev_b32_e32 v0, 1, v96
	s_mov_b32 s40, 0
	s_cselect_b64 s[20:21], -1, 0
	s_lshl_b32 s47, s22, 7
	v_add_u32_e32 v97, 16, v0
	v_lshl_add_u64 v[90:91], s[44:45], 0, v[0:1]
	s_mov_b64 s[28:29], -1
	s_branch .LBB0_275

; __global__ void __launch_bounds__(256, 2) fwd_kernel(Params p) {
;     ...
;         const float* md = MOD + ((size_t)layer * 33 + mr) * 6144;
;         RowIO4 io;
;         if (lat) { io.xin = (ph == 8) ? pp->in[0] + (size_t)row * 1024 : XL + (size_t)row * 1024; io.xout = XL + (size_t)row * 1024; }
;         else { io.xin = (ph == 8) ? pp->in[2] + (size_t)(row - NL) * 1024 : XC + (size_t)(row - NL) * 1024; io.xout = XC + (size_t)(row - NL) * 1024; }
;         io.y = Y + (size_t)row * 1024;
;         io.gate = md + (second ? 5120 : 2048);
;         if (ph == 23) { io.shift = nullptr; io.scale = nullptr; io.hout = nullptr; }
;         else if (ph == 12) { const float* md1 = MOD + ((size_t)33 + mr) * 6144; io.shift = md1; io.scale = md1 + 1024; io.hout = H + (size_t)row * 1024; }
;         else { io.shift = md + 3072; io.scale = md + 4096; io.hout = H + (size_t)row * 1024; }
.LBB0_361:
	s_min_i32 s10, s77, 0x4000
	s_ashr_i32 s63, s10, 9
	s_add_i32 s10, s57, s63
	s_mul_hi_i32 s11, s10, 0x6000
	s_mulk_i32 s10, 0x6000
	s_add_u32 s42, s53, s10
	s_addc_u32 s43, s56, s11
	s_lshl_b64 s[28:29], s[44:45], 10
	s_mov_b64 s[20:21], 0
	s_andn2_b64 vcc, exec, s[14:15]
	s_mov_b64 s[22:23], 0
	s_mov_b64 s[46:47], 0
	s_cbranch_vccnz .LBB0_366
	s_mov_b64 s[40:41], -1
	s_and_b64 vcc, exec, s[12:13]
	s_cbranch_vccz .LBB0_364
	s_add_u32 s20, s42, 0x3000
	s_addc_u32 s21, s43, 0
	s_add_u32 s22, s42, 0x4000
	s_addc_u32 s23, s43, 0
	s_lshl_b64 s[40:41], s[44:45], 6
	s_add_u32 s46, s60, s40
	s_addc_u32 s47, s61, s41
	s_mov_b64 s[40:41], 0
.LBB0_364:
	s_andn2_b64 vcc, exec, s[40:41]
	s_cbranch_vccnz .LBB0_366
	s_mul_hi_i32 s10, s63, 0x6000
	s_mulk_i32 s63, 0x6000
	s_add_u32 s11, s53, s63
	s_addc_u32 s10, s56, s10
	s_add_u32 s20, s11, 0xc6000
	s_addc_u32 s21, s10, 0
	s_add_u32 s22, s11, 0xc7000
	s_addc_u32 s23, s10, 0
	s_lshl_b64 s[40:41], s[44:45], 6
	s_add_u32 s46, s60, s40
	s_addc_u32 s47, s61, s41

; #define GAS __attribute__((address_space(1)))
; DI unsigned pk2(float a, float b) { f32x2 v = {a, b}; bf2_t r = __builtin_convertvector(v, bf2_t); return __builtin_bit_cast(unsigned, r); }
; DI void rw_rows4(const RowIO4& R, const float* __restrict__ ga, const float* __restrict__ gb, int lane) {
;     ...
;     if (R.hout) {
;       float ss = 0.f;
; #pragma unroll
;       for (int i = 0; i < 4; ++i) ss += x[r][i][0] * x[r][i][0] + x[r][i][1] * x[r][i][1] + x[r][i][2] * x[r][i][2] + x[r][i][3] * x[r][i][3];
;       const float rinv = rsqrtf(wave_sum(ss) * (1.f / 1024.f) + 1e-6f);
; #pragma unroll
;       for (int i = 0; i < 4; ++i) {
;         const f32x4 hv = (x[r][i] * rinv * gb4[i]) * (sc4[i] + 1.f) + sh4[i];
;         u32x2 w; w.x = pk2(hv[0], hv[1]); w.y = pk2(hv[2], hv[3]);
;         *(GAS u32x2*)(R.hout + r * 1024 + 4 * lane + 256 * i) = w;
;       }
;     }
.LBB0_371:
	v_cndmask_b32_e64 v168, 0, 1, s[18:19]
	v_cmp_ne_u32_e64 s[40:41], 1, v168
	s_andn2_b64 vcc, exec, s[18:19]
	v_lshlrev_b32_e32 v168, 1, v138
	v_lshrrev_b32_e32 v244, 6, v168
	v_and_b32_e32 v240, 56, v168
	v_mul_u32_u24_e32 v244, 0x480000, v244
	v_add_u32_e32 v240, v240, v244
	v_add_u32_e32 v241, 0x2400000, v240
	v_add_u32_e32 v242, 0x4800000, v240
	v_add_u32_e32 v243, 0x6c00000, v240
	s_cbranch_vccnz .LBB0_373
	v_mov_b32_e32 v194, v127
	v_mov_b32_e32 v195, v123
	v_mov_b32_e32 v192, v126
	v_mov_b32_e32 v193, v122
	v_pk_mul_f32 v[194:195], v[194:195], v[194:195]
	v_mov_b32_e32 v196, v115
	v_pk_fma_f32 v[192:193], v[192:193], v[192:193], v[194:195]
	v_mov_b32_e32 v194, v128
	v_mov_b32_e32 v195, v124
	v_pk_fma_f32 v[192:193], v[194:195], v[194:195], v[192:193]
	v_mov_b32_e32 v194, v129
	v_mov_b32_e32 v195, v125
	v_mov_b32_e32 v197, v119
	v_pk_fma_f32 v[192:193], v[194:195], v[194:195], v[192:193]
	v_mov_b32_e32 v194, v114
	v_mov_b32_e32 v195, v118
	v_pk_mul_f32 v[196:197], v[196:197], v[196:197]
	v_add_f32_e32 v169, v192, v193
	v_pk_fma_f32 v[194:195], v[194:195], v[194:195], v[196:197]
	v_mov_b32_e32 v196, v116
	v_mov_b32_e32 v197, v120
	v_pk_fma_f32 v[194:195], v[196:197], v[196:197], v[194:195]
	v_mov_b32_e32 v196, v117
	v_mov_b32_e32 v197, v121
	v_pk_fma_f32 v[194:195], v[196:197], v[196:197], v[194:195]
	s_nop 0
	v_add_f32_e32 v169, v195, v169
	v_add_f32_e32 v169, v194, v169
	ds_bpermute_b32 v192, v139, v169
	s_waitcnt lgkmcnt(0)
	v_add_f32_e32 v169, v169, v192
	ds_bpermute_b32 v192, v189, v169
	s_waitcnt lgkmcnt(0)
	v_add_f32_e32 v169, v169, v192
	ds_bpermute_b32 v192, v218, v169
	s_waitcnt lgkmcnt(0)
	v_add_f32_e32 v169, v169, v192
	ds_bpermute_b32 v192, v219, v169
	s_waitcnt lgkmcnt(0)
	v_add_f32_e32 v169, v169, v192
	ds_bpermute_b32 v192, v220, v169
	s_waitcnt lgkmcnt(0)
	v_add_f32_e32 v169, v169, v192
	ds_bpermute_b32 v192, v221, v169
	s_waitcnt lgkmcnt(0)
	v_add_f32_e32 v169, v169, v192
	v_fmamk_f32 v169, v169, 0x3a800000, v186
	v_mul_f32_e32 v192, 0x4b800000, v169
	v_cmp_gt_f32_e32 vcc, s11, v169
	s_nop 1
	v_cndmask_b32_e32 v169, v169, v192, vcc
	v_rsq_f32_e32 v169, v169
	s_nop 0
	v_mul_f32_e32 v192, 0x45800000, v169
	v_cndmask_b32_e32 v192, v169, v192, vcc
	v_pk_mul_f32 v[128:129], v[128:129], v[192:193] op_sel_hi:[1,0]
	v_pk_mul_f32 v[126:127], v[126:127], v[192:193] op_sel_hi:[1,0]
	v_pk_mul_f32 v[124:125], v[124:125], v[192:193] op_sel_hi:[1,0]
	v_pk_mul_f32 v[122:123], v[122:123], v[192:193] op_sel_hi:[1,0]
	v_pk_mul_f32 v[120:121], v[120:121], v[192:193] op_sel_hi:[1,0]
	v_pk_mul_f32 v[118:119], v[118:119], v[192:193] op_sel_hi:[1,0]
	v_pk_mul_f32 v[116:117], v[116:117], v[192:193] op_sel_hi:[1,0]
	v_pk_mul_f32 v[114:115], v[114:115], v[192:193] op_sel_hi:[1,0]
	v_pk_mul_f32 v[126:127], v[42:43], v[126:127]
	v_pk_mul_f32 v[128:129], v[44:45], v[128:129]
	v_pk_mul_f32 v[122:123], v[30:31], v[122:123]
	v_pk_mul_f32 v[124:125], v[32:33], v[124:125]
	v_pk_mul_f32 v[118:119], v[26:27], v[118:119]
	v_pk_mul_f32 v[120:121], v[28:29], v[120:121]
	v_pk_mul_f32 v[114:115], v[18:19], v[114:115]
	v_pk_mul_f32 v[116:117], v[20:21], v[116:117]
	v_pk_fma_f32 v[128:129], v[158:159], v[128:129], v[48:49]
	v_pk_fma_f32 v[126:127], v[156:157], v[126:127], v[46:47]
	v_pk_fma_f32 v[124:125], v[154:155], v[124:125], v[40:41]
	v_pk_fma_f32 v[122:123], v[152:153], v[122:123], v[38:39]
	v_pk_fma_f32 v[120:121], v[150:151], v[120:121], v[36:37]
	v_pk_fma_f32 v[118:119], v[148:149], v[118:119], v[34:35]
	v_pk_fma_f32 v[116:117], v[146:147], v[116:117], v[24:25]
	v_pk_fma_f32 v[114:115], v[144:145], v[114:115], v[22:23]
	v_cvt_pk_bf16_f32 v126, v126, v127
	v_cvt_pk_bf16_f32 v127, v128, v129
	v_cvt_pk_bf16_f32 v122, v122, v123
	v_cvt_pk_bf16_f32 v123, v124, v125
	v_cvt_pk_bf16_f32 v118, v118, v119
	v_cvt_pk_bf16_f32 v119, v120, v121
	v_cvt_pk_bf16_f32 v114, v114, v115
	v_cvt_pk_bf16_f32 v115, v116, v117
	global_store_dwordx2 v240, v[126:127], s[46:47]
	global_store_dwordx2 v241, v[122:123], s[46:47]
	global_store_dwordx2 v242, v[118:119], s[46:47]
	global_store_dwordx2 v243, v[114:115], s[46:47]

; #define GAS __attribute__((address_space(1)))
; DI unsigned pk2(float a, float b) { f32x2 v = {a, b}; bf2_t r = __builtin_convertvector(v, bf2_t); return __builtin_bit_cast(unsigned, r); }
; DI void rw_rows4(const RowIO4& R, const float* __restrict__ ga, const float* __restrict__ gb, int lane) {
;     ...
;     if (R.hout) {
;       float ss = 0.f;
; #pragma unroll
;       for (int i = 0; i < 4; ++i) ss += x[r][i][0] * x[r][i][0] + x[r][i][1] * x[r][i][1] + x[r][i][2] * x[r][i][2] + x[r][i][3] * x[r][i][3];
;       const float rinv = rsqrtf(wave_sum(ss) * (1.f / 1024.f) + 1e-6f);
; #pragma unroll
;       for (int i = 0; i < 4; ++i) {
;         const f32x4 hv = (x[r][i] * rinv * gb4[i]) * (sc4[i] + 1.f) + sh4[i];
;         u32x2 w; w.x = pk2(hv[0], hv[1]); w.y = pk2(hv[2], hv[3]);
;         *(GAS u32x2*)(R.hout + r * 1024 + 4 * lane + 256 * i) = w;
;       }
;     }
.LBB0_375:
	s_and_b64 vcc, exec, s[40:41]
	s_cbranch_vccnz .LBB0_377
	v_mov_b32_e32 v116, v111
	v_mov_b32_e32 v117, v107
	v_mov_b32_e32 v114, v110
	v_mov_b32_e32 v115, v106
	v_pk_mul_f32 v[116:117], v[116:117], v[116:117]
	v_mov_b32_e32 v118, v99
	v_pk_fma_f32 v[114:115], v[114:115], v[114:115], v[116:117]
	v_mov_b32_e32 v116, v112
	v_mov_b32_e32 v117, v108
	v_pk_fma_f32 v[114:115], v[116:117], v[116:117], v[114:115]
	v_mov_b32_e32 v116, v113
	v_mov_b32_e32 v117, v109
	v_mov_b32_e32 v119, v103
	v_pk_fma_f32 v[114:115], v[116:117], v[116:117], v[114:115]
	v_mov_b32_e32 v116, v98
	v_mov_b32_e32 v117, v102
	v_pk_mul_f32 v[118:119], v[118:119], v[118:119]
	v_add_f32_e32 v114, v114, v115
	v_pk_fma_f32 v[116:117], v[116:117], v[116:117], v[118:119]
	v_mov_b32_e32 v118, v100
	v_mov_b32_e32 v119, v104
	v_pk_fma_f32 v[116:117], v[118:119], v[118:119], v[116:117]
	v_mov_b32_e32 v118, v101
	v_mov_b32_e32 v119, v105
	v_pk_fma_f32 v[116:117], v[118:119], v[118:119], v[116:117]
	s_nop 0
	v_add_f32_e32 v114, v117, v114
	v_add_f32_e32 v114, v116, v114
	ds_bpermute_b32 v115, v139, v114
	s_waitcnt lgkmcnt(0)
	v_add_f32_e32 v114, v114, v115
	ds_bpermute_b32 v115, v189, v114
	s_waitcnt lgkmcnt(0)
	v_add_f32_e32 v114, v114, v115
	ds_bpermute_b32 v115, v218, v114
	s_waitcnt lgkmcnt(0)
	v_add_f32_e32 v114, v114, v115
	ds_bpermute_b32 v115, v219, v114
	s_waitcnt lgkmcnt(0)
	v_add_f32_e32 v114, v114, v115
	ds_bpermute_b32 v115, v220, v114
	s_waitcnt lgkmcnt(0)
	v_add_f32_e32 v114, v114, v115
	ds_bpermute_b32 v115, v221, v114
	s_waitcnt lgkmcnt(0)
	v_add_f32_e32 v114, v114, v115
	v_fmamk_f32 v114, v114, 0x3a800000, v186
	v_mul_f32_e32 v115, 0x4b800000, v114
	v_cmp_gt_f32_e32 vcc, s11, v114
	s_nop 1
	v_cndmask_b32_e32 v114, v114, v115, vcc
	v_rsq_f32_e32 v114, v114
	s_nop 0
	v_mul_f32_e32 v115, 0x45800000, v114
	v_cndmask_b32_e32 v114, v114, v115, vcc
	v_pk_mul_f32 v[112:113], v[112:113], v[114:115] op_sel_hi:[1,0]
	v_pk_mul_f32 v[110:111], v[110:111], v[114:115] op_sel_hi:[1,0]
	v_pk_mul_f32 v[108:109], v[108:109], v[114:115] op_sel_hi:[1,0]
	v_pk_mul_f32 v[106:107], v[106:107], v[114:115] op_sel_hi:[1,0]
	v_pk_mul_f32 v[104:105], v[104:105], v[114:115] op_sel_hi:[1,0]
	v_pk_mul_f32 v[102:103], v[102:103], v[114:115] op_sel_hi:[1,0]
	v_pk_mul_f32 v[100:101], v[100:101], v[114:115] op_sel_hi:[1,0]
	v_pk_mul_f32 v[98:99], v[98:99], v[114:115] op_sel_hi:[1,0]
	v_pk_mul_f32 v[110:111], v[42:43], v[110:111]
	v_pk_mul_f32 v[112:113], v[44:45], v[112:113]
	v_pk_mul_f32 v[106:107], v[30:31], v[106:107]
	v_pk_mul_f32 v[108:109], v[32:33], v[108:109]
	v_pk_mul_f32 v[102:103], v[26:27], v[102:103]
	v_pk_mul_f32 v[104:105], v[28:29], v[104:105]
	v_pk_mul_f32 v[98:99], v[18:19], v[98:99]
	v_pk_mul_f32 v[100:101], v[20:21], v[100:101]
	v_pk_fma_f32 v[112:113], v[158:159], v[112:113], v[48:49]
	v_pk_fma_f32 v[110:111], v[156:157], v[110:111], v[46:47]
	v_pk_fma_f32 v[108:109], v[154:155], v[108:109], v[40:41]
	v_pk_fma_f32 v[106:107], v[152:153], v[106:107], v[38:39]
	v_pk_fma_f32 v[104:105], v[150:151], v[104:105], v[36:37]
	v_pk_fma_f32 v[102:103], v[148:149], v[102:103], v[34:35]
	v_pk_fma_f32 v[100:101], v[146:147], v[100:101], v[24:25]
	v_pk_fma_f32 v[98:99], v[144:145], v[98:99], v[22:23]
	v_cvt_pk_bf16_f32 v110, v110, v111
	v_cvt_pk_bf16_f32 v111, v112, v113
	v_cvt_pk_bf16_f32 v106, v106, v107
	v_cvt_pk_bf16_f32 v107, v108, v109
	v_cvt_pk_bf16_f32 v102, v102, v103
	v_cvt_pk_bf16_f32 v103, v104, v105
	v_cvt_pk_bf16_f32 v98, v98, v99
	v_cvt_pk_bf16_f32 v99, v100, v101
	global_store_dwordx2 v240, v[110:111], s[46:47] offset:64
	global_store_dwordx2 v241, v[106:107], s[46:47] offset:64
	global_store_dwordx2 v242, v[102:103], s[46:47] offset:64
	global_store_dwordx2 v243, v[98:99], s[46:47] offset:64

; #define GAS __attribute__((address_space(1)))
; DI unsigned pk2(float a, float b) { f32x2 v = {a, b}; bf2_t r = __builtin_convertvector(v, bf2_t); return __builtin_bit_cast(unsigned, r); }
; DI void rw_rows4(const RowIO4& R, const float* __restrict__ ga, const float* __restrict__ gb, int lane) {
;     ...
;     if (R.hout) {
;       float ss = 0.f;
; #pragma unroll
;       for (int i = 0; i < 4; ++i) ss += x[r][i][0] * x[r][i][0] + x[r][i][1] * x[r][i][1] + x[r][i][2] * x[r][i][2] + x[r][i][3] * x[r][i][3];
;       const float rinv = rsqrtf(wave_sum(ss) * (1.f / 1024.f) + 1e-6f);
; #pragma unroll
;       for (int i = 0; i < 4; ++i) {
;         const f32x4 hv = (x[r][i] * rinv * gb4[i]) * (sc4[i] + 1.f) + sh4[i];
;         u32x2 w; w.x = pk2(hv[0], hv[1]); w.y = pk2(hv[2], hv[3]);
;         *(GAS u32x2*)(R.hout + r * 1024 + 4 * lane + 256 * i) = w;
;       }
;     }
.LBB0_379:
	s_and_b64 vcc, exec, s[40:41]
	s_cbranch_vccnz .LBB0_381
	v_mov_b32_e32 v100, v95
	v_mov_b32_e32 v101, v91
	v_mov_b32_e32 v98, v94
	v_mov_b32_e32 v99, v90
	v_pk_mul_f32 v[100:101], v[100:101], v[100:101]
	v_mov_b32_e32 v102, v83
	v_pk_fma_f32 v[98:99], v[98:99], v[98:99], v[100:101]
	v_mov_b32_e32 v100, v96
	v_mov_b32_e32 v101, v92
	v_pk_fma_f32 v[98:99], v[100:101], v[100:101], v[98:99]
	v_mov_b32_e32 v100, v97
	v_mov_b32_e32 v101, v93
	v_mov_b32_e32 v103, v87
	v_pk_fma_f32 v[98:99], v[100:101], v[100:101], v[98:99]
	v_mov_b32_e32 v100, v82
	v_mov_b32_e32 v101, v86
	v_pk_mul_f32 v[102:103], v[102:103], v[102:103]
	v_add_f32_e32 v98, v98, v99
	v_pk_fma_f32 v[100:101], v[100:101], v[100:101], v[102:103]
	v_mov_b32_e32 v102, v84
	v_mov_b32_e32 v103, v88
	v_pk_fma_f32 v[100:101], v[102:103], v[102:103], v[100:101]
	v_mov_b32_e32 v102, v85
	v_mov_b32_e32 v103, v89
	v_pk_fma_f32 v[100:101], v[102:103], v[102:103], v[100:101]
	v_mov_b32_e32 v169, v1
	v_add_f32_e32 v98, v101, v98
	v_add_f32_e32 v98, v100, v98
	ds_bpermute_b32 v99, v139, v98
	s_waitcnt lgkmcnt(0)
	v_add_f32_e32 v98, v98, v99
	ds_bpermute_b32 v99, v189, v98
	s_waitcnt lgkmcnt(0)
	v_add_f32_e32 v98, v98, v99
	ds_bpermute_b32 v99, v218, v98
	s_waitcnt lgkmcnt(0)
	v_add_f32_e32 v98, v98, v99
	ds_bpermute_b32 v99, v219, v98
	s_waitcnt lgkmcnt(0)
	v_add_f32_e32 v98, v98, v99
	ds_bpermute_b32 v99, v220, v98
	s_waitcnt lgkmcnt(0)
	v_add_f32_e32 v98, v98, v99
	ds_bpermute_b32 v99, v221, v98
	s_waitcnt lgkmcnt(0)
	v_add_f32_e32 v98, v98, v99
	v_fmamk_f32 v98, v98, 0x3a800000, v186
	v_mul_f32_e32 v99, 0x4b800000, v98
	v_cmp_gt_f32_e32 vcc, s11, v98
	s_nop 1
	v_cndmask_b32_e32 v98, v98, v99, vcc
	v_rsq_f32_e32 v100, v98
	v_lshl_add_u64 v[98:99], s[46:47], 0, v[168:169]
	v_mul_f32_e32 v101, 0x45800000, v100
	v_cndmask_b32_e32 v100, v100, v101, vcc
	v_pk_mul_f32 v[96:97], v[96:97], v[100:101] op_sel_hi:[1,0]
	v_pk_mul_f32 v[94:95], v[94:95], v[100:101] op_sel_hi:[1,0]
	v_pk_mul_f32 v[96:97], v[44:45], v[96:97]
	v_pk_mul_f32 v[94:95], v[42:43], v[94:95]
	v_pk_mul_f32 v[92:93], v[92:93], v[100:101] op_sel_hi:[1,0]
	v_pk_mul_f32 v[90:91], v[90:91], v[100:101] op_sel_hi:[1,0]
	v_pk_mul_f32 v[88:89], v[88:89], v[100:101] op_sel_hi:[1,0]
	v_pk_mul_f32 v[86:87], v[86:87], v[100:101] op_sel_hi:[1,0]
	v_pk_mul_f32 v[84:85], v[84:85], v[100:101] op_sel_hi:[1,0]
	v_pk_mul_f32 v[82:83], v[82:83], v[100:101] op_sel_hi:[1,0]
	v_pk_fma_f32 v[96:97], v[158:159], v[96:97], v[48:49]
	v_pk_fma_f32 v[94:95], v[156:157], v[94:95], v[46:47]
	v_pk_mul_f32 v[90:91], v[30:31], v[90:91]
	v_pk_mul_f32 v[92:93], v[32:33], v[92:93]
	v_pk_mul_f32 v[86:87], v[26:27], v[86:87]
	v_pk_mul_f32 v[88:89], v[28:29], v[88:89]
	v_pk_mul_f32 v[82:83], v[18:19], v[82:83]
	v_pk_mul_f32 v[84:85], v[20:21], v[84:85]
	v_cvt_pk_bf16_f32 v94, v94, v95
	v_cvt_pk_bf16_f32 v95, v96, v97
	v_add_co_u32_e32 v96, vcc, s10, v98
	v_pk_fma_f32 v[92:93], v[154:155], v[92:93], v[40:41]
	v_pk_fma_f32 v[90:91], v[152:153], v[90:91], v[38:39]
	v_pk_fma_f32 v[88:89], v[150:151], v[88:89], v[36:37]
	v_pk_fma_f32 v[86:87], v[148:149], v[86:87], v[34:35]
	v_pk_fma_f32 v[84:85], v[146:147], v[84:85], v[24:25]
	v_pk_fma_f32 v[82:83], v[144:145], v[82:83], v[22:23]
	v_addc_co_u32_e32 v97, vcc, 0, v99, vcc
	v_cvt_pk_bf16_f32 v90, v90, v91
	v_cvt_pk_bf16_f32 v91, v92, v93
	v_cvt_pk_bf16_f32 v86, v86, v87
	v_cvt_pk_bf16_f32 v87, v88, v89
	v_cvt_pk_bf16_f32 v82, v82, v83
	v_cvt_pk_bf16_f32 v83, v84, v85
	global_store_dwordx2 v240, v[94:95], s[46:47] offset:128
	global_store_dwordx2 v241, v[90:91], s[46:47] offset:128
	global_store_dwordx2 v242, v[86:87], s[46:47] offset:128
	global_store_dwordx2 v243, v[82:83], s[46:47] offset:128

; #define GAS __attribute__((address_space(1)))
; DI unsigned pk2(float a, float b) { f32x2 v = {a, b}; bf2_t r = __builtin_convertvector(v, bf2_t); return __builtin_bit_cast(unsigned, r); }
; DI void rw_rows4(const RowIO4& R, const float* __restrict__ ga, const float* __restrict__ gb, int lane) {
;     ...
;     if (R.hout) {
;       float ss = 0.f;
; #pragma unroll
;       for (int i = 0; i < 4; ++i) ss += x[r][i][0] * x[r][i][0] + x[r][i][1] * x[r][i][1] + x[r][i][2] * x[r][i][2] + x[r][i][3] * x[r][i][3];
;       const float rinv = rsqrtf(wave_sum(ss) * (1.f / 1024.f) + 1e-6f);
; #pragma unroll
;       for (int i = 0; i < 4; ++i) {
;         const f32x4 hv = (x[r][i] * rinv * gb4[i]) * (sc4[i] + 1.f) + sh4[i];
;         u32x2 w; w.x = pk2(hv[0], hv[1]); w.y = pk2(hv[2], hv[3]);
;         *(GAS u32x2*)(R.hout + r * 1024 + 4 * lane + 256 * i) = w;
;       }
;     }
.LBB0_383:
	s_and_b64 vcc, exec, s[40:41]
	s_cbranch_vccnz .LBB0_348
	v_mov_b32_e32 v60, v71
	v_mov_b32_e32 v61, v63
	v_mov_b32_e32 v58, v70
	v_mov_b32_e32 v59, v62
	v_pk_mul_f32 v[60:61], v[60:61], v[60:61]
	v_mov_b32_e32 v66, v51
	v_pk_fma_f32 v[58:59], v[58:59], v[58:59], v[60:61]
	v_mov_b32_e32 v60, v72
	v_mov_b32_e32 v61, v64
	v_pk_fma_f32 v[58:59], v[60:61], v[60:61], v[58:59]
	v_mov_b32_e32 v60, v73
	v_mov_b32_e32 v61, v65
	v_mov_b32_e32 v67, v55
	v_pk_fma_f32 v[58:59], v[60:61], v[60:61], v[58:59]
	v_mov_b32_e32 v60, v50
	v_mov_b32_e32 v61, v54
	v_pk_mul_f32 v[66:67], v[66:67], v[66:67]
	v_add_f32_e32 v58, v58, v59
	v_pk_fma_f32 v[60:61], v[60:61], v[60:61], v[66:67]
	v_mov_b32_e32 v66, v52
	v_mov_b32_e32 v67, v56
	v_pk_fma_f32 v[60:61], v[66:67], v[66:67], v[60:61]
	v_mov_b32_e32 v66, v53
	v_mov_b32_e32 v67, v57
	v_pk_fma_f32 v[60:61], v[66:67], v[66:67], v[60:61]
	v_mov_b32_e32 v169, v1
	v_add_f32_e32 v58, v61, v58
	v_add_f32_e32 v58, v60, v58
	ds_bpermute_b32 v59, v139, v58
	s_waitcnt lgkmcnt(0)
	v_add_f32_e32 v58, v58, v59
	ds_bpermute_b32 v59, v189, v58
	s_waitcnt lgkmcnt(0)
	v_add_f32_e32 v58, v58, v59
	ds_bpermute_b32 v59, v218, v58
	s_waitcnt lgkmcnt(0)
	v_add_f32_e32 v58, v58, v59
	ds_bpermute_b32 v59, v219, v58
	s_waitcnt lgkmcnt(0)
	v_add_f32_e32 v58, v58, v59
	ds_bpermute_b32 v59, v220, v58
	s_waitcnt lgkmcnt(0)
	v_add_f32_e32 v58, v58, v59
	ds_bpermute_b32 v59, v221, v58
	s_waitcnt lgkmcnt(0)
	v_add_f32_e32 v58, v58, v59
	v_fmamk_f32 v58, v58, 0x3a800000, v186
	v_mul_f32_e32 v59, 0x4b800000, v58
	v_cmp_gt_f32_e32 vcc, s11, v58
	s_nop 1
	v_cndmask_b32_e32 v58, v58, v59, vcc
	v_rsq_f32_e32 v60, v58
	v_lshl_add_u64 v[58:59], s[46:47], 0, v[168:169]
	v_mul_f32_e32 v61, 0x45800000, v60
	v_cndmask_b32_e32 v60, v60, v61, vcc
	v_pk_mul_f32 v[66:67], v[72:73], v[60:61] op_sel_hi:[1,0]
	v_pk_mul_f32 v[68:69], v[70:71], v[60:61] op_sel_hi:[1,0]
	v_pk_mul_f32 v[44:45], v[44:45], v[66:67]
	v_pk_mul_f32 v[42:43], v[42:43], v[68:69]
	v_pk_fma_f32 v[44:45], v[158:159], v[44:45], v[48:49]
	v_pk_fma_f32 v[42:43], v[156:157], v[42:43], v[46:47]
	v_pk_mul_f32 v[46:47], v[62:63], v[60:61] op_sel_hi:[1,0]
	v_cvt_pk_bf16_f32 v42, v42, v43
	v_cvt_pk_bf16_f32 v43, v44, v45
	v_add_co_u32_e32 v44, vcc, s10, v58
	v_pk_mul_f32 v[30:31], v[30:31], v[46:47]
	s_nop 0
	v_addc_co_u32_e32 v45, vcc, 0, v59, vcc
	global_store_dwordx2 v240, v[42:43], s[46:47] offset:192
	v_pk_mul_f32 v[42:43], v[64:65], v[60:61] op_sel_hi:[1,0]
	v_pk_fma_f32 v[30:31], v[152:153], v[30:31], v[38:39]
	v_pk_mul_f32 v[32:33], v[32:33], v[42:43]
	v_cvt_pk_bf16_f32 v30, v30, v31
	v_pk_fma_f32 v[32:33], v[154:155], v[32:33], v[40:41]
	s_nop 0
	v_cvt_pk_bf16_f32 v31, v32, v33
	global_store_dwordx2 v241, v[30:31], s[46:47] offset:192
	v_pk_mul_f32 v[30:31], v[56:57], v[60:61] op_sel_hi:[1,0]
	v_pk_mul_f32 v[32:33], v[54:55], v[60:61] op_sel_hi:[1,0]
	v_pk_mul_f32 v[28:29], v[28:29], v[30:31]
	v_pk_mul_f32 v[26:27], v[26:27], v[32:33]
	v_pk_fma_f32 v[28:29], v[150:151], v[28:29], v[36:37]
	v_pk_fma_f32 v[26:27], v[148:149], v[26:27], v[34:35]
	s_nop 0
	v_cvt_pk_bf16_f32 v26, v26, v27
	v_cvt_pk_bf16_f32 v27, v28, v29
	global_store_dwordx2 v242, v[26:27], s[46:47] offset:192
	v_pk_mul_f32 v[26:27], v[52:53], v[60:61] op_sel_hi:[1,0]
	v_pk_mul_f32 v[28:29], v[50:51], v[60:61] op_sel_hi:[1,0]
	v_pk_mul_f32 v[20:21], v[20:21], v[26:27]
	v_pk_mul_f32 v[18:19], v[18:19], v[28:29]
	v_pk_fma_f32 v[20:21], v[146:147], v[20:21], v[24:25]
	v_pk_fma_f32 v[18:19], v[144:145], v[18:19], v[22:23]
	s_nop 0
	v_cvt_pk_bf16_f32 v18, v18, v19
	v_cvt_pk_bf16_f32 v19, v20, v21
	global_store_dwordx2 v243, v[18:19], s[46:47] offset:192
	s_branch .LBB0_348
